# baseline (speedup 1.0000x reference)
; __global__ void __launch_bounds__(256, 2) trunk_fwd(Params p) {
;     ...
;   if (phi > 1000) cg::this_grid().sync();
.LBB0_12:
	s_or_b64 exec, exec, s[4:5]
	v_mov_b32_e32 v0, 0
	global_load_dword v2, v0, s[2:3] offset:32 sc1
	v_and_b32_e32 v1, 0xffff0000, v1
	s_waitcnt vmcnt(0)
	v_and_b32_e32 v2, 0xffff0000, v2
	v_cmp_eq_u32_e32 vcc, v2, v1
	s_and_b64 exec, exec, vcc
	s_cbranch_execz .LBB0_15
	s_mov_b64 s[4:5], 0
	.p2align	6

; DI unsigned xb_ld(unsigned* p) { return __hip_atomic_load(p, __ATOMIC_RELAXED, __HIP_MEMORY_SCOPE_AGENT); }
; DI void xcd_barrier_complete(unsigned* bar, unsigned x, unsigned& nloc, unsigned& nx) {
;     ...
;   for (;;) {
;     sum = 0u; cnt = 0u; mine = 0u;
; #pragma unroll
;     for (unsigned j = 0; j < 16; ++j) { const unsigned c = xb_ld(&bar[XB_XCNT(j)]); sum += c; cnt += (c > 0u) ? 1u : 0u; mine = (j == x) ? c : mine; }
;     if (sum == G) break;
.LBB0_22:
	s_and_b64 vcc, exec, s[14:15]
	s_cbranch_vccnz .LBB0_30
	.p2align	6

; DI unsigned xb_ld(unsigned* p) { return __hip_atomic_load(p, __ATOMIC_RELAXED, __HIP_MEMORY_SCOPE_AGENT); }
; DI unsigned xb_add(unsigned* p, unsigned v) { return __hip_atomic_fetch_add(p, v, __ATOMIC_RELAXED, __HIP_MEMORY_SCOPE_AGENT); }
; #define XB_SPIN(cond, bar) do { unsigned _sp = 0; while (cond) { __builtin_amdgcn_s_sleep(1); \
;     if ((++_sp & 255u) == 0u) { if (xb_ld(&(bar)[XB_TMO])) break; if (_sp > XB_SPIN_CAP) { atomicAdd(&(bar)[XB_TMO], 1u); break; } } } } while (0)
; DI void xcd_barrier(const XcdBarrier& b) {
;     ...
;       else XB_SPIN(xb_ld(&bar[XB_TOPGEN]) == tg, bar);
;       __builtin_amdgcn_fence(__ATOMIC_ACQUIRE, "agent");
;       xb_add(&bar[XB_XGEN(b.x)], 1u);
;       asm volatile("s_waitcnt vmcnt(0)" ::: "memory");
;     } else {
;       XB_SPIN(xb_ld(&bar[XB_XGEN(b.x)]) == gen, bar);
.LBB0_40:
	s_and_b64 s[16:17], exec, s[16:17]
	s_or_b64 s[12:13], s[16:17], s[12:13]
	s_andn2_b64 s[14:15], s[14:15], exec
	s_and_b64 s[16:17], s[18:19], exec
	s_or_b64 s[14:15], s[14:15], s[16:17]
	s_andn2_b64 exec, exec, s[12:13]
	s_cbranch_execz .LBB0_47
	.p2align	6

; DI unsigned xb_ld(unsigned* p) { return __hip_atomic_load(p, __ATOMIC_RELAXED, __HIP_MEMORY_SCOPE_AGENT); }
; DI unsigned xb_add(unsigned* p, unsigned v) { return __hip_atomic_fetch_add(p, v, __ATOMIC_RELAXED, __HIP_MEMORY_SCOPE_AGENT); }
; #define XB_SPIN(cond, bar) do { unsigned _sp = 0; while (cond) { __builtin_amdgcn_s_sleep(1); \
;     if ((++_sp & 255u) == 0u) { if (xb_ld(&(bar)[XB_TMO])) break; if (_sp > XB_SPIN_CAP) { atomicAdd(&(bar)[XB_TMO], 1u); break; } } } } while (0)
; DI void xcd_barrier(const XcdBarrier& b) {
;     ...
;       else XB_SPIN(xb_ld(&bar[XB_TOPGEN]) == tg, bar);
;       __builtin_amdgcn_fence(__ATOMIC_ACQUIRE, "agent");
;       xb_add(&bar[XB_XGEN(b.x)], 1u);
;       asm volatile("s_waitcnt vmcnt(0)" ::: "memory");
;     } else {
;       XB_SPIN(xb_ld(&bar[XB_XGEN(b.x)]) == gen, bar);
.LBB0_57:
	s_xor_b64 s[18:19], s[18:19], -1
	s_and_b64 s[20:21], exec, s[22:23]
	s_or_b64 s[14:15], s[20:21], s[14:15]
	s_andn2_b64 s[16:17], s[16:17], exec
	s_and_b64 s[18:19], s[18:19], exec
	s_or_b64 s[16:17], s[16:17], s[18:19]
	s_andn2_b64 exec, exec, s[14:15]
	s_cbranch_execz .LBB0_64
	.p2align	6

; DI int ltid() { int x = threadIdx.x; asm volatile("" : "+v"(x)); return x; }
; DI int lbid() { int x = blockIdx.x; asm volatile("" : "+s"(x)); return x; }
; DI void prep_phase(const Params& p, char* smem) {
;     ...
;   if (lbid() == 0) { for (int i = ltid(); i < 512; i += 256) p.kmax2[i] = 0u; }
.LBB0_140:
	s_mov_b32 s0, s43
	s_cmp_eq_u32 s0, 0
	s_cbranch_scc0 .LBB0_150
	v_mov_b32_e32 v0, v222
	s_movk_i32 s0, 0x200
	s_nop 0
	v_cmp_gt_i32_e32 vcc, s0, v0
	s_and_saveexec_b64 s[0:1], vcc
	s_cbranch_execz .LBB0_149
	s_load_dwordx2 s[4:5], s[56:57], 0x100
	v_max_i32_e32 v1, 0x100, v0
	v_sub_u32_e32 v1, v1, v0
	s_movk_i32 s6, 0xff
	v_add_u32_e32 v1, 0xff, v1
	v_cmp_lt_u32_e32 vcc, s6, v1
	s_mov_b64 s[8:9], -1
	s_and_saveexec_b64 s[6:7], vcc
	s_cbranch_execz .LBB0_146
	v_lshrrev_b32_e32 v1, 8, v1
	v_add_u32_e32 v4, 1, v1
	v_and_b32_e32 v5, 0x1fffffe, v4
	v_add_u32_e32 v1, 0x100, v0
	s_mov_b64 s[8:9], 0
	v_mov_b32_e32 v6, 0
	v_mov_b32_e32 v7, v5
	v_mov_b64_e32 v[2:3], v[0:1]
	.p2align	6

; DI int ltid() { int x = threadIdx.x; asm volatile("" : "+v"(x)); return x; }
; DI int lbid() { int x = blockIdx.x; asm volatile("" : "+s"(x)); return x; }
; DI void prep_phase(const Params& p, char* smem) {
;     ...
;   if (lbid() == 0) { for (int i = ltid(); i < 512; i += 256) p.kmax2[i] = 0u; }
.LBB0_146:
	s_or_b64 exec, exec, s[6:7]
	s_and_b64 exec, exec, s[8:9]
	s_cbranch_execz .LBB0_149
	v_ashrrev_i32_e32 v1, 31, v0
	v_add_u32_e32 v2, 0xffffff00, v0
	s_waitcnt lgkmcnt(0)
	v_lshl_add_u64 v[0:1], v[0:1], 2, s[4:5]
	s_mov_b64 s[4:5], 0
	v_mov_b32_e32 v3, 0
	s_mov_b64 s[6:7], 0x400
	s_movk_i32 s8, 0xff
	.p2align	6

; template <bool HI_BF, bool HO_BF>
; DI void post_phase(const u16* __restrict__ y, const void* hin_, void* hout_,
;                    const float* __restrict__ gpost, const float* __restrict__ gpre, u16* __restrict__ uout) {
;     ...
;   for (int row = gw; row < T_TOK; row += nw) {
;     float4 hv[4];
; #pragma unroll
;     for (int j = 0; j < 4; ++j) {
;       if (HI_BF) {
;         const u32x2 hb = *(const u32x2*)((const u16*)hin_ + (long)row * 1024 + 4 * lane + 256 * j);
;         hv[j] = make_float4(bflo(hb.x), bfhi(hb.x), bflo(hb.y), bfhi(hb.y));
;       } else hv[j] = *(const float4*)(hin + (long)row * 1024 + 4 * lane + 256 * j);
;     }
;     if (y) {
;       float4 yv[4]; float ss = 0.f;
; #pragma unroll
;       for (int j = 0; j < 4; ++j) {
;         const u32x2 yb = *(const u32x2*)(y + (long)row * 1024 + 4 * lane + 256 * j);
;         yv[j] = make_float4(bflo(yb.x), bfhi(yb.x), bflo(yb.y), bfhi(yb.y));
;         ss += yv[j].x * yv[j].x + yv[j].y * yv[j].y + yv[j].z * yv[j].z + yv[j].w * yv[j].w;
;       }
; #pragma unroll
;       for (int o = 32; o > 0; o >>= 1) ss += __shfl_xor(ss, o);
;       const float ri = rsqrtf(ss * (1.f / 1024.f) + RMS_EPS);
; #pragma unroll
;       for (int j = 0; j < 4; ++j) {
;         const float4 g = *(const float4*)(gpost + 4 * lane + 256 * j);
;         hv[j].x += yv[j].x * ri * g.x; hv[j].y += yv[j].y * ri * g.y; hv[j].z += yv[j].z * ri * g.z; hv[j].w += yv[j].w * ri * g.w;
;       }
;     }
;     if (hout_) {
; #pragma unroll
;       for (int j = 0; j < 4; ++j) {
;         if (HO_BF) { u32x2 v; v.x = pack2(hv[j].x, hv[j].y); v.y = pack2(hv[j].z, hv[j].w); *(u32x2*)((u16*)hout_ + (long)row * 1024 + 4 * lane + 256 * j) = v; }
;         else *(float4*)(hout + (long)row * 1024 + 4 * lane + 256 * j) = hv[j];
;       }
;     }
;     if (uout) {
;       float ss = 0.f;
; #pragma unroll
;       for (int j = 0; j < 4; ++j) ss += hv[j].x * hv[j].x + hv[j].y * hv[j].y + hv[j].z * hv[j].z + hv[j].w * hv[j].w;
; #pragma unroll
;       for (int o = 32; o > 0; o >>= 1) ss += __shfl_xor(ss, o);
;       const float ri = rsqrtf(ss * (1.f / 1024.f) + RMS_EPS);
; #pragma unroll
;       for (int j = 0; j < 4; ++j) {
;         const float4 g = *(const float4*)(gpre + 4 * lane + 256 * j);
;         u32x2 v; v.x = pack2(hv[j].x * ri * g.x, hv[j].y * ri * g.y); v.y = pack2(hv[j].z * ri * g.z, hv[j].w * ri * g.w);
.LBB0_152:
	v_add_u32_e32 v6, s8, v6
	v_cmp_lt_i32_e32 vcc, s1, v6
	v_lshl_add_u64 v[2:3], v[2:3], 0, s[12:13]
	s_or_b64 s[10:11], vcc, s[10:11]
	v_lshl_add_u64 v[4:5], v[4:5], 0, s[14:15]
	s_andn2_b64 exec, exec, s[10:11]
	s_cbranch_execz .LBB0_155
	.p2align	6

; DI unsigned xb_ld(unsigned* p) { return __hip_atomic_load(p, __ATOMIC_RELAXED, __HIP_MEMORY_SCOPE_AGENT); }
; DI void xcd_barrier_complete(unsigned* bar, unsigned x, unsigned& nloc, unsigned& nx) {
;     ...
;   for (;;) {
;     sum = 0u; cnt = 0u; mine = 0u;
; #pragma unroll
;     for (unsigned j = 0; j < 16; ++j) { const unsigned c = xb_ld(&bar[XB_XCNT(j)]); sum += c; cnt += (c > 0u) ? 1u : 0u; mine = (j == x) ? c : mine; }
;     if (sum == G) break;
.LBB0_161:
	s_and_b64 vcc, exec, s[12:13]
	s_cbranch_vccnz .LBB0_169
	.p2align	6

; DI unsigned xb_ld(unsigned* p) { return __hip_atomic_load(p, __ATOMIC_RELAXED, __HIP_MEMORY_SCOPE_AGENT); }
; DI unsigned xb_add(unsigned* p, unsigned v) { return __hip_atomic_fetch_add(p, v, __ATOMIC_RELAXED, __HIP_MEMORY_SCOPE_AGENT); }
; #define XB_SPIN(cond, bar) do { unsigned _sp = 0; while (cond) { __builtin_amdgcn_s_sleep(1); \
;     if ((++_sp & 255u) == 0u) { if (xb_ld(&(bar)[XB_TMO])) break; if (_sp > XB_SPIN_CAP) { atomicAdd(&(bar)[XB_TMO], 1u); break; } } } } while (0)
; DI void xcd_barrier(const XcdBarrier& b) {
;     ...
;       else XB_SPIN(xb_ld(&bar[XB_TOPGEN]) == tg, bar);
;       __builtin_amdgcn_fence(__ATOMIC_ACQUIRE, "agent");
;       xb_add(&bar[XB_XGEN(b.x)], 1u);
;       asm volatile("s_waitcnt vmcnt(0)" ::: "memory");
;     } else {
;       XB_SPIN(xb_ld(&bar[XB_XGEN(b.x)]) == gen, bar);
.LBB0_179:
	s_and_b64 s[16:17], exec, s[16:17]
	s_or_b64 s[10:11], s[16:17], s[10:11]
	s_andn2_b64 s[12:13], s[12:13], exec
	s_and_b64 s[16:17], s[18:19], exec
	s_or_b64 s[12:13], s[12:13], s[16:17]
	s_andn2_b64 exec, exec, s[10:11]
	s_cbranch_execz .LBB0_186
	.p2align	6

; DI unsigned xb_ld(unsigned* p) { return __hip_atomic_load(p, __ATOMIC_RELAXED, __HIP_MEMORY_SCOPE_AGENT); }
; DI unsigned xb_add(unsigned* p, unsigned v) { return __hip_atomic_fetch_add(p, v, __ATOMIC_RELAXED, __HIP_MEMORY_SCOPE_AGENT); }
; #define XB_SPIN(cond, bar) do { unsigned _sp = 0; while (cond) { __builtin_amdgcn_s_sleep(1); \
;     if ((++_sp & 255u) == 0u) { if (xb_ld(&(bar)[XB_TMO])) break; if (_sp > XB_SPIN_CAP) { atomicAdd(&(bar)[XB_TMO], 1u); break; } } } } while (0)
; DI void xcd_barrier(const XcdBarrier& b) {
;     ...
;       else XB_SPIN(xb_ld(&bar[XB_TOPGEN]) == tg, bar);
;       __builtin_amdgcn_fence(__ATOMIC_ACQUIRE, "agent");
;       xb_add(&bar[XB_XGEN(b.x)], 1u);
;       asm volatile("s_waitcnt vmcnt(0)" ::: "memory");
;     } else {
;       XB_SPIN(xb_ld(&bar[XB_XGEN(b.x)]) == gen, bar);
.LBB0_196:
	s_xor_b64 s[18:19], s[18:19], -1
	s_and_b64 s[20:21], exec, s[22:23]
	s_or_b64 s[12:13], s[20:21], s[12:13]
	s_andn2_b64 s[16:17], s[16:17], exec
	s_and_b64 s[18:19], s[18:19], exec
	s_or_b64 s[16:17], s[16:17], s[18:19]
	s_andn2_b64 exec, exec, s[12:13]
	s_cbranch_execz .LBB0_203
	.p2align	6

; DI int ltid() { int x = threadIdx.x; asm volatile("" : "+v"(x)); return x; }
; DI int lbid() { int x = blockIdx.x; asm volatile("" : "+s"(x)); return x; }
; template <class ARow, class Epi>
; DI void gemm_tile(const ARow& arow, long a_kstride, const u16* __restrict__ Bt, long ldb, int K, int m0, int n0,
;                   const Epi& epi, char* smem) {
;   const int tid = ltid(), lane = tid & 63, wid = tid >> 6;
;   const int r = lane & 31, h = lane >> 5;
;   const int wn = wid & 1, wm = wid >> 1;
;   const u16* ap[4]; const u16* bp[4];
;   {
;     const int lr = lane >> 3;
; #pragma unroll
;     for (int j = 0; j < 4; ++j) {
;       const int row = (wid * 4 + j) * 8 + lr;
;       const int cc = (lane & 7) ^ ((row >> 1) & 7);
;       ap[j] = arow(m0 + row) + cc * 8;
;       bp[j] = Bt + (long)(n0 + row) * ldb + cc * 8;
;     }
;   }
; template <class Epi>
; DI void gemm_phase_plain(const u16* A, long lda, const u16* Bt, long ldb, int M, int N, int K, const Epi& epi, char* smem) {
;     ...
;   for (int t = lbid(); t < nwg; t += gridDim.x) {
;     const int xcd = t & 7, off = t >> 3;
;     const int wg = (xcd < rr ? xcd * (q + 1) : rr * (q + 1) + (xcd - rr) * q) + off;
;     const int nig = 8 * MT, gid = wg / nig, fm = gid * 8, gsz = (NT - fm) < 8 ? (NT - fm) : 8;
;     const int nt = fm + (wg % nig) % gsz, mt = (wg % nig) / gsz;
;     gemm_tile(ar, 64, Bt, ldb, K, mt * 128, nt * 128, epi, smem);
.LBB0_216:
	s_and_b32 s1, s31, 7
	s_ashr_i32 s0, s31, 3
	s_mulk_i32 s1, 0x1d0
	s_add_i32 s4, s1, s0
	s_ashr_i32 s0, s4, 31
	s_lshr_b32 s0, s0, 22
	s_add_i32 s0, s4, s0
	s_ashr_i32 s1, s0, 10
	s_lshl_b32 s5, s1, 3
	s_sub_i32 s1, 29, s5
	s_min_u32 s6, s1, 8
	s_and_b32 s7, s0, 0xfffffc00
	s_sub_i32 s8, s4, s7
	v_cvt_f32_ubyte0_e32 v1, s6
	v_cvt_f32_i32_e32 v0, s8
	v_rcp_iflag_f32_e32 v2, v1
	s_ashr_i32 s0, s8, 30
	s_or_b32 s9, s0, 1
	v_mov_b32_e32 v83, v222
	v_mul_f32_e32 v2, v0, v2
	v_trunc_f32_e32 v2, v2
	v_fma_f32 v0, -v2, v1, v0
	v_cvt_i32_f32_e32 v2, v2
	v_cmp_ge_f32_e64 s[0:1], |v0|, v1
	s_and_b64 s[0:1], s[0:1], exec
	s_cselect_b32 s0, s9, 0
	v_readfirstlane_b32 s1, v2
	s_add_i32 s0, s1, s0
	s_mul_i32 s6, s0, s6
	s_sext_i32_i16 s1, s0
	s_sub_i32 s0, s8, s6
	s_sext_i32_i16 s0, s0
	v_ashrrev_i32_e32 v16, 6, v83
	v_bfe_u32 v17, v83, 3, 3
	v_lshlrev_b32_e32 v18, 5, v16
	s_add_i32 s5, s5, s0
	s_lshl_b32 s0, s1, 7
	v_or_b32_e32 v12, v18, v17
	v_bfe_u32 v84, v83, 4, 2
	v_add_u32_e32 v0, s0, v12
	s_lshl_b32 s42, s5, 7
	v_xor_b32_e32 v2, v84, v83
	v_ashrrev_i32_e32 v1, 31, v0
	v_or_b32_e32 v8, 8, v12
	v_lshlrev_b64 v[0:1], 11, v[0:1]
	v_lshlrev_b32_e32 v2, 4, v2
	v_lshrrev_b32_e32 v19, 1, v8
	v_add_u32_e32 v4, s0, v8
	v_add_u32_e32 v8, s42, v8
	v_lshlrev_b32_e32 v91, 12, v16
	v_lshl_add_u64 v[0:1], s[16:17], 0, v[0:1]
	v_and_b32_e32 v64, 0x70, v2
	v_add_u32_e32 v2, s42, v12
	v_xor_b32_e32 v6, v19, v83
	v_ashrrev_i32_e32 v5, 31, v4
	v_ashrrev_i32_e32 v9, 31, v8
	v_readfirstlane_b32 s1, v91
	v_lshl_add_u64 v[0:1], v[0:1], 0, v[64:65]
	v_ashrrev_i32_e32 v3, 31, v2
	v_lshlrev_b64 v[4:5], 11, v[4:5]
	v_lshlrev_b32_e32 v6, 4, v6
	v_lshlrev_b64 v[8:9], 11, v[8:9]
	s_mov_b32 m0, s1
	v_lshlrev_b64 v[2:3], 11, v[2:3]
	v_lshl_add_u64 v[4:5], s[16:17], 0, v[4:5]
	v_and_b32_e32 v6, 0x70, v6
	v_mov_b32_e32 v7, v65
	v_lshl_add_u64 v[8:9], s[22:23], 0, v[8:9]
	v_or_b32_e32 v10, 16, v12
	global_load_lds_dwordx4 v[0:1], off
	v_add_u32_e32 v0, 0x4000, v91
	v_lshl_add_u64 v[2:3], s[22:23], 0, v[2:3]
	v_lshl_add_u64 v[4:5], v[4:5], 0, v[6:7]
	v_lshl_add_u64 v[6:7], v[8:9], 0, v[6:7]
	v_add_u32_e32 v8, s0, v10
	v_add_u32_e32 v10, s42, v10
	v_or_b32_e32 v14, 24, v12
	v_readfirstlane_b32 s1, v0
	v_or_b32_e32 v0, 0x400, v91
	v_lshl_add_u64 v[2:3], v[2:3], 0, v[64:65]
	v_ashrrev_i32_e32 v9, 31, v8
	v_ashrrev_i32_e32 v11, 31, v10
	v_lshrrev_b32_e32 v20, 1, v14
	s_mov_b32 m0, s1
	v_readfirstlane_b32 s1, v0
	v_add_u32_e32 v0, 0x4400, v91
	v_lshlrev_b64 v[8:9], 11, v[8:9]
	v_lshlrev_b64 v[10:11], 11, v[10:11]
	v_xor_b32_e32 v15, v20, v83
	v_add_u32_e32 v12, s0, v14
	global_load_lds_dwordx4 v[2:3], off
	s_mov_b32 m0, s1
	v_readfirstlane_b32 s1, v0
	v_or_b32_e32 v0, 0x800, v91
	v_lshl_add_u64 v[8:9], s[16:17], 0, v[8:9]
	v_lshl_add_u64 v[10:11], s[22:23], 0, v[10:11]
	v_ashrrev_i32_e32 v13, 31, v12
	v_lshlrev_b32_e32 v15, 4, v15
	v_add_u32_e32 v14, s42, v14
	global_load_lds_dwordx4 v[4:5], off
	s_mov_b32 m0, s1
	v_readfirstlane_b32 s1, v0
	v_add_u32_e32 v0, 0x4800, v91
	v_lshl_add_u64 v[8:9], v[8:9], 0, v[64:65]
	v_lshl_add_u64 v[10:11], v[10:11], 0, v[64:65]
	v_lshlrev_b64 v[12:13], 11, v[12:13]
	v_and_b32_e32 v64, 0x70, v15
	v_ashrrev_i32_e32 v15, 31, v14
	global_load_lds_dwordx4 v[6:7], off
	s_mov_b32 m0, s1
	v_readfirstlane_b32 s1, v0
	v_or_b32_e32 v0, 0xc00, v91
	v_lshl_add_u64 v[12:13], s[16:17], 0, v[12:13]
	v_lshlrev_b64 v[14:15], 11, v[14:15]
	global_load_lds_dwordx4 v[8:9], off
	s_mov_b32 m0, s1
	v_readfirstlane_b32 s1, v0
	v_add_u32_e32 v0, 0x4c00, v91
	v_lshl_add_u64 v[12:13], v[12:13], 0, v[64:65]
	v_lshl_add_u64 v[14:15], s[22:23], 0, v[14:15]
	global_load_lds_dwordx4 v[10:11], off
	s_mov_b32 m0, s1
	v_readfirstlane_b32 s1, v0
	v_lshl_add_u64 v[14:15], v[14:15], 0, v[64:65]
	global_load_lds_dwordx4 v[12:13], off
	s_mov_b32 m0, s1
	v_or_b32_e32 v0, s0, v17
	global_load_lds_dwordx4 v[14:15], off
	s_sub_i32 s1, s4, s6
	v_add_u32_e32 v0, v0, v18
	s_sub_i32 s1, s1, s7
	v_ashrrev_i32_e32 v1, 31, v0
	v_bitop3_b32 v2, v84, 7, v83 bitop3:0x48
	s_sext_i32_i16 s1, s1
	v_lshlrev_b64 v[0:1], 11, v[0:1]
	v_lshlrev_b32_e32 v2, 4, v2
	s_lshl_b32 s1, s1, 7
	v_or_b32_e32 v0, v0, v2
	s_add_i32 s1, s1, s7
	v_lshl_add_u64 v[66:67], s[26:27], 0, v[0:1]
	v_or_b32_e32 v0, s1, v17
	v_add_u32_e32 v0, v0, v18
	v_ashrrev_i32_e32 v1, 31, v0
	v_lshlrev_b64 v[0:1], 11, v[0:1]
	v_or_b32_e32 v0, v0, v2
	v_or_b32_e32 v3, 8, v17
	v_lshl_add_u64 v[68:69], s[28:29], 0, v[0:1]
	v_or_b32_e32 v0, s0, v3
	v_add_u32_e32 v0, v0, v18
	v_ashrrev_i32_e32 v1, 31, v0
	v_bitop3_b32 v4, v19, 7, v83 bitop3:0x48
	v_lshlrev_b64 v[0:1], 11, v[0:1]
	v_lshlrev_b32_e32 v4, 4, v4
	v_or_b32_e32 v0, v0, v4
	v_lshl_add_u64 v[70:71], s[26:27], 0, v[0:1]
	v_or_b32_e32 v0, s1, v3
	v_add_u32_e32 v0, v0, v18
	v_ashrrev_i32_e32 v1, 31, v0
	v_lshlrev_b64 v[0:1], 11, v[0:1]
	v_or_b32_e32 v0, v0, v4
	v_or_b32_e32 v3, 16, v17
	v_lshl_add_u64 v[72:73], s[28:29], 0, v[0:1]
	v_or_b32_e32 v0, s0, v3
	v_add_u32_e32 v0, v0, v18
	v_ashrrev_i32_e32 v1, 31, v0
	v_lshlrev_b64 v[0:1], 11, v[0:1]
	v_or_b32_e32 v0, v0, v2
	v_lshl_add_u64 v[74:75], s[26:27], 0, v[0:1]
	v_or_b32_e32 v0, s1, v3
	v_add_u32_e32 v0, v0, v18
	v_ashrrev_i32_e32 v1, 31, v0
	v_lshlrev_b64 v[0:1], 11, v[0:1]
	v_or_b32_e32 v0, v0, v2
	v_or_b32_e32 v2, 24, v17
	v_lshl_add_u64 v[76:77], s[28:29], 0, v[0:1]
	v_or_b32_e32 v0, s0, v2
	v_add_u32_e32 v0, v0, v18
	v_ashrrev_i32_e32 v1, 31, v0
	v_bitop3_b32 v3, v20, 7, v83 bitop3:0x48
	v_lshlrev_b64 v[0:1], 11, v[0:1]
	v_lshlrev_b32_e32 v3, 4, v3
	v_or_b32_e32 v0, v0, v3
	v_lshl_add_u64 v[78:79], s[26:27], 0, v[0:1]
	v_or_b32_e32 v0, s1, v2
	v_add_u32_e32 v0, v0, v18
	v_and_b32_e32 v64, 15, v83
	v_lshrrev_b32_e32 v22, 1, v83
	v_ashrrev_i32_e32 v1, 31, v0
	v_lshlrev_b32_e32 v21, 7, v64
	v_bfe_u32 v23, v83, 1, 3
	v_bitop3_b32 v22, v84, v22, 7 bitop3:0x78
	s_waitcnt vmcnt(0)
; template <class ARow, class Epi>
; DI void gemm_tile(const ARow& arow, long a_kstride, const u16* __restrict__ Bt, long ldb, int K, int m0, int n0,
;                   const Epi& epi, char* smem) {
;     ...
;   const int fr = lane & 15, fq = lane >> 4;
;   int foff[2];
; #pragma unroll
;   for (int ks = 0; ks < 2; ++ks) foff[ks] = fr * 128 + ((((4 * ks + fq) ^ ((fr >> 1) & 7))) << 4);
;   f32x4 acc[4][4];
; #pragma unroll
;   for (int a = 0; a < 4; ++a)
; #pragma unroll
;     for (int b = 0; b < 4; ++b) acc[a][b] = (f32x4){0.f, 0.f, 0.f, 0.f};
;   const int KT = K >> 6;
;   GEMM_STAGE(0, 0);
;   asm volatile("s_waitcnt vmcnt(0)" ::: "memory");
;   __syncthreads();
	v_lshlrev_b64 v[0:1], 11, v[0:1]
	v_and_b32_e32 v85, 1, v16
	v_lshl_or_b32 v88, v22, 4, v21
	v_bitop3_b32 v22, v84, v23, 4 bitop3:0x36
	v_ashrrev_i32_e32 v86, 7, v83
	v_or_b32_e32 v0, v0, v3
	v_lshl_or_b32 v87, v22, 4, v21
	v_lshlrev_b32_e32 v89, 13, v86
	v_lshlrev_b32_e32 v90, 13, v85
	v_lshl_add_u64 v[80:81], s[28:29], 0, v[0:1]
	s_mov_b64 s[4:5], 0
	s_mov_b32 s1, 0
	v_mov_b32_e32 v44, 0
	v_mov_b32_e32 v45, v65
	v_mov_b32_e32 v46, v65
	v_mov_b32_e32 v47, v65
	v_mov_b32_e32 v52, 0
	v_mov_b32_e32 v53, v65
	v_mov_b32_e32 v54, v65
	v_mov_b32_e32 v55, v65
	v_mov_b32_e32 v0, 0
	v_mov_b32_e32 v1, v65
	v_mov_b32_e32 v2, v65
	v_mov_b32_e32 v3, v65
	v_mov_b32_e32 v4, 0
	v_mov_b32_e32 v5, v65
	v_mov_b32_e32 v6, v65
	v_mov_b32_e32 v7, v65
	v_mov_b32_e32 v8, 0
	v_mov_b32_e32 v9, v65
	v_mov_b32_e32 v10, v65
	v_mov_b32_e32 v11, v65
	v_mov_b32_e32 v12, 0
	v_mov_b32_e32 v13, v65
	v_mov_b32_e32 v14, v65
	v_mov_b32_e32 v15, v65
	v_mov_b32_e32 v16, 0
	v_mov_b32_e32 v17, v65
	v_mov_b32_e32 v18, v65
	v_mov_b32_e32 v19, v65
	v_mov_b32_e32 v20, 0
	v_mov_b32_e32 v21, v65
	v_mov_b32_e32 v22, v65
	v_mov_b32_e32 v23, v65
	v_mov_b32_e32 v24, 0
	v_mov_b32_e32 v25, v65
	v_mov_b32_e32 v26, v65
	v_mov_b32_e32 v27, v65
	v_mov_b32_e32 v28, 0
	v_mov_b32_e32 v29, v65
	v_mov_b32_e32 v30, v65
	v_mov_b32_e32 v31, v65
	v_mov_b32_e32 v32, 0
	v_mov_b32_e32 v33, v65
	v_mov_b32_e32 v34, v65
	v_mov_b32_e32 v35, v65
	v_mov_b32_e32 v36, 0
	v_mov_b32_e32 v37, v65
	v_mov_b32_e32 v38, v65
	v_mov_b32_e32 v39, v65
	v_mov_b32_e32 v40, 0
	v_mov_b32_e32 v41, v65
	v_mov_b32_e32 v42, v65
	v_mov_b32_e32 v43, v65
	v_mov_b32_e32 v48, 0
	v_mov_b32_e32 v49, v65
	v_mov_b32_e32 v50, v65
	v_mov_b32_e32 v51, v65
	v_mov_b32_e32 v56, 0
	v_mov_b32_e32 v57, v65
	v_mov_b32_e32 v58, v65
	v_mov_b32_e32 v59, v65
	v_mov_b32_e32 v60, 0
	v_mov_b32_e32 v61, v65
	v_mov_b32_e32 v62, v65
	v_mov_b32_e32 v63, v65
	s_waitcnt vmcnt(0) lgkmcnt(0)
	s_barrier
	.p2align	6

; DI int lbid() { int x = blockIdx.x; asm volatile("" : "+s"(x)); return x; }
; template <class ARow, class Epi>
; DI void gemm_tile(const ARow& arow, long a_kstride, const u16* __restrict__ Bt, long ldb, int K, int m0, int n0,
;                   const Epi& epi, char* smem) {
;     ...
;   const u16* ap[4]; const u16* bp[4];
;   {
;     const int lr = lane >> 3;
; #pragma unroll
;     for (int j = 0; j < 4; ++j) {
;       const int row = (wid * 4 + j) * 8 + lr;
;       const int cc = (lane & 7) ^ ((row >> 1) & 7);
;       ap[j] = arow(m0 + row) + cc * 8;
;       bp[j] = Bt + (long)(n0 + row) * ldb + cc * 8;
;     }
;   }
; __global__ void __launch_bounds__(256, 2) trunk_fwd(Params p) {
;     ...
;     for (int t = lbid(); t < 128; t += gridDim.x) {
;       const int c = t >> 6, tt = t & 63, nt = tt & 1, mt = tt >> 1;
;       ARowCmp ar{p.qkvz + 1024 + c * 256, 3584};
;       EpiCmp1 e{p.h1 + (long)c * 4096 * 256, p.bias_part + c * 16 * 256};
;       gemm_tile(ar, 3584, p.w1t[c], 2048, 2048, mt * 128, nt * 128, e, smem);
.LBB0_677:
	s_ashr_i32 s16, s23, 6
	s_lshl_b32 s0, s16, 8
	s_ashr_i32 s1, s0, 31
	s_and_b32 s36, s24, 0x80
	s_and_b32 s20, s26, 0xf80
	s_and_b32 s21, s26, 0xff80
	s_lshl_b64 s[18:19], s[0:1], 1
	s_add_u32 s38, s4, s18
	s_addc_u32 s39, s5, s19
	s_ashr_i32 s17, s16, 31
	s_lshl_b64 s[0:1], s[16:17], 3
	s_add_u32 s0, s56, s0
	s_addc_u32 s1, s57, s1
	v_mov_b32_e32 v223, v222
	s_load_dwordx2 s[0:1], s[0:1], 0xe8
	s_lshl_b32 s34, s23, 6
	v_ashrrev_i32_e32 v24, 6, v223
	v_bfe_u32 v30, v223, 3, 3
	v_lshlrev_b32_e32 v31, 5, v24
	v_or_b32_e32 v14, v31, v30
	s_and_b32 s34, s34, 0xf80
	v_or_b32_e32 v10, 8, v14
	v_add_u32_e32 v5, s34, v14
	v_add_u32_e32 v8, s34, v10
	v_lshlrev_b32_e32 v1, 4, v5
	v_lshlrev_b32_e32 v7, 4, v8
	s_lshl_b32 s35, s23, 7
	v_lshlrev_b32_e32 v0, 2, v5
	v_and_b32_e32 v1, 0x1e70, v1
	v_lshlrev_b32_e32 v6, 2, v8
	v_and_b32_e32 v7, 0x1ef0, v7
	s_and_b32 s35, s35, 0x80
	v_and_or_b32 v2, v0, s28, v1
	v_mov_b64_e32 v[0:1], s[38:39]
	v_lshrrev_b32_e32 v18, 1, v10
	v_and_or_b32 v6, v6, s28, v7
	v_lshrrev_b32_e32 v8, 2, v8
	v_xor_b32_e32 v11, v18, v223
	v_mad_i64_i32 v[6:7], s[38:39], v6, s29, v[0:1]
	v_and_b32_e32 v8, 0x180, v8
	v_mov_b32_e32 v9, v213
	v_add_u32_e32 v10, s35, v10
	v_lshl_add_u64 v[6:7], v[6:7], 0, v[8:9]
	v_lshlrev_b32_e32 v8, 4, v11
	v_ashrrev_i32_e32 v11, 31, v10
	v_bfe_u32 v113, v223, 4, 2
	v_lshlrev_b64 v[10:11], 12, v[10:11]
	v_or_b32_e32 v15, 16, v14
	v_xor_b32_e32 v4, v113, v223
	v_lshrrev_b32_e32 v5, 2, v5
	v_and_b32_e32 v8, 0x70, v8
	s_waitcnt lgkmcnt(0)
	v_lshl_add_u64 v[10:11], s[0:1], 0, v[10:11]
	v_add_u32_e32 v12, s34, v15
	v_mad_i64_i32 v[2:3], s[38:39], v2, s29, v[0:1]
	v_and_b32_e32 v212, 0x180, v5
	v_lshlrev_b32_e32 v4, 4, v4
	v_lshl_add_u64 v[6:7], v[6:7], 0, v[8:9]
	v_lshl_add_u64 v[8:9], v[10:11], 0, v[8:9]
	v_lshlrev_b32_e32 v11, 4, v12
	v_lshl_add_u64 v[2:3], v[2:3], 0, v[212:213]
	v_and_b32_e32 v212, 0x70, v4
	v_lshlrev_b32_e32 v10, 2, v12
	v_and_b32_e32 v11, 0x1f70, v11
	v_lshlrev_b32_e32 v33, 12, v24
	v_lshl_add_u64 v[2:3], v[2:3], 0, v[212:213]
	v_add_u32_e32 v4, s35, v14
	v_and_or_b32 v10, v10, s28, v11
	v_lshrrev_b32_e32 v12, 2, v12
	v_readfirstlane_b32 s37, v33
	v_lshl_add_u64 v[2:3], v[2:3], 0, s[12:13]
	v_ashrrev_i32_e32 v5, 31, v4
	v_mad_i64_i32 v[10:11], s[38:39], v10, s29, v[0:1]
	v_and_b32_e32 v12, 0x180, v12
	v_mov_b32_e32 v13, v213
	v_or_b32_e32 v14, 24, v14
	s_mov_b32 m0, s37
	v_lshlrev_b64 v[4:5], 12, v[4:5]
	v_lshl_add_u64 v[10:11], v[10:11], 0, v[12:13]
	v_add_u32_e32 v12, s35, v15
	v_add_u32_e32 v16, s34, v14
	global_load_lds_dwordx4 v[2:3], off
	v_add_u32_e32 v2, 0x4000, v33
	v_lshl_add_u64 v[4:5], s[0:1], 0, v[4:5]
	v_ashrrev_i32_e32 v13, 31, v12
	v_lshlrev_b32_e32 v19, 4, v16
	v_readfirstlane_b32 s37, v2
	v_or_b32_e32 v2, 0x400, v33
	v_lshl_add_u64 v[4:5], v[4:5], 0, v[212:213]
	v_lshlrev_b64 v[12:13], 12, v[12:13]
	v_lshrrev_b32_e32 v22, 1, v14
	v_lshlrev_b32_e32 v17, 2, v16
	v_and_b32_e32 v19, 0x1ff0, v19
	s_mov_b32 m0, s37
	v_readfirstlane_b32 s37, v2
	v_add_u32_e32 v2, 0x4400, v33
	v_lshl_add_u64 v[6:7], v[6:7], 0, s[12:13]
	v_lshl_add_u64 v[12:13], s[0:1], 0, v[12:13]
	v_xor_b32_e32 v15, v22, v223
	v_and_or_b32 v17, v17, s28, v19
	v_lshrrev_b32_e32 v16, 2, v16
	global_load_lds_dwordx4 v[4:5], off
	s_mov_b32 m0, s37
	v_readfirstlane_b32 s37, v2
	v_or_b32_e32 v2, 0x800, v33
	v_lshl_add_u64 v[10:11], v[10:11], 0, v[212:213]
	v_lshl_add_u64 v[12:13], v[12:13], 0, v[212:213]
	v_mad_i64_i32 v[0:1], s[38:39], v17, s29, v[0:1]
	v_and_b32_e32 v212, 0x180, v16
	v_lshlrev_b32_e32 v15, 4, v15
	global_load_lds_dwordx4 v[6:7], off
	s_mov_b32 m0, s37
	v_readfirstlane_b32 s37, v2
	v_add_u32_e32 v2, 0x4800, v33
	v_lshl_add_u64 v[10:11], v[10:11], 0, s[12:13]
	v_lshl_add_u64 v[0:1], v[0:1], 0, v[212:213]
	v_and_b32_e32 v212, 0x70, v15
	global_load_lds_dwordx4 v[8:9], off
	s_mov_b32 m0, s37
	v_readfirstlane_b32 s37, v2
	v_or_b32_e32 v2, 0xc00, v33
	v_lshl_add_u64 v[0:1], v[0:1], 0, v[212:213]
	v_add_u32_e32 v14, s35, v14
	global_load_lds_dwordx4 v[10:11], off
	s_mov_b32 m0, s37
	v_readfirstlane_b32 s37, v2
	v_lshl_add_u64 v[0:1], v[0:1], 0, s[12:13]
	v_ashrrev_i32_e32 v15, 31, v14
	global_load_lds_dwordx4 v[12:13], off
	s_mov_b32 m0, s37
	v_lshlrev_b64 v[14:15], 12, v[14:15]
	global_load_lds_dwordx4 v[0:1], off
	v_add_u32_e32 v0, 0x4c00, v33
	v_lshl_add_u64 v[14:15], s[0:1], 0, v[14:15]
	v_readfirstlane_b32 s37, v0
	v_lshl_add_u64 v[14:15], v[14:15], 0, v[212:213]
	s_mov_b32 m0, s37
	v_or_b32_e32 v0, s36, v30
	global_load_lds_dwordx4 v[14:15], off
	v_add_u32_e32 v0, v0, v31
	v_and_b32_e32 v227, 15, v223
	v_lshrrev_b32_e32 v17, 1, v223
	v_ashrrev_i32_e32 v1, 31, v0
; DI int ltid() { int x = threadIdx.x; asm volatile("" : "+v"(x)); return x; }
; template <class ARow, class Epi>
; DI void gemm_tile(const ARow& arow, long a_kstride, const u16* __restrict__ Bt, long ldb, int K, int m0, int n0,
;                   const Epi& epi, char* smem) {
;   const int tid = ltid(), lane = tid & 63, wid = tid >> 6;
;   const int r = lane & 31, h = lane >> 5;
;   const int wn = wid & 1, wm = wid >> 1;
;   const u16* ap[4]; const u16* bp[4];
;   {
;     const int lr = lane >> 3;
; #pragma unroll
;     for (int j = 0; j < 4; ++j) {
;       const int row = (wid * 4 + j) * 8 + lr;
;       const int cc = (lane & 7) ^ ((row >> 1) & 7);
;       ap[j] = arow(m0 + row) + cc * 8;
;       bp[j] = Bt + (long)(n0 + row) * ldb + cc * 8;
;     }
;   }
;     ...
;   const int fr = lane & 15, fq = lane >> 4;
;   int foff[2];
; #pragma unroll
;   for (int ks = 0; ks < 2; ++ks) foff[ks] = fr * 128 + ((((4 * ks + fq) ^ ((fr >> 1) & 7))) << 4);
;   f32x4 acc[4][4];
; #pragma unroll
;   for (int a = 0; a < 4; ++a)
; #pragma unroll
;     for (int b = 0; b < 4; ++b) acc[a][b] = (f32x4){0.f, 0.f, 0.f, 0.f};
;   const int KT = K >> 6;
;   GEMM_STAGE(0, 0);
;   asm volatile("s_waitcnt vmcnt(0)" ::: "memory");
;   __syncthreads();
	v_bitop3_b32 v2, v113, 7, v223 bitop3:0x48
	v_lshlrev_b32_e32 v16, 7, v227
	v_bfe_u32 v19, v223, 1, 3
	v_bitop3_b32 v17, v113, v17, 7 bitop3:0x78
	s_add_u32 s0, s0, 0x80
	v_lshlrev_b64 v[0:1], 12, v[0:1]
	v_lshlrev_b32_e32 v2, 4, v2
	v_lshl_or_b32 v36, v17, 4, v16
	v_bitop3_b32 v17, v113, v19, 4 bitop3:0x36
	s_addc_u32 s1, s1, 0
	v_or_b32_e32 v0, v0, v2
	v_or_b32_e32 v3, 8, v30
	v_lshl_or_b32 v32, v17, 4, v16
	v_lshl_add_u64 v[16:17], s[0:1], 0, v[0:1]
	v_or_b32_e32 v0, s36, v3
	v_add_u32_e32 v0, v0, v31
	v_ashrrev_i32_e32 v1, 31, v0
	v_bitop3_b32 v4, v18, 7, v223 bitop3:0x48
	v_lshlrev_b64 v[0:1], 12, v[0:1]
	v_lshlrev_b32_e32 v4, 4, v4
	v_or_b32_e32 v0, v0, v4
	v_or_b32_e32 v5, 16, v30
	v_lshl_add_u64 v[18:19], s[0:1], 0, v[0:1]
	v_or_b32_e32 v0, s36, v5
	v_add_u32_e32 v0, v0, v31
	v_ashrrev_i32_e32 v1, 31, v0
	v_lshlrev_b64 v[0:1], 12, v[0:1]
	v_or_b32_e32 v0, v0, v2
	v_or_b32_e32 v6, 24, v30
	v_lshl_add_u64 v[20:21], s[0:1], 0, v[0:1]
	v_or_b32_e32 v0, s36, v6
	v_add_u32_e32 v0, v0, v31
	v_ashrrev_i32_e32 v1, 31, v0
	v_bitop3_b32 v7, v22, 7, v223 bitop3:0x48
	v_lshlrev_b64 v[0:1], 12, v[0:1]
	v_lshlrev_b32_e32 v7, 4, v7
	v_or_b32_e32 v0, v0, v7
	v_lshl_add_u64 v[22:23], s[0:1], 0, v[0:1]
	v_lshlrev_b16_e32 v1, 5, v24
	v_add_u16_e32 v8, s21, v1
	v_or_b32_e32 v0, s20, v6
	v_bitop3_b16 v1, v8, 24, v30 bitop3:0xfe
	v_add_u32_e32 v6, v0, v31
	v_and_b32_e32 v1, 0x1ff, v1
	v_lshlrev_b32_e32 v0, 2, v6
	v_lshlrev_b32_e32 v1, 4, v1
	v_and_or_b32 v0, v0, s28, v1
	v_lshrrev_b32_e32 v6, 2, v6
	v_mad_i64_i32 v[0:1], s[0:1], v0, s29, 0
	v_and_b32_e32 v6, 0x180, v6
	v_or3_b32 v0, v0, v6, v7
	v_and_b32_e32 v112, 1, v24
	v_lshl_add_u64 v[24:25], s[10:11], 0, v[0:1]
	v_or_b32_e32 v0, s20, v5
	v_bitop3_b16 v1, v8, 16, v30 bitop3:0xfe
	v_add_u32_e32 v5, v0, v31
	v_and_b32_e32 v1, 0x1f7, v1
	v_lshlrev_b32_e32 v0, 2, v5
	v_lshlrev_b32_e32 v1, 4, v1
	v_and_or_b32 v0, v0, s28, v1
	v_lshrrev_b32_e32 v5, 2, v5
	v_mad_i64_i32 v[0:1], s[0:1], v0, s29, 0
	v_and_b32_e32 v5, 0x180, v5
	v_or3_b32 v0, v0, v5, v2
	v_lshl_add_u64 v[26:27], s[10:11], 0, v[0:1]
	v_or_b32_e32 v0, s20, v3
	v_bitop3_b16 v1, v8, 8, v30 bitop3:0xfe
	v_add_u32_e32 v3, v0, v31
	v_and_b32_e32 v1, 0x1ef, v1
	v_lshlrev_b32_e32 v0, 2, v3
	v_lshlrev_b32_e32 v1, 4, v1
	v_and_or_b32 v0, v0, s28, v1
	v_lshrrev_b32_e32 v3, 2, v3
	v_mad_i64_i32 v[0:1], s[0:1], v0, s29, 0
	v_and_b32_e32 v3, 0x180, v3
	v_or3_b32 v0, v0, v3, v4
	v_lshl_add_u64 v[28:29], s[10:11], 0, v[0:1]
	v_or_b32_e32 v0, s20, v30
	v_or_b32_e32 v1, v8, v30
	v_add_u32_e32 v3, v0, v31
	v_and_b32_e32 v1, 0x1e7, v1
	v_lshlrev_b32_e32 v0, 2, v3
	v_lshlrev_b32_e32 v1, 4, v1
	v_and_or_b32 v0, v0, s28, v1
	v_lshrrev_b32_e32 v3, 2, v3
	s_waitcnt vmcnt(0)
	v_mad_i64_i32 v[0:1], s[0:1], v0, s29, 0
	v_and_b32_e32 v3, 0x180, v3
	v_ashrrev_i32_e32 v254, 7, v223
	v_or3_b32 v0, v0, v3, v2
	v_lshlrev_b32_e32 v38, 13, v254
	v_lshlrev_b32_e32 v37, 13, v112
	v_lshl_add_u64 v[30:31], s[10:11], 0, v[0:1]
	s_mov_b64 s[20:21], 0
	s_mov_b32 s0, 0
	v_mov_b32_e32 v8, 0
	v_mov_b32_e32 v9, v213
	v_mov_b32_e32 v10, v213
	v_mov_b32_e32 v11, v213
	v_mov_b32_e32 v64, 0
	v_mov_b32_e32 v65, v213
	v_mov_b32_e32 v66, v213
	v_mov_b32_e32 v67, v213
	v_mov_b32_e32 v88, 0
	v_mov_b32_e32 v89, v213
	v_mov_b32_e32 v90, v213
	v_mov_b32_e32 v91, v213
	v_mov_b32_e32 v104, 0
	v_mov_b32_e32 v105, v213
	v_mov_b32_e32 v106, v213
	v_mov_b32_e32 v107, v213
	v_mov_b32_e32 v0, 0
	v_mov_b32_e32 v1, v213
	v_mov_b32_e32 v2, v213
	v_mov_b32_e32 v3, v213
	v_mov_b32_e32 v56, 0
	v_mov_b32_e32 v57, v213
	v_mov_b32_e32 v58, v213
	v_mov_b32_e32 v59, v213
	v_mov_b32_e32 v80, 0
	v_mov_b32_e32 v81, v213
	v_mov_b32_e32 v82, v213
	v_mov_b32_e32 v83, v213
	v_mov_b32_e32 v128, 0
	v_mov_b32_e32 v129, v213
	v_mov_b32_e32 v130, v213
	v_mov_b32_e32 v131, v213
	v_mov_b32_e32 v4, 0
	v_mov_b32_e32 v5, v213
	v_mov_b32_e32 v6, v213
	v_mov_b32_e32 v7, v213
	v_mov_b32_e32 v60, 0
	v_mov_b32_e32 v61, v213
	v_mov_b32_e32 v62, v213
	v_mov_b32_e32 v63, v213
	v_mov_b32_e32 v84, 0
	v_mov_b32_e32 v85, v213
	v_mov_b32_e32 v86, v213
	v_mov_b32_e32 v87, v213
	v_mov_b32_e32 v140, 0
	v_mov_b32_e32 v141, v213
	v_mov_b32_e32 v142, v213
	v_mov_b32_e32 v143, v213
	v_mov_b32_e32 v12, 0
	v_mov_b32_e32 v13, v213
	v_mov_b32_e32 v14, v213
	v_mov_b32_e32 v15, v213
	v_mov_b32_e32 v68, 0
	v_mov_b32_e32 v69, v213
	v_mov_b32_e32 v70, v213
	v_mov_b32_e32 v71, v213
	v_mov_b32_e32 v92, 0
	v_mov_b32_e32 v93, v213
	v_mov_b32_e32 v94, v213
	v_mov_b32_e32 v95, v213
	v_mov_b32_e32 v144, 0
	v_mov_b32_e32 v145, v213
	v_mov_b32_e32 v146, v213
	v_mov_b32_e32 v147, v213
	s_waitcnt vmcnt(0) lgkmcnt(0)
	s_barrier
	.p2align	6

; DI float bflo(unsigned v) { return __uint_as_float(v << 16); }
; DI float bfhi(unsigned v) { return __uint_as_float(v & 0xffff0000u); }
; DI void cmp2_phase(const Params& p) {
;     ...
;     const int c = task >> 10, m = (task & 1023) * 4 + rr;
;     const u16* hrow = p.h1 + ((long)c * 4096 + m) * 256;
;     const float* w2 = p.a_w2_k; if (c) w2 = p.a_w2_v;
;     float s = 0.f;
;     for (int k = 0; k < 256; k += 2) {
;       const unsigned hv = *(const unsigned*)(hrow + k);
;       s += bflo(hv) * w2[k * 64 + nn] + bfhi(hv) * w2[(k + 1) * 64 + nn];
.Lcmp2_have_w:
	v_add_u32_e32 v96, 0xfffff100, v2
	.p2align	6

; DI unsigned xb_ld(unsigned* p) { return __hip_atomic_load(p, __ATOMIC_RELAXED, __HIP_MEMORY_SCOPE_AGENT); }
; DI unsigned xb_add(unsigned* p, unsigned v) { return __hip_atomic_fetch_add(p, v, __ATOMIC_RELAXED, __HIP_MEMORY_SCOPE_AGENT); }
; #define XB_SPIN(cond, bar) do { unsigned _sp = 0; while (cond) { __builtin_amdgcn_s_sleep(1); \
;     if ((++_sp & 255u) == 0u) { if (xb_ld(&(bar)[XB_TMO])) break; if (_sp > XB_SPIN_CAP) { atomicAdd(&(bar)[XB_TMO], 1u); break; } } } } while (0)
; DI void xcd_barrier(const XcdBarrier& b) {
;     ...
;       else XB_SPIN(xb_ld(&bar[XB_TOPGEN]) == tg, bar);
;       __builtin_amdgcn_fence(__ATOMIC_ACQUIRE, "agent");
;       xb_add(&bar[XB_XGEN(b.x)], 1u);
;       asm volatile("s_waitcnt vmcnt(0)" ::: "memory");
;     } else {
;       XB_SPIN(xb_ld(&bar[XB_XGEN(b.x)]) == gen, bar);
.LBB0_767:
	s_and_b64 s[14:15], exec, s[14:15]
	s_or_b64 s[10:11], s[14:15], s[10:11]
	s_andn2_b64 s[12:13], s[12:13], exec
	s_and_b64 s[14:15], s[16:17], exec
	s_or_b64 s[12:13], s[12:13], s[14:15]
	s_andn2_b64 exec, exec, s[10:11]
	s_cbranch_execz .LBB0_774
	.p2align	6

; DI unsigned xb_ld(unsigned* p) { return __hip_atomic_load(p, __ATOMIC_RELAXED, __HIP_MEMORY_SCOPE_AGENT); }
; DI unsigned xb_add(unsigned* p, unsigned v) { return __hip_atomic_fetch_add(p, v, __ATOMIC_RELAXED, __HIP_MEMORY_SCOPE_AGENT); }
; #define XB_SPIN(cond, bar) do { unsigned _sp = 0; while (cond) { __builtin_amdgcn_s_sleep(1); \
;     if ((++_sp & 255u) == 0u) { if (xb_ld(&(bar)[XB_TMO])) break; if (_sp > XB_SPIN_CAP) { atomicAdd(&(bar)[XB_TMO], 1u); break; } } } } while (0)
; DI void xcd_barrier(const XcdBarrier& b) {
;     ...
;       else XB_SPIN(xb_ld(&bar[XB_TOPGEN]) == tg, bar);
;       __builtin_amdgcn_fence(__ATOMIC_ACQUIRE, "agent");
;       xb_add(&bar[XB_XGEN(b.x)], 1u);
;       asm volatile("s_waitcnt vmcnt(0)" ::: "memory");
;     } else {
;       XB_SPIN(xb_ld(&bar[XB_XGEN(b.x)]) == gen, bar);
.LBB0_784:
	s_xor_b64 s[16:17], s[16:17], -1
	s_and_b64 s[18:19], exec, s[20:21]
	s_or_b64 s[12:13], s[18:19], s[12:13]
	s_andn2_b64 s[14:15], s[14:15], exec
	s_and_b64 s[16:17], s[16:17], exec
	s_or_b64 s[14:15], s[14:15], s[16:17]
	s_andn2_b64 exec, exec, s[12:13]
	s_cbranch_execz .LBB0_791
	.p2align	6

; DI int ltid() { int x = threadIdx.x; asm volatile("" : "+v"(x)); return x; }
; DI void nsa_attn_phase(const Params& p, char* smem) {
;     ...
;     const int task = fetch_task(p.ctr + 0, smem);
;     if (task >= 2048) break;
;     const int tid = ltid(), lane = tid & 63, wid = tid >> 6, r = lane & 31, h = lane >> 5;
;     const int qt = 255 - (task >> 3), bh = task & 7, b = bh >> 2, hk = bh & 3;
;     const int hq = hk * 4 + wid;
;     const int t0 = qt * 32, tq = t0 + r;
;     const long tok = (long)b * SEQ + tq;
;     const float slope2 = exp2f(-0.5f * (float)(hq + 1)) * LOG2E;
;     bf16x8 qf[4];
;     load_q(qf, p.qkvz + tok * LD + hq * 64, h);
;     const float qb_s = q_bound(qf, p.kmax2[b * 64 + 24 + hk]), qb_w = q_bound(qf, p.kmax2[b * 64 + 32 + hk]);
;     const float* gp = p.gates + tok * 48;
;     const float g_c = gp[hq], g_s = gp[16 + hq], g_w = gp[32 + hq];
;     __syncthreads();
;     {
;       const int tz = ltid();
;       for (int i = tz; i < 32 * 128; i += 256) imp[i] = 0.f;
;       if (tz < 128) selm[tz] = 0u;
;       if (tz < 4) um[tz] = 0u;
.LBB0_807:
	s_or_b64 exec, exec, s[0:1]
	s_waitcnt lgkmcnt(0)
	s_barrier
	ds_read_b32 v0, v206
	s_mov_b32 s98, 1
	s_movk_i32 s0, 0x7ff
	s_waitcnt lgkmcnt(0)
	v_cmp_lt_i32_e32 vcc, s0, v0
	v_readfirstlane_b32 s20, v0
	s_mov_b64 s[0:1], -1
	s_cbranch_vccnz .LBB0_802
	v_mov_b32_e32 v105, v222
	s_and_b32 s0, s20, 3
	s_lshl_b32 s5, s0, 2
	v_ashrrev_i32_e32 v107, 6, v105
	v_add_u32_e32 v2, s5, v107
	s_bfe_u32 s4, s20, 0x10002
	v_add_u32_e32 v0, 1, v2
	v_writelane_b32 v255, s0, 36
	s_lshl_b32 s63, s20, 2
	s_lshl_b32 s0, s4, 13
	v_cvt_f32_i32_e32 v7, v0
	s_andn2_b32 s63, s63, 31
	v_writelane_b32 v255, s0, 37
	v_and_b32_e32 v104, 31, v105
	s_sub_i32 s62, 0x1fe0, s63
	v_readlane_b32 s8, v255, 28
	v_or_b32_e32 v227, s62, v104
	v_readlane_b32 s10, v255, 30
	v_readlane_b32 s11, v255, 31
	v_add_u32_e32 v176, s0, v227
	v_mul_f32_e32 v0, -0.5, v7
	s_mov_b32 s0, 0xc2fc0000
	v_mov_b64_e32 v[4:5], s[10:11]
	v_lshlrev_b32_e32 v180, 6, v2
	v_bfe_u32 v226, v105, 5, 1
	v_cmp_gt_f32_e32 vcc, s0, v0
	v_mad_u64_u32 v[178:179], s[0:1], v176, s33, v[4:5]
	v_ashrrev_i32_e32 v181, 31, v180
	v_lshl_add_u64 v[4:5], v[180:181], 1, v[178:179]
	v_lshlrev_b32_e32 v0, 4, v226
	v_lshl_add_u64 v[4:5], v[4:5], 0, v[0:1]
	global_load_dwordx4 v[160:163], v[4:5], off
	global_load_dwordx4 v[164:167], v[4:5], off offset:32
	global_load_dwordx4 v[168:171], v[4:5], off offset:64
	global_load_dwordx4 v[172:175], v[4:5], off offset:96
	s_lshl_b32 s0, s4, 8
	s_or_b32 s0, s0, s5
	v_readlane_b32 s12, v255, 24
	v_mov_b32_e32 v3, s0
	v_readlane_b32 s13, v255, 25
	s_mov_b32 s0, 0xf800000
	v_readlane_b32 s9, v255, 29
	v_readlane_b32 s14, v255, 26
	v_readlane_b32 s15, v255, 27
	s_mov_b32 s21, 0xf800000
	global_load_dword v0, v3, s[12:13] offset:96
	s_waitcnt vmcnt(4)
	v_and_b32_e32 v5, 0xffff0000, v160
	global_load_dword v3, v3, s[12:13] offset:128
	v_lshlrev_b32_e32 v4, 16, v160
	v_mul_f32_e32 v6, v5, v5
	v_fmac_f32_e32 v6, v4, v4
	v_lshlrev_b32_e32 v4, 16, v161
	v_fmac_f32_e32 v6, v4, v4
	v_and_b32_e32 v4, 0xffff0000, v161
	v_fmac_f32_e32 v6, v4, v4
	v_lshlrev_b32_e32 v4, 16, v162
	v_fmac_f32_e32 v6, v4, v4
	v_and_b32_e32 v4, 0xffff0000, v162
	v_fmac_f32_e32 v6, v4, v4
	v_lshlrev_b32_e32 v4, 16, v163
	v_fmac_f32_e32 v6, v4, v4
	v_and_b32_e32 v4, 0xffff0000, v163
	v_fmac_f32_e32 v6, v4, v4
	s_waitcnt vmcnt(4)
	v_lshlrev_b32_e32 v4, 16, v164
	v_fmac_f32_e32 v6, v4, v4
	v_and_b32_e32 v4, 0xffff0000, v164
	v_fmac_f32_e32 v6, v4, v4
	v_lshlrev_b32_e32 v4, 16, v165
	v_fmac_f32_e32 v6, v4, v4
	v_and_b32_e32 v4, 0xffff0000, v165
	v_fmac_f32_e32 v6, v4, v4
	v_lshlrev_b32_e32 v4, 16, v166
	v_fmac_f32_e32 v6, v4, v4
	v_and_b32_e32 v4, 0xffff0000, v166
	v_fmac_f32_e32 v6, v4, v4
	v_lshlrev_b32_e32 v4, 16, v167
	v_fmac_f32_e32 v6, v4, v4
	v_and_b32_e32 v4, 0xffff0000, v167
	v_fmac_f32_e32 v6, v4, v4
	s_waitcnt vmcnt(3)
	v_lshlrev_b32_e32 v4, 16, v168
	v_fmac_f32_e32 v6, v4, v4
	v_and_b32_e32 v4, 0xffff0000, v168
	v_fmac_f32_e32 v6, v4, v4
	v_lshlrev_b32_e32 v4, 16, v169
	v_fmac_f32_e32 v6, v4, v4
	v_and_b32_e32 v4, 0xffff0000, v169
	v_fmac_f32_e32 v6, v4, v4
	v_lshlrev_b32_e32 v4, 16, v170
	v_fmac_f32_e32 v6, v4, v4
	v_and_b32_e32 v4, 0xffff0000, v170
	v_fmac_f32_e32 v6, v4, v4
	v_lshlrev_b32_e32 v4, 16, v171
	v_fmac_f32_e32 v6, v4, v4
	v_and_b32_e32 v4, 0xffff0000, v171
	v_fmac_f32_e32 v6, v4, v4
	s_waitcnt vmcnt(2)
	v_lshlrev_b32_e32 v4, 16, v172
	v_fmac_f32_e32 v6, v4, v4
	v_and_b32_e32 v4, 0xffff0000, v172
	v_fmac_f32_e32 v6, v4, v4
	v_lshlrev_b32_e32 v4, 16, v173
	v_fmac_f32_e32 v6, v4, v4
	v_and_b32_e32 v4, 0xffff0000, v173
	v_fmac_f32_e32 v6, v4, v4
	v_lshlrev_b32_e32 v4, 16, v174
	v_fmac_f32_e32 v6, v4, v4
	v_and_b32_e32 v4, 0xffff0000, v174
	v_fmac_f32_e32 v6, v4, v4
	v_lshlrev_b32_e32 v4, 16, v175
	v_fmac_f32_e32 v6, v4, v4
	v_and_b32_e32 v4, 0xffff0000, v175
	v_fmac_f32_e32 v6, v4, v4
	v_mov_b32_e32 v4, v6
	v_mov_b32_e32 v5, v6
	s_nop 1
	v_permlane32_swap_b32_e32 v4, v5
	v_add_f32_e32 v4, v4, v5
	s_waitcnt vmcnt(1)
	v_mul_f32_e32 v0, v0, v4
	v_cmp_gt_f32_e64 s[4:5], s0, v0
	v_mul_f32_e32 v5, 0x4f800000, v0
	s_waitcnt vmcnt(0)
	v_mul_f32_e32 v3, v3, v4
	v_cndmask_b32_e64 v0, v0, v5, s[4:5]
	v_cmp_gt_f32_e64 s[6:7], s0, v3
	v_mul_f32_e32 v4, 0x4f800000, v3
	v_sqrt_f32_e32 v8, v0
	v_cndmask_b32_e64 v10, v3, v4, s[6:7]
	v_readlane_b32 s0, v255, 0
	v_sqrt_f32_e32 v12, v10
	v_readlane_b32 s1, v255, 1
	s_load_dwordx2 s[0:1], s[0:1], 0x140
	v_add_u32_e32 v9, -1, v8
	v_fma_f32 v5, -v9, v8, v0
	v_add_u32_e32 v11, 1, v8
	v_add_u32_e32 v13, -1, v12
	v_cmp_ge_f32_e64 s[8:9], 0, v5
	v_fma_f32 v5, -v11, v8, v0
	v_fma_f32 v3, -v13, v12, v10
	v_add_u32_e32 v14, 1, v12
	v_cmp_lt_f32_e64 s[10:11], 0, v5
	v_cmp_ge_f32_e64 s[12:13], 0, v3
	v_fma_f32 v3, -v14, v12, v10
	s_waitcnt lgkmcnt(0)
	v_mov_b64_e32 v[4:5], s[0:1]
	s_movk_i32 s0, 0xc0
	v_cmp_lt_f32_e64 s[14:15], 0, v3
	v_mad_u64_u32 v[4:5], s[0:1], v176, s0, v[4:5]
	v_ashrrev_i32_e32 v3, 31, v2
	v_lshl_add_u64 v[2:3], v[2:3], 2, v[4:5]
	global_load_dword v229, v[2:3], off
	global_load_dword v228, v[2:3], off offset:64
	global_load_dword v181, v[2:3], off offset:128
	v_mov_b32_e32 v2, v222
	s_movk_i32 s0, 0x1000
	s_barrier
	s_nop 0
	v_cmp_gt_i32_e64 s[16:17], s0, v2
	s_and_saveexec_b64 s[0:1], s[16:17]
	s_cbranch_execz .LBB0_811
	v_lshl_add_u32 v3, v2, 2, v208
	v_add_u32_e32 v4, 0xffffff00, v2
	s_mov_b64 s[18:19], 0
	.p2align	6

; DI int ltid() { int x = threadIdx.x; asm volatile("" : "+v"(x)); return x; }
; #define RAW_BARRIER() do { asm volatile("s_waitcnt lgkmcnt(0)" ::: "memory"); __builtin_amdgcn_s_barrier(); } while (0)
; template <int DV, bool SEL, bool TERM> ...
;   constexpr int G = Ring<DV>::G;
;   const int tid = ltid(), lane = tid & 63, wid = tid >> 6, r = lane & 31, h = lane >> 5;
;   unsigned* flags = (unsigned*)(smem + SM_FLAG);
;   int foff[4];
;   make_foff(foff, r, h);
;   unsigned done = 0u;
;   const float sk = slope2 * (float)kp_mul;
;   RAW_BARRIER();
;   int t = prev_active(thi - 1, tlo, um);
;   int t1 = (t >= tlo) ? prev_active(t - 1, tlo, um) : t;
;   if (t >= tlo) kv_issue<DV, true>(smem, 0, kbase, kpitch, vbase, vpitch, t, lane, wid);
;   if (t1 >= tlo) kv_issue<DV, true>(smem, 1, kbase, kpitch, vbase, vpitch, t1, lane, wid);
;   int c = 0;
; DI void nsa_attn_phase(const Params& p, char* smem) {
;     ...
;     const u16* kc = p.kcmp + (long)bh * 512 * 64;
;     const u16* vc = p.vcmp + (long)bh * 512 * 64;
;     const int tmax = t0 + 31;
;     const int ncmp_tiles = (tmax >= 31) ? (((tmax - 31) >> 4) >> 6) + 1 : 0;
;     f32x16 ot[2];
;     f32x16 tot[2];
;     int foff[4];
;     make_foff(foff, r, h);
;     float m = 0.f, l = 0.f;
; #pragma unroll
;     for (int dc = 0; dc < 2; ++dc)
; #pragma unroll
;       for (int i = 0; i < 16; ++i) ot[dc][i] = 0.f;
;     int tc_lo = ncmp_tiles;
;     flash_pass<64, false, true>(smem, kc, 64, vc, 64, 0, ncmp_tiles, nullptr, qf, tq - 31, 16, BIGW, slope2, t0 - 31, tmax - 31, nullptr, q_bound(qf, p.kmax2[480 + bh]), ot, m, l, &tc_lo);
.LBB0_817:
	v_add_f32_e32 v6, v6, v11
	s_waitcnt vmcnt(0)
	v_mul_f32_e32 v6, v9, v6
	v_mul_f32_e32 v9, 0x4f800000, v6
	v_cmp_gt_f32_e32 vcc, s21, v6
	v_mul_f32_e32 v182, 0x3fb8aa3b, v4
	v_and_b32_e32 v10, 63, v7
	v_cndmask_b32_e32 v6, v6, v9, vcc
	v_sqrt_f32_e32 v9, v6
	v_lshl_add_u64 v[84:85], s[12:13], 0, v[0:1]
	v_lshl_add_u64 v[86:87], s[12:13], 0, v[2:3]
	v_bfe_u32 v0, v7, 2, 2
	v_add_u32_e32 v4, -1, v9
	v_fma_f32 v11, -v4, v9, v6
	v_cmp_ge_f32_e64 s[4:5], 0, v11
	v_add_u32_e32 v11, 1, v9
	v_lshrrev_b32_e32 v2, 3, v7
	v_cndmask_b32_e64 v4, v9, v4, s[4:5]
	v_fma_f32 v9, -v11, v9, v6
	v_cmp_lt_f32_e64 s[4:5], 0, v9
	s_mov_b32 s0, 0x3f828f5c
	v_and_or_b32 v0, v2, 4, v0
	v_cndmask_b32_e64 v4, v4, v11, s[4:5]
	v_mul_f32_e32 v9, 0x37800000, v4
	v_cndmask_b32_e32 v4, v4, v9, vcc
	v_cmp_class_f32_e32 vcc, v6, v207
	v_lshlrev_b32_e32 v2, 1, v10
	v_lshlrev_b32_e32 v3, 3, v10
	v_cndmask_b32_e32 v4, v4, v6, vcc
	v_fma_f32 v116, v4, s0, 1.0
	v_lshrrev_b32_e32 v4, 5, v10
	v_lshlrev_b32_e32 v6, 7, v7
	v_lshrrev_b32_e32 v9, 1, v7
	v_bfe_u32 v11, v7, 1, 3
	v_lshlrev_b32_e32 v0, 7, v0
	v_and_b32_e32 v2, 32, v2
	v_and_b32_e32 v3, 24, v3
	v_and_b32_e32 v6, 0xf80, v6
	v_bitop3_b32 v9, v4, v9, 7 bitop3:0x78
	v_bitop3_b32 v12, v4, v11, 2 bitop3:0x36
	v_bitop3_b32 v13, v4, v11, 4 bitop3:0x36
	v_bitop3_b32 v11, v4, v11, 6 bitop3:0x36
	v_or3_b32 v119, v3, v2, v0
	v_lshlrev_b32_e32 v0, 3, v7
	v_mov_b32_e32 v30, v1
	v_mov_b32_e32 v31, v1
	v_mul_f32_e32 v82, 0x41800000, v182
	v_lshl_add_u32 v117, v8, 2, v213
	v_cmp_eq_u32_e64 s[4:5], 0, v10
	v_and_b32_e32 v120, 64, v0
	v_bitop3_b32 v121, v0, 64, v0 bitop3:0xc
	v_lshlrev_b32_e32 v123, 6, v4
	v_add_u32_e32 v124, 0xa400, v5
	v_add_u32_e32 v125, 0x8400, v5
	v_add_u32_e32 v126, 0xa000, v5
	v_add_u32_e32 v127, 0x8000, v5
	v_lshl_or_b32 v128, v11, 4, v6
	v_lshl_or_b32 v129, v9, 4, v6
	v_lshl_or_b32 v130, v13, 4, v6
	v_lshl_or_b32 v131, v12, 4, v6
	v_mov_b32_e32 v0, v1
	v_mov_b32_e32 v2, v1
	v_mov_b32_e32 v3, v1
	v_mov_b32_e32 v4, v1
	v_mov_b32_e32 v5, v1
	v_mov_b32_e32 v6, v1
	v_mov_b32_e32 v7, v1
	v_mov_b32_e32 v8, v1
	v_mov_b32_e32 v9, v1
	v_mov_b32_e32 v10, v1
	v_mov_b32_e32 v11, v1
	v_mov_b32_e32 v12, v1
	v_mov_b32_e32 v13, v1
	v_mov_b32_e32 v14, v1
	v_mov_b32_e32 v15, v1
	v_mov_b32_e32 v16, v1
	v_mov_b32_e32 v17, v1
	v_mov_b32_e32 v18, v1
	v_mov_b32_e32 v19, v1
	v_mov_b32_e32 v20, v1
	v_mov_b32_e32 v21, v1
	v_mov_b32_e32 v22, v1
	v_mov_b32_e32 v23, v1
	v_mov_b32_e32 v24, v1
	v_mov_b32_e32 v25, v1
	v_mov_b32_e32 v26, v1
	v_mov_b32_e32 v27, v1
	v_mov_b32_e32 v28, v1
	v_mov_b32_e32 v29, v1
	v_mov_b32_e32 v108, 0
	v_mov_b64_e32 v[62:63], v[30:31]
	s_add_i32 s6, s14, 1
	v_subrev_u32_e32 v114, 31, v227
	s_mov_b32 s16, 0
	s_mov_b32 s17, 2
	v_or_b32_e32 v118, v111, v110
	v_add_u32_e32 v122, -15, v227
	v_mov_b32_e32 v83, v82
	v_mov_b32_e32 v88, v82
	v_mov_b32_e32 v89, v82
	v_mov_b32_e32 v90, v82
	v_mov_b32_e32 v91, v82
	v_mov_b32_e32 v92, v82
	v_mov_b32_e32 v93, v82
	v_mov_b32_e32 v94, v82
	v_mov_b32_e32 v95, v82
	v_mov_b32_e32 v96, v82
	v_mov_b32_e32 v97, v82
	v_mov_b32_e32 v98, v82
	v_mov_b32_e32 v99, v82
	v_mov_b32_e32 v100, v82
	v_mov_b32_e32 v101, v82
	v_mov_b32_e32 v102, v82
	v_mov_b32_e32 v103, v82
	s_mov_b32 s18, 0
	v_mov_b32_e32 v132, 0
	v_mov_b32_e32 v115, 0
	v_mov_b64_e32 v[60:61], v[28:29]
	v_mov_b64_e32 v[58:59], v[26:27]
	v_mov_b64_e32 v[56:57], v[24:25]
	v_mov_b64_e32 v[54:55], v[22:23]
	v_mov_b64_e32 v[52:53], v[20:21]
	v_mov_b64_e32 v[50:51], v[18:19]
	v_mov_b64_e32 v[48:49], v[16:17]
	v_mov_b64_e32 v[46:47], v[14:15]
	v_mov_b64_e32 v[44:45], v[12:13]
	v_mov_b64_e32 v[42:43], v[10:11]
	v_mov_b64_e32 v[40:41], v[8:9]
	v_mov_b64_e32 v[38:39], v[6:7]
	v_mov_b64_e32 v[36:37], v[4:5]
	v_mov_b64_e32 v[34:35], v[2:3]
	v_mov_b64_e32 v[32:33], v[0:1]
	s_mov_b32 s20, s14
	s_mov_b32 s19, 0
	v_mov_b32_e32 v2, 0
	v_mov_b32_e32 v3, v108
	v_mov_b32_e32 v4, v108
	v_mov_b32_e32 v5, v108
	v_mov_b32_e32 v6, v108
	v_mov_b32_e32 v7, v108
	v_mov_b32_e32 v8, v108
	v_mov_b32_e32 v9, v108
	v_mov_b32_e32 v10, v108
	v_mov_b32_e32 v11, v108
	v_mov_b32_e32 v12, v108
	v_mov_b32_e32 v13, v108
	v_mov_b32_e32 v14, v108
	v_mov_b32_e32 v15, v108
	v_mov_b32_e32 v16, v108
	v_mov_b32_e32 v17, v108
	v_mov_b32_e32 v64, v108
	v_mov_b32_e32 v65, v108
	v_mov_b32_e32 v66, v108
	v_mov_b32_e32 v67, v108
	v_mov_b32_e32 v68, v108
	v_mov_b32_e32 v69, v108
	v_mov_b32_e32 v70, v108
	v_mov_b32_e32 v71, v108
	v_mov_b32_e32 v72, v108
	v_mov_b32_e32 v73, v108
	v_mov_b32_e32 v74, v108
	v_mov_b32_e32 v75, v108
	v_mov_b32_e32 v76, v108
	v_mov_b32_e32 v77, v108
	v_mov_b32_e32 v78, v108
	v_mov_b32_e32 v79, v108
	.p2align	6

; DI float fexp2(float x) { return __builtin_amdgcn_exp2f(x); }
; #define WAIT_VM(n) asm volatile("s_waitcnt vmcnt(%0)" ::"n"(n) : "memory")
; #define RAW_BARRIER() do { asm volatile("s_waitcnt lgkmcnt(0)" ::: "memory"); __builtin_amdgcn_s_barrier(); } while (0)
; DI void nsa_attn_phase(const Params& p, char* smem) {
;     ...
;       for (int t = tc_lo; t < ncmp_tiles; ++t) {
;         if (t + 1 < ncmp_tiles) WAIT_VM(2); else WAIT_VM(0);
;         RAW_BARRIER();
;         if (t + 2 < ncmp_tiles) kv_issue<64, false>(smem, (t - tc_lo + 2) % 3, kc, 64, nullptr, 0, t + 2, lane, wid);
;         f32x16 st[2];
; #pragma unroll
;         for (int kb = 0; kb < 2; ++kb)
; #pragma unroll
;           for (int i = 0; i < 16; ++i) st[kb][i] = 0.f;
;         qk_acc(st, qf, smem + ((t - tc_lo) % 3) * Ring<64>::STAGE, foff);
;         const float base = (float)(tq - 31 - 16 * (t * 64 + 4 * h));
; #pragma unroll
;         for (int kb = 0; kb < 2; ++kb)
; #pragma unroll
;           for (int g4 = 0; g4 < 4; ++g4) {
;             float pr[4];
; #pragma unroll
;             for (int x = 0; x < 4; ++x) {
;               const float dist = base - 16.f * (float)(kb * 32 + 8 * g4 + x);
;               const float s = st[kb][4 * g4 + x] - slope2 * dist;
;               pr[x] = (dist >= 0.f) ? fexp2(s - m) * rl : 0.f;
;             }
;             const int j = t * 16 + kb * 8 + 2 * g4 + h;
;             atomicAdd(&imp[r * 128 + j], pr[0] + pr[1] + pr[2] + 0.5f * pr[3]);
;             if (j + 1 < 128) atomicAdd(&imp[r * 128 + j + 1], 0.5f * pr[3]);
;           }
;       }
.LBB0_844:
	s_or_b64 exec, exec, s[0:1]
	s_add_i32 s5, s5, 1
	s_addk_i32 s7, 0x4000
	s_add_i32 s6, s6, 1
	s_add_i32 s4, s4, 1
	v_add_u32_e32 v0, 0xfffffc00, v0
	v_add_u32_e32 v31, 64, v31
	v_add_u32_e32 v80, 16, v80
	s_cmp_ge_u32 s8, s14
	v_add_u32_e32 v22, 64, v22
	s_cbranch_scc1 .LBB0_867
	.p2align	6

; #define TOPK_STEP(CTRL) { const float ov = __uint_as_float(__builtin_amdgcn_update_dpp(0u, __float_as_uint(bv), CTRL, 0xf, 0xf, false)); \
;           const int oj = (int)__builtin_amdgcn_update_dpp(0u, (unsigned)bj, CTRL, 0xf, 0xf, false); \
;           if (ov > bv || (ov == bv && oj < bj)) { bv = ov; bj = oj; } }
; DI void nsa_attn_phase(const Params& p, char* smem) {
;     ...
; #pragma unroll 1
;       for (int rd = 0; rd < 13; ++rd) {
;         float bv = v[0];
; #pragma unroll
;         for (int e = 1; e < 16; ++e) bv = fmaxf(bv, v[e]);
;         int bj = 1 << 20;
; #pragma unroll
;         for (int e = 15; e >= 0; --e) bj = (v[e] == bv) ? (part * 16 + e) : bj;
;     ...
;         TOPK_STEP(0xB1)
;         TOPK_STEP(0x4E)
;         TOPK_STEP(0x141)
;     ...
;         if (bv >= 0.f && (bj >> 4) == part) {
; #pragma unroll
;           for (int e = 0; e < 16; ++e) if (e == (bj & 15)) { v[e] = -1.f; mine |= 1u << e; }
;         }
;       }
.LBB0_900:
	s_or_b64 exec, exec, s[0:1]
	s_add_i32 s8, s8, -1
	s_cmp_eq_u32 s8, 0
	s_cbranch_scc1 .LBB0_915
	.p2align	6

; DI int prev_active(int t, int tlo, const unsigned* um) {
;   if (um) { while (t >= tlo && !((um[t >> 5] >> (t & 31)) & 1u)) --t; }
;   return t;
; }
.LBB0_919:
	s_andn2_b64 vcc, exec, s[0:1]
	s_cbranch_vccz .LBB0_922
	.p2align	6

; DI int prev_active(int t, int tlo, const unsigned* um) {
;   if (um) { while (t >= tlo && !((um[t >> 5] >> (t & 31)) & 1u)) --t; }
;   return t;
; }
.LBB0_930:
	v_sub_co_u32_e64 v0, s[0:1], s16, 1
	s_nop 0
	v_readfirstlane_b32 s18, v0
	s_and_b64 vcc, exec, s[0:1]
	s_mov_b32 s6, s16
	s_cbranch_vccz .LBB0_938
	.p2align	6

; DI int ltid() { int x = threadIdx.x; asm volatile("" : "+v"(x)); return x; }
; #define RAW_BARRIER() do { asm volatile("s_waitcnt lgkmcnt(0)" ::: "memory"); __builtin_amdgcn_s_barrier(); } while (0)
; template <int DV, bool SEL, bool TERM> ...
;   constexpr int G = Ring<DV>::G;
;   const int tid = ltid(), lane = tid & 63, wid = tid >> 6, r = lane & 31, h = lane >> 5;
;   unsigned* flags = (unsigned*)(smem + SM_FLAG);
;   int foff[4];
;   make_foff(foff, r, h);
;   unsigned done = 0u;
;   const float sk = slope2 * (float)kp_mul;
;   RAW_BARRIER();
;   int t = prev_active(thi - 1, tlo, um);
;   int t1 = (t >= tlo) ? prev_active(t - 1, tlo, um) : t;
;   if (t >= tlo) kv_issue<DV, true>(smem, 0, kbase, kpitch, vbase, vpitch, t, lane, wid);
;   if (t1 >= tlo) kv_issue<DV, true>(smem, 1, kbase, kpitch, vbase, vpitch, t1, lane, wid);
;   int c = 0;
; DI void nsa_attn_phase(const Params& p, char* smem) {
;     ...
;       m = 0.f; l = 0.f;
; #pragma unroll
;       for (int dc = 0; dc < 2; ++dc)
; #pragma unroll
;         for (int i = 0; i < 16; ++i) ot[dc][i] = 0.f;
;       const u16* kb_ = p.qkvz + (long)b * SEQ * LD + 1536 + hk * 64;
;       const u16* vb_ = p.qkvz + (long)b * SEQ * LD + 1792 + hk * 64;
;       flash_pass<64, true, true>(smem, kb_, LD, vb_, LD, 0, (tmax >> 6) + 1, um, qf, tq, 1, BIGW, slope2, t0, tmax, selm + r * 4, qb_s, ot, m, l);
.LBB0_964:
	s_andn2_b64 vcc, exec, s[0:1]
	s_cbranch_vccnz .LBB0_800
	v_lshlrev_b32_e32 v0, 7, v2
	v_lshrrev_b32_e32 v5, 5, v3
	v_and_b32_e32 v6, 0xf80, v0
	v_lshrrev_b32_e32 v0, 1, v2
	v_bitop3_b32 v8, v5, v0, 7 bitop3:0x78
	v_lshrrev_b32_e32 v0, 4, v3
	v_lshlrev_b32_e32 v195, 4, v4
	v_xor_b32_e32 v0, v0, v3
	v_lshrrev_b32_e32 v194, 3, v3
	v_lshlrev_b32_e32 v0, 4, v0
	v_or_b32_e32 v197, 8, v195
	v_and_b32_e32 v0, 0x70, v0
	v_or_b32_e32 v198, v197, v194
	v_lshl_add_u64 v[144:145], s[8:9], 0, v[0:1]
	v_lshrrev_b32_e32 v0, 1, v198
	v_xor_b32_e32 v0, v0, v2
	v_lshlrev_b32_e32 v0, 4, v0
	v_and_b32_e32 v0, 0x70, v0
	v_lshl_add_u64 v[146:147], s[8:9], 0, v[0:1]
	v_and_b32_e32 v0, 7, v2
	v_lshrrev_b32_e32 v11, 2, v2
	v_bitop3_b32 v0, v11, v0, 4 bitop3:0x6c
	v_lshlrev_b32_e32 v0, 4, v0
	v_lshl_add_u64 v[148:149], s[6:7], 0, v[0:1]
	v_bfe_u32 v0, v2, 2, 2
	v_lshrrev_b32_e32 v11, 3, v2
	v_cmp_eq_u32_e64 s[4:5], 0, v3
	v_and_or_b32 v0, v11, 4, v0
	v_lshlrev_b32_e32 v11, 1, v3
	v_lshlrev_b32_e32 v3, 3, v3
	v_bfe_u32 v7, v2, 1, 3
	v_lshlrev_b32_e32 v0, 7, v0
	v_and_b32_e32 v11, 32, v11
	v_and_b32_e32 v3, 24, v3
	v_lshl_add_u32 v192, v4, 2, v213
	v_bitop3_b32 v9, v5, v7, 2 bitop3:0x36
	v_bitop3_b32 v10, v5, v7, 4 bitop3:0x36
	v_bitop3_b32 v7, v5, v7, 6 bitop3:0x36
	s_mov_b32 s0, 0x3f828f5c
	v_lshlrev_b32_e32 v4, 11, v4
	v_or3_b32 v199, v3, v11, v0
	v_lshlrev_b32_e32 v0, 3, v2
	v_mov_b32_e32 v30, v1
	v_mov_b32_e32 v31, v1
	v_fma_f32 v193, v230, s0, 1.0
	v_and_b32_e32 v200, 64, v0
	v_bitop3_b32 v201, v0, 64, v0 bitop3:0xc
	v_lshlrev_b32_e32 v202, 2, v5
	v_add_u32_e32 v203, 0xa400, v4
	v_add_u32_e32 v204, 0x8400, v4
	v_add_u32_e32 v205, 0xa000, v4
	v_add_u32_e32 v230, 0x8000, v4
	v_lshl_or_b32 v234, v7, 4, v6
	v_lshl_or_b32 v235, v8, 4, v6
	v_lshl_or_b32 v236, v10, 4, v6
	v_lshl_or_b32 v237, v9, 4, v6
	v_mov_b32_e32 v0, v1
	v_mov_b32_e32 v2, v1
	v_mov_b32_e32 v3, v1
	v_mov_b32_e32 v4, v1
	v_mov_b32_e32 v5, v1
	v_mov_b32_e32 v6, v1
	v_mov_b32_e32 v7, v1
	v_mov_b32_e32 v8, v1
	v_mov_b32_e32 v9, v1
	v_mov_b32_e32 v10, v1
	v_mov_b32_e32 v11, v1
	v_mov_b32_e32 v12, v1
	v_mov_b32_e32 v13, v1
	v_mov_b32_e32 v14, v1
	v_mov_b32_e32 v15, v1
	v_mov_b32_e32 v16, v1
	v_mov_b32_e32 v17, v1
	v_mov_b32_e32 v18, v1
	v_mov_b32_e32 v19, v1
	v_mov_b32_e32 v20, v1
	v_mov_b32_e32 v21, v1
	v_mov_b32_e32 v22, v1
	v_mov_b32_e32 v23, v1
	v_mov_b32_e32 v24, v1
	v_mov_b32_e32 v25, v1
	v_mov_b32_e32 v26, v1
	v_mov_b32_e32 v27, v1
	v_mov_b32_e32 v28, v1
	v_mov_b32_e32 v29, v1
	v_mov_b32_e32 v238, 0
	v_mov_b64_e32 v[126:127], v[30:31]
	s_mov_b32 s16, 2
	s_mov_b32 s17, 0
	v_or_b32_e32 v196, v195, v194
	v_mov_b32_e32 v183, v182
	v_mov_b32_e32 v150, v182
	v_mov_b32_e32 v151, v182
	v_mov_b32_e32 v152, v182
	v_mov_b32_e32 v153, v182
	v_mov_b32_e32 v154, v182
	v_mov_b32_e32 v155, v182
	v_mov_b32_e32 v156, v182
	v_mov_b32_e32 v157, v182
	v_mov_b32_e32 v158, v182
	v_mov_b32_e32 v159, v182
	v_mov_b32_e32 v184, v182
	v_mov_b32_e32 v185, v182
	v_mov_b32_e32 v186, v182
	v_mov_b32_e32 v187, v182
	v_mov_b32_e32 v188, v182
	v_mov_b32_e32 v189, v182
	v_mov_b32_e32 v239, 0
	s_mov_b32 s18, 0
	v_mov_b32_e32 v191, 0
	v_mov_b64_e32 v[124:125], v[28:29]
	v_mov_b64_e32 v[122:123], v[26:27]
	v_mov_b64_e32 v[120:121], v[24:25]
	v_mov_b64_e32 v[118:119], v[22:23]
	v_mov_b64_e32 v[116:117], v[20:21]
	v_mov_b64_e32 v[114:115], v[18:19]
	v_mov_b64_e32 v[112:113], v[16:17]
	v_mov_b64_e32 v[110:111], v[14:15]
	v_mov_b64_e32 v[108:109], v[12:13]
	v_mov_b64_e32 v[106:107], v[10:11]
	v_mov_b64_e32 v[104:105], v[8:9]
	v_mov_b64_e32 v[102:103], v[6:7]
	v_mov_b64_e32 v[100:101], v[4:5]
	v_mov_b64_e32 v[98:99], v[2:3]
	v_mov_b64_e32 v[96:97], v[0:1]
	s_mov_b32 s19, 0
	v_mov_b32_e32 v2, 0
	v_mov_b32_e32 v3, v238
	v_mov_b32_e32 v4, v238
	v_mov_b32_e32 v5, v238
	v_mov_b32_e32 v6, v238
	v_mov_b32_e32 v7, v238
	v_mov_b32_e32 v8, v238
	v_mov_b32_e32 v9, v238
	v_mov_b32_e32 v10, v238
	v_mov_b32_e32 v11, v238
	v_mov_b32_e32 v12, v238
	v_mov_b32_e32 v13, v238
	v_mov_b32_e32 v14, v238
	v_mov_b32_e32 v15, v238
	v_mov_b32_e32 v16, v238
	v_mov_b32_e32 v17, v238
	v_mov_b32_e32 v128, v238
	v_mov_b32_e32 v129, v238
	v_mov_b32_e32 v130, v238
	v_mov_b32_e32 v131, v238
	v_mov_b32_e32 v132, v238
	v_mov_b32_e32 v133, v238
	v_mov_b32_e32 v134, v238
	v_mov_b32_e32 v135, v238
	v_mov_b32_e32 v136, v238
	v_mov_b32_e32 v137, v238
	v_mov_b32_e32 v138, v238
	v_mov_b32_e32 v139, v238
	v_mov_b32_e32 v140, v238
	v_mov_b32_e32 v141, v238
	v_mov_b32_e32 v142, v238
	v_mov_b32_e32 v143, v238
	.p2align	6

; DI int ltid() { int x = threadIdx.x; asm volatile("" : "+v"(x)); return x; }
; DI int lbid() { int x = blockIdx.x; asm volatile("" : "+s"(x)); return x; }
; template <class ARow, class Epi>
; DI void gemm_tile(const ARow& arow, long a_kstride, const u16* __restrict__ Bt, long ldb, int K, int m0, int n0,
;                   const Epi& epi, char* smem) {
;   const int tid = ltid(), lane = tid & 63, wid = tid >> 6;
;   const int r = lane & 31, h = lane >> 5;
;   const int wn = wid & 1, wm = wid >> 1;
;   const u16* ap[4]; const u16* bp[4];
;   {
;     const int lr = lane >> 3;
; #pragma unroll
;     for (int j = 0; j < 4; ++j) {
;       const int row = (wid * 4 + j) * 8 + lr;
;       const int cc = (lane & 7) ^ ((row >> 1) & 7);
;       ap[j] = arow(m0 + row) + cc * 8;
;       bp[j] = Bt + (long)(n0 + row) * ldb + cc * 8;
;     }
;   }
; template <class Epi>
; DI void gemm_phase_plain(const u16* A, long lda, const u16* Bt, long ldb, int M, int N, int K, const Epi& epi, char* smem) {
;     ...
;   for (int t = lbid(); t < nwg; t += gridDim.x) {
;     const int xcd = t & 7, off = t >> 3;
;     const int wg = (xcd < rr ? xcd * (q + 1) : rr * (q + 1) + (xcd - rr) * q) + off;
;     const int nig = 8 * MT, gid = wg / nig, fm = gid * 8, gsz = (NT - fm) < 8 ? (NT - fm) : 8;
;     const int nt = fm + (wg % nig) % gsz, mt = (wg % nig) / gsz;
;     gemm_tile(ar, 64, Bt, ldb, K, mt * 128, nt * 128, epi, smem);
.LBB0_1044:
	s_lshl_b32 s16, s0, 7
	s_ashr_i32 s1, s0, 3
	s_and_b32 s16, s16, 0x380
	s_add_i32 s1, s16, s1
	s_ashr_i32 s16, s1, 31
	s_lshr_b32 s16, s16, 22
	s_add_i32 s16, s1, s16
	s_and_b32 s16, s16, 0xfffffc00
	s_sub_i32 s1, s1, s16
	s_sext_i32_i16 s17, s1
	s_bfe_u32 s17, s17, 0x3001c
	s_add_i32 s17, s1, s17
	s_sext_i32_i16 s18, s17
	s_and_b32 s17, s17, 0xfff8
	v_mov_b32_e32 v82, v222
	s_sub_i32 s1, s1, s17
	s_sext_i32_i16 s17, s1
	v_ashrrev_i32_e32 v16, 6, v82
	s_lshl_b32 s1, s18, 4
	v_bfe_u32 v17, v82, 3, 3
	v_lshlrev_b32_e32 v18, 5, v16
	s_and_b32 s1, s1, 0xffffff80
	v_or_b32_e32 v12, v18, v17
	s_lshl_b32 s18, s17, 7
	v_bfe_u32 v83, v82, 4, 2
	v_add_u32_e32 v0, s1, v12
	s_add_i32 s18, s18, s16
	v_xor_b32_e32 v2, v83, v82
	v_ashrrev_i32_e32 v1, 31, v0
	v_or_b32_e32 v8, 8, v12
	v_lshlrev_b64 v[0:1], 11, v[0:1]
	v_lshlrev_b32_e32 v2, 4, v2
	v_lshrrev_b32_e32 v19, 1, v8
	v_add_u32_e32 v4, s1, v8
	v_add_u32_e32 v8, s18, v8
	v_lshlrev_b32_e32 v88, 12, v16
	v_lshl_add_u64 v[0:1], s[4:5], 0, v[0:1]
	v_and_b32_e32 v64, 0x70, v2
	v_add_u32_e32 v2, s18, v12
	v_xor_b32_e32 v6, v19, v82
	v_ashrrev_i32_e32 v5, 31, v4
	v_ashrrev_i32_e32 v9, 31, v8
	v_readfirstlane_b32 s16, v88
	v_lshl_add_u64 v[0:1], v[0:1], 0, v[64:65]
	v_ashrrev_i32_e32 v3, 31, v2
	v_lshlrev_b64 v[4:5], 11, v[4:5]
	v_lshlrev_b32_e32 v6, 4, v6
	v_lshlrev_b64 v[8:9], 11, v[8:9]
	s_mov_b32 m0, s16
	v_lshlrev_b64 v[2:3], 11, v[2:3]
	v_lshl_add_u64 v[4:5], s[4:5], 0, v[4:5]
	v_and_b32_e32 v6, 0x70, v6
	v_mov_b32_e32 v7, v65
	v_lshl_add_u64 v[8:9], s[8:9], 0, v[8:9]
	v_or_b32_e32 v10, 16, v12
	global_load_lds_dwordx4 v[0:1], off
	v_add_u32_e32 v0, 0x4000, v88
	v_lshl_add_u64 v[2:3], s[8:9], 0, v[2:3]
	v_lshl_add_u64 v[4:5], v[4:5], 0, v[6:7]
	v_lshl_add_u64 v[6:7], v[8:9], 0, v[6:7]
	v_add_u32_e32 v8, s1, v10
	v_add_u32_e32 v10, s18, v10
	v_or_b32_e32 v14, 24, v12
	v_readfirstlane_b32 s16, v0
	v_or_b32_e32 v0, 0x400, v88
	v_lshl_add_u64 v[2:3], v[2:3], 0, v[64:65]
	v_ashrrev_i32_e32 v9, 31, v8
	v_ashrrev_i32_e32 v11, 31, v10
	v_lshrrev_b32_e32 v20, 1, v14
	s_mov_b32 m0, s16
	v_readfirstlane_b32 s16, v0
	v_add_u32_e32 v0, 0x4400, v88
	v_lshlrev_b64 v[8:9], 11, v[8:9]
	v_lshlrev_b64 v[10:11], 11, v[10:11]
	v_xor_b32_e32 v15, v20, v82
	v_add_u32_e32 v12, s1, v14
	global_load_lds_dwordx4 v[2:3], off
	s_mov_b32 m0, s16
	v_readfirstlane_b32 s16, v0
	v_or_b32_e32 v0, 0x800, v88
	v_lshl_add_u64 v[8:9], s[4:5], 0, v[8:9]
	v_lshl_add_u64 v[10:11], s[8:9], 0, v[10:11]
	v_ashrrev_i32_e32 v13, 31, v12
	v_lshlrev_b32_e32 v15, 4, v15
	v_add_u32_e32 v14, s18, v14
	global_load_lds_dwordx4 v[4:5], off
	s_mov_b32 m0, s16
	v_readfirstlane_b32 s16, v0
	v_add_u32_e32 v0, 0x4800, v88
	v_lshl_add_u64 v[8:9], v[8:9], 0, v[64:65]
	v_lshl_add_u64 v[10:11], v[10:11], 0, v[64:65]
	v_lshlrev_b64 v[12:13], 11, v[12:13]
	v_and_b32_e32 v64, 0x70, v15
	v_ashrrev_i32_e32 v15, 31, v14
	global_load_lds_dwordx4 v[6:7], off
	s_mov_b32 m0, s16
	v_readfirstlane_b32 s16, v0
	v_or_b32_e32 v0, 0xc00, v88
	v_lshl_add_u64 v[12:13], s[4:5], 0, v[12:13]
	v_lshlrev_b64 v[14:15], 11, v[14:15]
	global_load_lds_dwordx4 v[8:9], off
	s_mov_b32 m0, s16
	v_readfirstlane_b32 s16, v0
	v_add_u32_e32 v0, 0x4c00, v88
	v_lshl_add_u64 v[12:13], v[12:13], 0, v[64:65]
	v_lshl_add_u64 v[14:15], s[8:9], 0, v[14:15]
	global_load_lds_dwordx4 v[10:11], off
	s_mov_b32 m0, s16
	v_readfirstlane_b32 s16, v0
	v_lshl_add_u64 v[14:15], v[14:15], 0, v[64:65]
	global_load_lds_dwordx4 v[12:13], off
	s_mov_b32 m0, s16
	v_or_b32_e32 v0, s1, v17
	global_load_lds_dwordx4 v[14:15], off
	v_add_u32_e32 v0, v0, v18
	v_ashrrev_i32_e32 v1, 31, v0
	v_bitop3_b32 v2, v83, 7, v82 bitop3:0x48
	v_lshlrev_b64 v[0:1], 11, v[0:1]
	v_lshlrev_b32_e32 v2, 4, v2
	v_or_b32_e32 v0, v0, v2
	v_lshl_add_u64 v[66:67], s[12:13], 0, v[0:1]
	v_or_b32_e32 v0, s18, v17
	v_add_u32_e32 v0, v0, v18
	v_ashrrev_i32_e32 v1, 31, v0
	v_lshlrev_b64 v[0:1], 11, v[0:1]
	v_or_b32_e32 v0, v0, v2
	v_or_b32_e32 v3, 8, v17
	v_lshl_add_u64 v[68:69], s[14:15], 0, v[0:1]
	v_or_b32_e32 v0, s1, v3
	v_add_u32_e32 v0, v0, v18
	v_ashrrev_i32_e32 v1, 31, v0
	v_bitop3_b32 v4, v19, 7, v82 bitop3:0x48
	v_lshlrev_b64 v[0:1], 11, v[0:1]
	v_lshlrev_b32_e32 v4, 4, v4
	v_or_b32_e32 v0, v0, v4
	v_lshl_add_u64 v[70:71], s[12:13], 0, v[0:1]
	v_or_b32_e32 v0, s18, v3
	v_add_u32_e32 v0, v0, v18
	v_ashrrev_i32_e32 v1, 31, v0
	v_lshlrev_b64 v[0:1], 11, v[0:1]
	v_or_b32_e32 v0, v0, v4
	v_or_b32_e32 v3, 16, v17
	v_lshl_add_u64 v[72:73], s[14:15], 0, v[0:1]
	v_or_b32_e32 v0, s1, v3
	v_add_u32_e32 v0, v0, v18
	v_ashrrev_i32_e32 v1, 31, v0
	v_lshlrev_b64 v[0:1], 11, v[0:1]
	v_or_b32_e32 v0, v0, v2
	v_lshl_add_u64 v[74:75], s[12:13], 0, v[0:1]
	v_or_b32_e32 v0, s18, v3
	v_add_u32_e32 v0, v0, v18
	v_ashrrev_i32_e32 v1, 31, v0
	v_lshlrev_b64 v[0:1], 11, v[0:1]
	v_or_b32_e32 v0, v0, v2
	v_or_b32_e32 v2, 24, v17
	v_lshl_add_u64 v[76:77], s[14:15], 0, v[0:1]
	v_or_b32_e32 v0, s1, v2
	v_add_u32_e32 v0, v0, v18
	v_ashrrev_i32_e32 v1, 31, v0
	v_bitop3_b32 v3, v20, 7, v82 bitop3:0x48
	v_lshlrev_b64 v[0:1], 11, v[0:1]
	v_lshlrev_b32_e32 v3, 4, v3
	v_or_b32_e32 v0, v0, v3
	v_lshl_add_u64 v[78:79], s[12:13], 0, v[0:1]
	v_or_b32_e32 v0, s18, v2
	v_add_u32_e32 v0, v0, v18
	v_and_b32_e32 v64, 15, v82
	v_lshrrev_b32_e32 v22, 1, v82
	v_ashrrev_i32_e32 v1, 31, v0
	v_lshlrev_b32_e32 v21, 7, v64
	v_bfe_u32 v23, v82, 1, 3
	v_bitop3_b32 v22, v83, v22, 7 bitop3:0x78
	s_waitcnt vmcnt(0)
; template <class ARow, class Epi>
; DI void gemm_tile(const ARow& arow, long a_kstride, const u16* __restrict__ Bt, long ldb, int K, int m0, int n0,
;                   const Epi& epi, char* smem) {
;     ...
;   const int fr = lane & 15, fq = lane >> 4;
;   int foff[2];
; #pragma unroll
;   for (int ks = 0; ks < 2; ++ks) foff[ks] = fr * 128 + ((((4 * ks + fq) ^ ((fr >> 1) & 7))) << 4);
;   f32x4 acc[4][4];
; #pragma unroll
;   for (int a = 0; a < 4; ++a)
; #pragma unroll
;     for (int b = 0; b < 4; ++b) acc[a][b] = (f32x4){0.f, 0.f, 0.f, 0.f};
;   const int KT = K >> 6;
;   GEMM_STAGE(0, 0);
;   asm volatile("s_waitcnt vmcnt(0)" ::: "memory");
;   __syncthreads();
	v_lshlrev_b64 v[0:1], 11, v[0:1]
	v_and_b32_e32 v84, 1, v16
	v_lshl_or_b32 v87, v22, 4, v21
	v_bitop3_b32 v22, v83, v23, 4 bitop3:0x36
	v_ashrrev_i32_e32 v85, 7, v82
	v_or_b32_e32 v0, v0, v3
	v_lshl_or_b32 v86, v22, 4, v21
	v_lshlrev_b32_e32 v89, 13, v85
	v_lshlrev_b32_e32 v90, 13, v84
	v_lshl_add_u64 v[80:81], s[14:15], 0, v[0:1]
	s_mov_b64 s[16:17], 0
	s_mov_b32 s19, 0
	v_mov_b32_e32 v20, 0
	v_mov_b32_e32 v21, v65
	v_mov_b32_e32 v22, v65
	v_mov_b32_e32 v23, v65
	v_mov_b32_e32 v28, 0
	v_mov_b32_e32 v29, v65
	v_mov_b32_e32 v30, v65
	v_mov_b32_e32 v31, v65
	v_mov_b32_e32 v0, 0
	v_mov_b32_e32 v1, v65
	v_mov_b32_e32 v2, v65
	v_mov_b32_e32 v3, v65
	v_mov_b32_e32 v24, 0
	v_mov_b32_e32 v25, v65
	v_mov_b32_e32 v26, v65
	v_mov_b32_e32 v27, v65
	v_mov_b32_e32 v4, 0
	v_mov_b32_e32 v5, v65
	v_mov_b32_e32 v6, v65
	v_mov_b32_e32 v7, v65
	v_mov_b32_e32 v8, 0
	v_mov_b32_e32 v9, v65
	v_mov_b32_e32 v10, v65
	v_mov_b32_e32 v11, v65
	v_mov_b32_e32 v12, 0
	v_mov_b32_e32 v13, v65
	v_mov_b32_e32 v14, v65
	v_mov_b32_e32 v15, v65
	v_mov_b32_e32 v32, 0
	v_mov_b32_e32 v33, v65
	v_mov_b32_e32 v34, v65
	v_mov_b32_e32 v35, v65
	v_mov_b32_e32 v16, 0
	v_mov_b32_e32 v17, v65
	v_mov_b32_e32 v18, v65
	v_mov_b32_e32 v19, v65
	v_mov_b32_e32 v36, 0
	v_mov_b32_e32 v37, v65
	v_mov_b32_e32 v38, v65
	v_mov_b32_e32 v39, v65
	v_mov_b32_e32 v40, 0
	v_mov_b32_e32 v41, v65
	v_mov_b32_e32 v42, v65
	v_mov_b32_e32 v43, v65
	v_mov_b32_e32 v44, 0
	v_mov_b32_e32 v45, v65
	v_mov_b32_e32 v46, v65
	v_mov_b32_e32 v47, v65
	v_mov_b32_e32 v48, 0
	v_mov_b32_e32 v49, v65
	v_mov_b32_e32 v50, v65
	v_mov_b32_e32 v51, v65
	v_mov_b32_e32 v52, 0
	v_mov_b32_e32 v53, v65
	v_mov_b32_e32 v54, v65
	v_mov_b32_e32 v55, v65
	v_mov_b32_e32 v56, 0
	v_mov_b32_e32 v57, v65
	v_mov_b32_e32 v58, v65
	v_mov_b32_e32 v59, v65
	v_mov_b32_e32 v60, 0
	v_mov_b32_e32 v61, v65
	v_mov_b32_e32 v62, v65
	v_mov_b32_e32 v63, v65
	s_waitcnt vmcnt(0) lgkmcnt(0)
	s_barrier
	.p2align	6

; template <bool HI_BF, bool HO_BF>
; DI void post_phase(const u16* __restrict__ y, const void* hin_, void* hout_,
;                    const float* __restrict__ gpost, const float* __restrict__ gpre, u16* __restrict__ uout) {
;     ...
;   for (int row = gw; row < T_TOK; row += nw) {
;     float4 hv[4];
; #pragma unroll
;     for (int j = 0; j < 4; ++j) {
;       if (HI_BF) {
;         const u32x2 hb = *(const u32x2*)((const u16*)hin_ + (long)row * 1024 + 4 * lane + 256 * j);
;         hv[j] = make_float4(bflo(hb.x), bfhi(hb.x), bflo(hb.y), bfhi(hb.y));
;       } else hv[j] = *(const float4*)(hin + (long)row * 1024 + 4 * lane + 256 * j);
;     }
;     if (y) {
;       float4 yv[4]; float ss = 0.f;
; #pragma unroll
;       for (int j = 0; j < 4; ++j) {
;         const u32x2 yb = *(const u32x2*)(y + (long)row * 1024 + 4 * lane + 256 * j);
;         yv[j] = make_float4(bflo(yb.x), bfhi(yb.x), bflo(yb.y), bfhi(yb.y));
;         ss += yv[j].x * yv[j].x + yv[j].y * yv[j].y + yv[j].z * yv[j].z + yv[j].w * yv[j].w;
;       }
; #pragma unroll
;       for (int o = 32; o > 0; o >>= 1) ss += __shfl_xor(ss, o);
;       const float ri = rsqrtf(ss * (1.f / 1024.f) + RMS_EPS);
; #pragma unroll
;       for (int j = 0; j < 4; ++j) {
;         const float4 g = *(const float4*)(gpost + 4 * lane + 256 * j);
;         hv[j].x += yv[j].x * ri * g.x; hv[j].y += yv[j].y * ri * g.y; hv[j].z += yv[j].z * ri * g.z; hv[j].w += yv[j].w * ri * g.w;
;       }
;     }
;     if (hout_) {
; #pragma unroll
;       for (int j = 0; j < 4; ++j) {
;         if (HO_BF) { u32x2 v; v.x = pack2(hv[j].x, hv[j].y); v.y = pack2(hv[j].z, hv[j].w); *(u32x2*)((u16*)hout_ + (long)row * 1024 + 4 * lane + 256 * j) = v; }
;         else *(float4*)(hout + (long)row * 1024 + 4 * lane + 256 * j) = hv[j];
;       }
;     }
;     if (uout) {
;       float ss = 0.f;
; #pragma unroll
;       for (int j = 0; j < 4; ++j) ss += hv[j].x * hv[j].x + hv[j].y * hv[j].y + hv[j].z * hv[j].z + hv[j].w * hv[j].w;
; #pragma unroll
;       for (int o = 32; o > 0; o >>= 1) ss += __shfl_xor(ss, o);
;       const float ri = rsqrtf(ss * (1.f / 1024.f) + RMS_EPS);
; #pragma unroll
;       for (int j = 0; j < 4; ++j) {
;         const float4 g = *(const float4*)(gpre + 4 * lane + 256 * j);
;         u32x2 v; v.x = pack2(hv[j].x * ri * g.x, hv[j].y * ri * g.y); v.y = pack2(hv[j].z * ri * g.z, hv[j].w * ri * g.w);
.LBB0_1104:
	v_add_u32_e32 v30, s24, v30
	v_cmp_lt_i32_e32 vcc, s1, v30
	v_lshl_add_u64 v[22:23], v[22:23], 0, s[28:29]
	v_lshl_add_u64 v[24:25], v[24:25], 0, s[30:31]
	v_lshl_add_u64 v[26:27], v[26:27], 0, s[30:31]
	s_or_b64 s[26:27], vcc, s[26:27]
	v_lshl_add_u64 v[28:29], v[28:29], 0, s[30:31]
	s_andn2_b64 exec, exec, s[26:27]
	s_cbranch_execz .LBB0_1111
	.p2align	6

; DI int ltid() { int x = threadIdx.x; asm volatile("" : "+v"(x)); return x; }
; DI int lbid() { int x = blockIdx.x; asm volatile("" : "+s"(x)); return x; }
; template <class ARow, class Epi>
; DI void gemm_tile(const ARow& arow, long a_kstride, const u16* __restrict__ Bt, long ldb, int K, int m0, int n0,
;                   const Epi& epi, char* smem) {
;   const int tid = ltid(), lane = tid & 63, wid = tid >> 6;
;   const int r = lane & 31, h = lane >> 5;
;   const int wn = wid & 1, wm = wid >> 1;
;   const u16* ap[4]; const u16* bp[4];
;   {
;     const int lr = lane >> 3;
; #pragma unroll
;     for (int j = 0; j < 4; ++j) {
;       const int row = (wid * 4 + j) * 8 + lr;
;       const int cc = (lane & 7) ^ ((row >> 1) & 7);
;       ap[j] = arow(m0 + row) + cc * 8;
;       bp[j] = Bt + (long)(n0 + row) * ldb + cc * 8;
;     }
;   }
; template <class Epi>
; DI void gemm_phase_plain(const u16* A, long lda, const u16* Bt, long ldb, int M, int N, int K, const Epi& epi, char* smem) {
;     ...
;   for (int t = lbid(); t < nwg; t += gridDim.x) {
;     const int xcd = t & 7, off = t >> 3;
;     const int wg = (xcd < rr ? xcd * (q + 1) : rr * (q + 1) + (xcd - rr) * q) + off;
;     const int nig = 8 * MT, gid = wg / nig, fm = gid * 8, gsz = (NT - fm) < 8 ? (NT - fm) : 8;
;     const int nt = fm + (wg % nig) % gsz, mt = (wg % nig) / gsz;
;     gemm_tile(ar, 64, Bt, ldb, K, mt * 128, nt * 128, epi, smem);
.LBB0_1172:
	s_lshl_b32 s1, s29, 9
	s_ashr_i32 s0, s29, 3
	s_and_b32 s1, s1, 0xe00
	s_add_i32 s0, s1, s0
	s_ashr_i32 s1, s0, 31
	s_lshr_b32 s1, s1, 22
	s_add_i32 s1, s0, s1
	s_and_b32 s1, s1, 0xfffffc00
	s_sub_i32 s0, s0, s1
	s_sext_i32_i16 s4, s0
	s_bfe_u32 s4, s4, 0x3001c
	s_add_i32 s4, s0, s4
	s_sext_i32_i16 s5, s4
	s_and_b32 s4, s4, 0xfff8
	v_mov_b32_e32 v83, v222
	s_sub_i32 s0, s0, s4
	s_sext_i32_i16 s4, s0
	v_ashrrev_i32_e32 v16, 6, v83
	s_lshl_b32 s0, s5, 4
	v_bfe_u32 v17, v83, 3, 3
	v_lshlrev_b32_e32 v18, 5, v16
	s_and_b32 s0, s0, 0xffffff80
	v_or_b32_e32 v12, v18, v17
	s_lshl_b32 s38, s4, 7
	v_bfe_u32 v84, v83, 4, 2
	v_add_u32_e32 v0, s0, v12
	s_add_i32 s38, s38, s1
	v_xor_b32_e32 v2, v84, v83
	v_ashrrev_i32_e32 v1, 31, v0
	v_or_b32_e32 v8, 8, v12
	v_lshlrev_b64 v[0:1], 11, v[0:1]
	v_lshlrev_b32_e32 v2, 4, v2
	v_lshrrev_b32_e32 v19, 1, v8
	v_add_u32_e32 v4, s0, v8
	v_add_u32_e32 v8, s38, v8
	v_lshlrev_b32_e32 v91, 12, v16
	v_lshl_add_u64 v[0:1], s[16:17], 0, v[0:1]
	v_and_b32_e32 v64, 0x70, v2
	v_add_u32_e32 v2, s38, v12
	v_xor_b32_e32 v6, v19, v83
	v_ashrrev_i32_e32 v5, 31, v4
	v_ashrrev_i32_e32 v9, 31, v8
	v_readfirstlane_b32 s1, v91
	v_lshl_add_u64 v[0:1], v[0:1], 0, v[64:65]
	v_ashrrev_i32_e32 v3, 31, v2
	v_lshlrev_b64 v[4:5], 11, v[4:5]
	v_lshlrev_b32_e32 v6, 4, v6
	v_lshlrev_b64 v[8:9], 11, v[8:9]
	s_mov_b32 m0, s1
	v_lshlrev_b64 v[2:3], 11, v[2:3]
	v_lshl_add_u64 v[4:5], s[16:17], 0, v[4:5]
	v_and_b32_e32 v6, 0x70, v6
	v_mov_b32_e32 v7, v65
	v_lshl_add_u64 v[8:9], s[20:21], 0, v[8:9]
	v_or_b32_e32 v10, 16, v12
	global_load_lds_dwordx4 v[0:1], off
	v_add_u32_e32 v0, 0x4000, v91
	v_lshl_add_u64 v[2:3], s[20:21], 0, v[2:3]
	v_lshl_add_u64 v[4:5], v[4:5], 0, v[6:7]
	v_lshl_add_u64 v[6:7], v[8:9], 0, v[6:7]
	v_add_u32_e32 v8, s0, v10
	v_add_u32_e32 v10, s38, v10
	v_or_b32_e32 v14, 24, v12
	v_readfirstlane_b32 s1, v0
	v_or_b32_e32 v0, 0x400, v91
	v_lshl_add_u64 v[2:3], v[2:3], 0, v[64:65]
	v_ashrrev_i32_e32 v9, 31, v8
	v_ashrrev_i32_e32 v11, 31, v10
	v_lshrrev_b32_e32 v20, 1, v14
	s_mov_b32 m0, s1
	v_readfirstlane_b32 s1, v0
	v_add_u32_e32 v0, 0x4400, v91
	v_lshlrev_b64 v[8:9], 11, v[8:9]
	v_lshlrev_b64 v[10:11], 11, v[10:11]
	v_xor_b32_e32 v15, v20, v83
	v_add_u32_e32 v12, s0, v14
	global_load_lds_dwordx4 v[2:3], off
	s_mov_b32 m0, s1
	v_readfirstlane_b32 s1, v0
	v_or_b32_e32 v0, 0x800, v91
	v_lshl_add_u64 v[8:9], s[16:17], 0, v[8:9]
	v_lshl_add_u64 v[10:11], s[20:21], 0, v[10:11]
	v_ashrrev_i32_e32 v13, 31, v12
	v_lshlrev_b32_e32 v15, 4, v15
	v_add_u32_e32 v14, s38, v14
	global_load_lds_dwordx4 v[4:5], off
	s_mov_b32 m0, s1
	v_readfirstlane_b32 s1, v0
	v_add_u32_e32 v0, 0x4800, v91
	v_lshl_add_u64 v[8:9], v[8:9], 0, v[64:65]
	v_lshl_add_u64 v[10:11], v[10:11], 0, v[64:65]
	v_lshlrev_b64 v[12:13], 11, v[12:13]
	v_and_b32_e32 v64, 0x70, v15
	v_ashrrev_i32_e32 v15, 31, v14
	global_load_lds_dwordx4 v[6:7], off
	s_mov_b32 m0, s1
	v_readfirstlane_b32 s1, v0
	v_or_b32_e32 v0, 0xc00, v91
	v_lshl_add_u64 v[12:13], s[16:17], 0, v[12:13]
	v_lshlrev_b64 v[14:15], 11, v[14:15]
	global_load_lds_dwordx4 v[8:9], off
	s_mov_b32 m0, s1
	v_readfirstlane_b32 s1, v0
	v_add_u32_e32 v0, 0x4c00, v91
	v_lshl_add_u64 v[12:13], v[12:13], 0, v[64:65]
	v_lshl_add_u64 v[14:15], s[20:21], 0, v[14:15]
	global_load_lds_dwordx4 v[10:11], off
	s_mov_b32 m0, s1
	v_readfirstlane_b32 s1, v0
	v_lshl_add_u64 v[14:15], v[14:15], 0, v[64:65]
	global_load_lds_dwordx4 v[12:13], off
	s_mov_b32 m0, s1
	v_or_b32_e32 v0, s0, v17
	global_load_lds_dwordx4 v[14:15], off
	v_add_u32_e32 v0, v0, v18
	v_ashrrev_i32_e32 v1, 31, v0
	v_bitop3_b32 v2, v84, 7, v83 bitop3:0x48
	v_lshlrev_b64 v[0:1], 11, v[0:1]
	v_lshlrev_b32_e32 v2, 4, v2
	v_or_b32_e32 v0, v0, v2
	v_lshl_add_u64 v[66:67], s[24:25], 0, v[0:1]
	v_or_b32_e32 v0, s38, v17
	v_add_u32_e32 v0, v0, v18
	v_ashrrev_i32_e32 v1, 31, v0
	v_lshlrev_b64 v[0:1], 11, v[0:1]
	v_or_b32_e32 v0, v0, v2
	v_or_b32_e32 v3, 8, v17
	v_lshl_add_u64 v[68:69], s[26:27], 0, v[0:1]
	v_or_b32_e32 v0, s0, v3
	v_add_u32_e32 v0, v0, v18
	v_ashrrev_i32_e32 v1, 31, v0
	v_bitop3_b32 v4, v19, 7, v83 bitop3:0x48
	v_lshlrev_b64 v[0:1], 11, v[0:1]
	v_lshlrev_b32_e32 v4, 4, v4
	v_or_b32_e32 v0, v0, v4
	v_lshl_add_u64 v[70:71], s[24:25], 0, v[0:1]
	v_or_b32_e32 v0, s38, v3
	v_add_u32_e32 v0, v0, v18
	v_ashrrev_i32_e32 v1, 31, v0
	v_lshlrev_b64 v[0:1], 11, v[0:1]
	v_or_b32_e32 v0, v0, v4
	v_or_b32_e32 v3, 16, v17
	v_lshl_add_u64 v[72:73], s[26:27], 0, v[0:1]
	v_or_b32_e32 v0, s0, v3
	v_add_u32_e32 v0, v0, v18
	v_ashrrev_i32_e32 v1, 31, v0
	v_lshlrev_b64 v[0:1], 11, v[0:1]
	v_or_b32_e32 v0, v0, v2
	v_lshl_add_u64 v[74:75], s[24:25], 0, v[0:1]
	v_or_b32_e32 v0, s38, v3
	v_add_u32_e32 v0, v0, v18
	v_ashrrev_i32_e32 v1, 31, v0
	v_lshlrev_b64 v[0:1], 11, v[0:1]
	v_or_b32_e32 v0, v0, v2
	v_or_b32_e32 v2, 24, v17
	v_lshl_add_u64 v[76:77], s[26:27], 0, v[0:1]
	v_or_b32_e32 v0, s0, v2
	v_add_u32_e32 v0, v0, v18
	v_ashrrev_i32_e32 v1, 31, v0
	v_bitop3_b32 v3, v20, 7, v83 bitop3:0x48
	v_lshlrev_b64 v[0:1], 11, v[0:1]
	v_lshlrev_b32_e32 v3, 4, v3
	v_or_b32_e32 v0, v0, v3
	v_lshl_add_u64 v[78:79], s[24:25], 0, v[0:1]
	v_or_b32_e32 v0, s38, v2
	v_add_u32_e32 v0, v0, v18
	v_and_b32_e32 v64, 15, v83
	v_lshrrev_b32_e32 v22, 1, v83
	v_ashrrev_i32_e32 v1, 31, v0
	v_lshlrev_b32_e32 v21, 7, v64
	v_bfe_u32 v23, v83, 1, 3
	v_bitop3_b32 v22, v84, v22, 7 bitop3:0x78
	s_waitcnt vmcnt(0)
; template <class ARow, class Epi>
; DI void gemm_tile(const ARow& arow, long a_kstride, const u16* __restrict__ Bt, long ldb, int K, int m0, int n0,
;                   const Epi& epi, char* smem) {
;     ...
;   const int fr = lane & 15, fq = lane >> 4;
;   int foff[2];
; #pragma unroll
;   for (int ks = 0; ks < 2; ++ks) foff[ks] = fr * 128 + ((((4 * ks + fq) ^ ((fr >> 1) & 7))) << 4);
;   f32x4 acc[4][4];
; #pragma unroll
;   for (int a = 0; a < 4; ++a)
; #pragma unroll
;     for (int b = 0; b < 4; ++b) acc[a][b] = (f32x4){0.f, 0.f, 0.f, 0.f};
;   const int KT = K >> 6;
;   GEMM_STAGE(0, 0);
;   asm volatile("s_waitcnt vmcnt(0)" ::: "memory");
;   __syncthreads();
	v_lshlrev_b64 v[0:1], 11, v[0:1]
	v_and_b32_e32 v85, 1, v16
	v_lshl_or_b32 v88, v22, 4, v21
	v_bitop3_b32 v22, v84, v23, 4 bitop3:0x36
	v_ashrrev_i32_e32 v86, 7, v83
	v_or_b32_e32 v0, v0, v3
	v_lshl_or_b32 v87, v22, 4, v21
	v_lshlrev_b32_e32 v89, 13, v86
	v_lshlrev_b32_e32 v90, 13, v85
	v_lshl_add_u64 v[80:81], s[26:27], 0, v[0:1]
	s_mov_b64 s[4:5], 0
	s_mov_b32 s1, 0
	v_mov_b32_e32 v44, 0
	v_mov_b32_e32 v45, v65
	v_mov_b32_e32 v46, v65
	v_mov_b32_e32 v47, v65
	v_mov_b32_e32 v52, 0
	v_mov_b32_e32 v53, v65
	v_mov_b32_e32 v54, v65
	v_mov_b32_e32 v55, v65
	v_mov_b32_e32 v0, 0
	v_mov_b32_e32 v1, v65
	v_mov_b32_e32 v2, v65
	v_mov_b32_e32 v3, v65
	v_mov_b32_e32 v4, 0
	v_mov_b32_e32 v5, v65
	v_mov_b32_e32 v6, v65
	v_mov_b32_e32 v7, v65
	v_mov_b32_e32 v8, 0
	v_mov_b32_e32 v9, v65
	v_mov_b32_e32 v10, v65
	v_mov_b32_e32 v11, v65
	v_mov_b32_e32 v12, 0
	v_mov_b32_e32 v13, v65
	v_mov_b32_e32 v14, v65
	v_mov_b32_e32 v15, v65
	v_mov_b32_e32 v16, 0
	v_mov_b32_e32 v17, v65
	v_mov_b32_e32 v18, v65
	v_mov_b32_e32 v19, v65
	v_mov_b32_e32 v20, 0
	v_mov_b32_e32 v21, v65
	v_mov_b32_e32 v22, v65
	v_mov_b32_e32 v23, v65
	v_mov_b32_e32 v24, 0
	v_mov_b32_e32 v25, v65
	v_mov_b32_e32 v26, v65
	v_mov_b32_e32 v27, v65
	v_mov_b32_e32 v28, 0
	v_mov_b32_e32 v29, v65
	v_mov_b32_e32 v30, v65
	v_mov_b32_e32 v31, v65
	v_mov_b32_e32 v32, 0
	v_mov_b32_e32 v33, v65
	v_mov_b32_e32 v34, v65
	v_mov_b32_e32 v35, v65
	v_mov_b32_e32 v36, 0
	v_mov_b32_e32 v37, v65
	v_mov_b32_e32 v38, v65
	v_mov_b32_e32 v39, v65
	v_mov_b32_e32 v40, 0
	v_mov_b32_e32 v41, v65
	v_mov_b32_e32 v42, v65
	v_mov_b32_e32 v43, v65
	v_mov_b32_e32 v48, 0
	v_mov_b32_e32 v49, v65
	v_mov_b32_e32 v50, v65
	v_mov_b32_e32 v51, v65
	v_mov_b32_e32 v56, 0
	v_mov_b32_e32 v57, v65
	v_mov_b32_e32 v58, v65
	v_mov_b32_e32 v59, v65
	v_mov_b32_e32 v60, 0
	v_mov_b32_e32 v61, v65
	v_mov_b32_e32 v62, v65
	v_mov_b32_e32 v63, v65
	s_waitcnt vmcnt(0) lgkmcnt(0)
	s_barrier
	.p2align	6

; DI int ltid() { int x = threadIdx.x; asm volatile("" : "+v"(x)); return x; }
; DI void diff_attn_phase(const Params& p, char* smem) {
;     ...
;     const int slot = fetch_task(p.ctr + 1, smem);
;     if (slot >= 2048) break;
;     const int tid = ltid(), lane = tid & 63, wid = tid >> 6, r = lane & 31, h = lane >> 5;
;     const int pair = slot >> 1, mm = (slot & 1) ? 0 : 1;
;     const int qt = 63 - (pair >> 4), bh = pair & 15;
;     const int b = bh >> 3, hd = bh & 7;
;     const int q0 = qt * 128 + wid * 32, tq = q0 + r;
;     const long tok = (long)b * SEQ + tq;
;     const float slope2 = exp2f(-(float)(hd + 1)) * LOG2E;
;     const int thi = ((qt * 128 + 127) >> 6) + 1;
;     const u16* vb_ = p.qkvz + (long)b * SEQ * LD + 2048 + hd * 128;
;     f32x16 ot[4];
;     float rl;
;     {
;       bf16x8 qf[4];
;       load_q(qf, p.qkvz + tok * LD + hd * 128 + mm * 64, h);
;       const u16* kb_ = p.qkvz + (long)b * SEQ * LD + 1024 + hd * 128 + mm * 64;
;       float m = 0.f, l = 0.f;
; #pragma unroll
;       for (int dc = 0; dc < 4; ++dc)
; #pragma unroll
;         for (int i = 0; i < 16; ++i) ot[dc][i] = 0.f;
;       const float qb = q_bound(qf, p.kmax2[128 + b * 64 + 16 + hd * 2 + mm]);
.LBB0_1479:
	s_or_b64 exec, exec, s[0:1]
	s_waitcnt lgkmcnt(0)
	s_barrier
	ds_read_b32 v0, v148
	s_mov_b32 s98, 1
	s_movk_i32 s0, 0x7ff
	s_waitcnt lgkmcnt(0)
	v_cmp_lt_i32_e32 vcc, s0, v0
	v_readfirstlane_b32 s2, v0
	s_mov_b64 s[0:1], -1
	s_cbranch_vccnz .LBB0_1474
	v_mov_b32_e32 v154, v222
	s_ashr_i32 s92, s2, 1
	s_lshl_b32 s0, s2, 2
	v_ashrrev_i32_e32 v0, 1, v154
	s_and_b32 s17, s92, 7
	s_and_b32 s4, s0, 0xffffff80
	v_and_b32_e32 v0, 0xffffffe0, v0
	v_subrev_u32_e32 v2, s4, v0
	s_add_i32 s0, s17, 1
	s_and_b32 s56, s2, 1
	s_bfe_u32 s16, s92, 0x10003
	v_add_u32_e32 v156, 0x1f80, v2
	v_cvt_f32_ubyte0_e32 v3, s0
	s_mov_b32 s0, 0x42fc0000
	s_xor_b32 s11, s56, 1
	v_and_or_b32 v134, v154, 31, v156
	s_lshl_b32 s2, s16, 13
	v_cmp_lt_f32_e32 vcc, s0, v3
	v_ashrrev_i32_e32 v135, 31, v134
	s_and_b64 s[0:1], vcc, exec
	v_lshl_add_u64 v[132:133], v[134:135], 0, s[2:3]
	s_cselect_b32 s1, 0xffffffc0, 0
	s_sub_i32 s0, 0x1fc0, s4
	s_lshl_b32 s2, s16, 26
	s_add_u32 s6, s62, s2
	v_lshlrev_b64 v[4:5], 13, v[132:133]
	s_addc_u32 s7, s63, 0
	v_lshl_add_u64 v[130:131], s[62:63], 0, v[4:5]
	s_lshl_b32 s2, s17, 8
	v_bfe_u32 v155, v154, 5, 1
	v_lshl_add_u64 v[4:5], v[130:131], 0, s[2:3]
	s_lshl_b32 s4, s11, 7
	s_mov_b32 s5, s3
	v_lshl_add_u64 v[4:5], v[4:5], 0, s[4:5]
	v_lshlrev_b32_e32 v0, 4, v155
	v_lshl_add_u64 v[4:5], v[4:5], 0, v[0:1]
	global_load_dwordx4 v[112:115], v[4:5], off
	global_load_dwordx4 v[116:119], v[4:5], off offset:32
	global_load_dwordx4 v[120:123], v[4:5], off offset:64
	global_load_dwordx4 v[124:127], v[4:5], off offset:96
	s_lshl_b32 s57, s17, 7
	s_add_u32 s8, s6, s2
	s_addc_u32 s9, s7, 0
	s_lshr_b32 s10, s0, 6
	s_add_u32 s6, s8, s4
	s_addc_u32 s7, s9, 0
	s_lshl_b32 s2, s16, 6
	s_lshl_b32 s4, s17, 1
	s_or_b32 s2, s2, s4
	s_or_b32 s2, s2, s11
	s_lshl_b32 s2, s2, 2
	v_readlane_b32 s16, v255, 14
	v_mov_b32_e32 v0, s2
	v_readlane_b32 s17, v255, 15
	v_cndmask_b32_e32 v6, 0, v152, vcc
	v_sub_f32_e32 v3, v6, v3
	s_mov_b32 s4, 0xf800000
	v_exp_f32_e32 v3, v3
	v_add_u32_e32 v157, 0x1f9f, v2
	global_load_dword v0, v0, s[16:17] offset:576
	s_add_i32 s24, s10, -1
	v_ldexp_f32 v3, v3, s1
	v_mul_f32_e32 v136, 0x3fb8aa3b, v3
	s_mov_b32 s1, 0x3f828f5c
	v_mov_b32_e32 v183, 0
	s_mov_b32 s2, 2
	s_mov_b32 s93, 0
	v_add_u32_e32 v171, 1, v134
	v_mov_b32_e32 v144, v136
	v_mov_b32_e32 v145, v136
	v_mov_b32_e32 v146, v136
	v_mov_b32_e32 v147, v136
	s_add_i32 s25, s10, 1
	s_mov_b32 s16, 0
	v_mov_b32_e32 v184, 0
	s_mov_b32 s17, 0
	v_mov_b32_e32 v80, 0
	v_mov_b32_e32 v81, v183
	v_mov_b32_e32 v82, v183
	v_mov_b32_e32 v83, v183
	v_mov_b32_e32 v84, v183
	v_mov_b32_e32 v85, v183
	v_mov_b32_e32 v86, v183
	v_mov_b32_e32 v87, v183
	v_mov_b32_e32 v88, v183
	v_mov_b32_e32 v89, v183
	v_mov_b32_e32 v90, v183
	v_mov_b32_e32 v91, v183
	v_mov_b32_e32 v92, v183
	v_mov_b32_e32 v93, v183
	v_mov_b32_e32 v94, v183
	v_mov_b32_e32 v95, v183
	v_mov_b32_e32 v96, v183
	v_mov_b32_e32 v97, v183
	v_mov_b32_e32 v98, v183
	v_mov_b32_e32 v99, v183
	v_mov_b32_e32 v100, v183
	v_mov_b32_e32 v101, v183
	v_mov_b32_e32 v102, v183
	v_mov_b32_e32 v103, v183
	v_mov_b32_e32 v104, v183
	v_mov_b32_e32 v105, v183
	v_mov_b32_e32 v106, v183
	v_mov_b32_e32 v107, v183
	v_mov_b32_e32 v108, v183
	v_mov_b32_e32 v109, v183
	v_mov_b32_e32 v110, v183
	v_mov_b32_e32 v111, v183
	v_readlane_b32 s18, v255, 16
	v_readlane_b32 s19, v255, 17
	s_waitcnt vmcnt(0)
	v_and_b32_e32 v5, 0xffff0000, v112
	v_lshlrev_b32_e32 v4, 16, v112
	v_mul_f32_e32 v5, v5, v5
	v_lshlrev_b32_e32 v6, 16, v113
	v_fmac_f32_e32 v5, v4, v4
	v_and_b32_e32 v7, 0xffff0000, v113
	v_fmac_f32_e32 v5, v6, v6
	v_lshlrev_b32_e32 v8, 16, v114
	v_fmac_f32_e32 v5, v7, v7
	v_and_b32_e32 v9, 0xffff0000, v114
	v_fmac_f32_e32 v5, v8, v8
	v_lshlrev_b32_e32 v10, 16, v115
	v_fmac_f32_e32 v5, v9, v9
	v_and_b32_e32 v11, 0xffff0000, v115
	v_fmac_f32_e32 v5, v10, v10
	s_waitcnt vmcnt(3)
	v_lshlrev_b32_e32 v12, 16, v116
	v_fmac_f32_e32 v5, v11, v11
	v_and_b32_e32 v13, 0xffff0000, v116
	v_fmac_f32_e32 v5, v12, v12
	v_lshlrev_b32_e32 v14, 16, v117
	v_fmac_f32_e32 v5, v13, v13
	v_and_b32_e32 v15, 0xffff0000, v117
	v_fmac_f32_e32 v5, v14, v14
	v_lshlrev_b32_e32 v16, 16, v118
	v_fmac_f32_e32 v5, v15, v15
	v_and_b32_e32 v17, 0xffff0000, v118
	v_fmac_f32_e32 v5, v16, v16
	v_lshlrev_b32_e32 v18, 16, v119
	v_fmac_f32_e32 v5, v17, v17
	v_and_b32_e32 v19, 0xffff0000, v119
	v_fmac_f32_e32 v5, v18, v18
	s_waitcnt vmcnt(2)
	v_lshlrev_b32_e32 v20, 16, v120
	v_fmac_f32_e32 v5, v19, v19
	v_and_b32_e32 v21, 0xffff0000, v120
	v_fmac_f32_e32 v5, v20, v20
	v_lshlrev_b32_e32 v22, 16, v121
	v_fmac_f32_e32 v5, v21, v21
	v_and_b32_e32 v23, 0xffff0000, v121
	v_fmac_f32_e32 v5, v22, v22
	v_lshlrev_b32_e32 v24, 16, v122
	v_fmac_f32_e32 v5, v23, v23
	v_and_b32_e32 v25, 0xffff0000, v122
	v_fmac_f32_e32 v5, v24, v24
	v_lshlrev_b32_e32 v26, 16, v123
	v_fmac_f32_e32 v5, v25, v25
	v_and_b32_e32 v27, 0xffff0000, v123
	v_fmac_f32_e32 v5, v26, v26
	s_waitcnt vmcnt(1)
	v_lshlrev_b32_e32 v28, 16, v124
	v_fmac_f32_e32 v5, v27, v27
	v_and_b32_e32 v29, 0xffff0000, v124
	v_fmac_f32_e32 v5, v28, v28
	v_lshlrev_b32_e32 v30, 16, v125
	v_fmac_f32_e32 v5, v29, v29
	v_and_b32_e32 v31, 0xffff0000, v125
	v_fmac_f32_e32 v5, v30, v30
	v_lshlrev_b32_e32 v32, 16, v126
	v_fmac_f32_e32 v5, v31, v31
	v_and_b32_e32 v33, 0xffff0000, v126
	v_fmac_f32_e32 v5, v32, v32
	v_lshlrev_b32_e32 v34, 16, v127
	v_fmac_f32_e32 v5, v33, v33
	v_and_b32_e32 v35, 0xffff0000, v127
	v_fmac_f32_e32 v5, v34, v34
	v_fmac_f32_e32 v5, v35, v35
	v_mov_b32_e32 v4, v5
	s_nop 1
	v_permlane32_swap_b32_e32 v5, v4
	v_add_f32_e32 v4, v5, v4
	s_waitcnt vmcnt(0)
	v_mul_f32_e32 v0, v0, v4
	v_mul_f32_e32 v4, 0x4f800000, v0
	v_cmp_gt_f32_e32 vcc, s4, v0
	s_nop 1
	v_cndmask_b32_e32 v0, v0, v4, vcc
	v_sqrt_f32_e32 v4, v0
	s_nop 0
	v_add_u32_e32 v3, -1, v4
	v_add_u32_e32 v5, 1, v4
	v_fma_f32 v6, -v3, v4, v0
	v_fma_f32 v7, -v5, v4, v0
	v_cmp_ge_f32_e64 s[4:5], 0, v6
	v_mov_b32_e32 v6, v222
	s_waitcnt lgkmcnt(0)
	s_barrier
; #define LAS __attribute__((address_space(3)))
; #define RAW_BARRIER() do { asm volatile("s_waitcnt lgkmcnt(0)" ::: "memory"); __builtin_amdgcn_s_barrier(); } while (0)
; template <int DV, bool WITH_V>
; DI void kv_issue(char* smem, int stage, const u16* kbase, long kpitch, const u16* vbase, long vpitch, int t, int lane, int wid) {
;   char* sb = smem + stage * Ring<DV>::STAGE;
;   {
;     const int lr = lane >> 3;
; #pragma unroll
;     for (int j = 0; j < 2; ++j) {
;       const int q = wid * 2 + j, row = q * 8 + lr;
;       const int cc = (lane & 7) ^ ((row >> 1) & 7);
;       __builtin_amdgcn_global_load_lds((const unsigned*)(kbase + (long)(t * 64 + row) * kpitch + cc * 8), (LAS unsigned*)(sb + q * 1024), 16, 0, 0);
;     }
;   }
;   if (WITH_V) {
;     if (DV == 128) {
;       const int lr = lane >> 4, cc = (lane & 15) ^ (lr << 2);
; #pragma unroll
;       for (int j = 0; j < 4; ++j) {
;         const int q = wid * 4 + j, row = q * 4 + lr;
;         __builtin_amdgcn_global_load_lds((const unsigned*)(vbase + (long)(t * 64 + row) * vpitch + cc * 8), (LAS unsigned*)(sb + 8192 + q * 1024), 16, 0, 0);
;       }
;     } else {
;       const int lr = lane >> 3, cc = (lane & 7) ^ (((lr >> 1) & 1) << 2);
; #pragma unroll
;       for (int j = 0; j < 2; ++j) {
;         const int q = wid * 2 + j, row = q * 8 + lr;
;         __builtin_amdgcn_global_load_lds((const unsigned*)(vbase + (long)(t * 64 + row) * vpitch + cc * 8), (LAS unsigned*)(sb + 8192 + q * 1024), 16, 0, 0);
;       }
;     }
;   }
; }
; template <int DV, bool SEL, bool TERM> ...
;     ...
;   RAW_BARRIER();
;   int t = prev_active(thi - 1, tlo, um);
;   int t1 = (t >= tlo) ? prev_active(t - 1, tlo, um) : t;
;   if (t >= tlo) kv_issue<DV, true>(smem, 0, kbase, kpitch, vbase, vpitch, t, lane, wid);
;   if (t1 >= tlo) kv_issue<DV, true>(smem, 1, kbase, kpitch, vbase, vpitch, t1, lane, wid);
	v_cndmask_b32_e64 v3, v4, v3, s[4:5]
	v_cmp_lt_f32_e64 s[4:5], 0, v7
	v_ashrrev_i32_e32 v8, 6, v6
	v_bfe_u32 v9, v6, 5, 1
	v_cndmask_b32_e64 v3, v3, v5, s[4:5]
	v_mul_f32_e32 v4, 0x37800000, v3
	v_cndmask_b32_e32 v3, v3, v4, vcc
	v_cmp_class_f32_e32 vcc, v0, v149
	v_bfe_u32 v2, v6, 1, 3
	v_bfe_u32 v15, v6, 3, 3
	v_cndmask_b32_e32 v0, v3, v0, vcc
	v_fma_f32 v135, v0, s1, 1.0
	v_lshlrev_b32_e32 v0, 7, v6
	v_bitop3_b32 v12, v9, v2, 2 bitop3:0x36
	v_bitop3_b32 v13, v9, v2, 4 bitop3:0x36
	v_bitop3_b32 v14, v9, v2, 6 bitop3:0x36
	v_lshlrev_b32_e32 v158, 4, v8
	v_or_b32_e32 v2, s0, v15
	v_and_b32_e32 v10, 0xf80, v0
	v_lshrrev_b32_e32 v0, 1, v6
	v_bfe_u32 v159, v6, 4, 2
	v_add_u32_e32 v2, v2, v158
	v_bitop3_b32 v11, v9, v0, 7 bitop3:0x78
	v_xor_b32_e32 v0, v159, v6
	v_ashrrev_i32_e32 v3, 31, v2
	v_lshlrev_b64 v[2:3], 13, v[2:3]
	v_lshlrev_b32_e32 v0, 4, v0
	v_lshl_add_u64 v[2:3], s[6:7], 0, v[2:3]
	v_and_b32_e32 v0, 0x70, v0
	v_lshlrev_b32_e32 v16, 11, v8
	v_lshl_add_u64 v[2:3], v[2:3], 0, v[0:1]
	v_readfirstlane_b32 s1, v16
	v_lshl_or_b32 v17, v8, 1, 1
	v_lshl_add_u64 v[2:3], v[2:3], 0, s[12:13]
	s_mov_b32 m0, s1
	v_lshl_or_b32 v160, v17, 3, v15
	global_load_lds_dwordx4 v[2:3], off
	v_lshrrev_b32_e32 v2, 1, v160
	v_xor_b32_e32 v4, v2, v6
	v_add_u32_e32 v2, s0, v160
	v_ashrrev_i32_e32 v3, 31, v2
	v_lshlrev_b64 v[2:3], 13, v[2:3]
	v_lshlrev_b32_e32 v4, 4, v4
	v_lshl_add_u64 v[2:3], s[6:7], 0, v[2:3]
	v_and_b32_e32 v4, 0x70, v4
	v_mov_b32_e32 v5, v1
	v_lshlrev_b32_e32 v17, 10, v17
	v_lshl_add_u64 v[2:3], v[2:3], 0, v[4:5]
	v_readfirstlane_b32 s1, v17
	v_lshl_add_u64 v[2:3], v[2:3], 0, s[12:13]
	s_mov_b32 m0, s1
	v_or_b32_e32 v19, s0, v159
	global_load_lds_dwordx4 v[2:3], off
	v_lshlrev_b32_e32 v2, 4, v6
	v_lshlrev_b32_e32 v3, 6, v159
	s_movk_i32 s0, 0xf0
	v_bitop3_b32 v2, v3, v2, s0 bitop3:0x78
	v_mov_b32_e32 v3, v1
	v_lshl_add_u64 v[2:3], s[8:9], 0, v[2:3]
	s_mov_b64 s[0:1], 0x1000
	v_lshl_add_u64 v[138:139], v[2:3], 0, s[0:1]
	v_add_u32_e32 v2, v19, v158
	v_add_u32_e32 v21, v16, v16
	v_lshlrev_b32_e32 v18, 2, v8
	v_ashrrev_i32_e32 v3, 31, v2
	v_add_u32_e32 v22, 0x2000, v21
	v_lshlrev_b64 v[2:3], 13, v[2:3]
	v_readfirstlane_b32 s0, v22
	v_or_b32_e32 v22, 1, v18
	v_lshl_add_u64 v[2:3], v[138:139], 0, v[2:3]
	s_mov_b32 m0, s0
	v_lshlrev_b32_e32 v161, 2, v22
	global_load_lds_dwordx4 v[2:3], off
	v_add_u32_e32 v2, v161, v19
	v_lshlrev_b32_e32 v22, 10, v22
	v_ashrrev_i32_e32 v3, 31, v2
	v_add_u32_e32 v23, 0x2000, v22
	v_lshlrev_b64 v[2:3], 13, v[2:3]
	v_readfirstlane_b32 s0, v23
	v_or_b32_e32 v23, 2, v18
	v_lshl_add_u64 v[2:3], v[138:139], 0, v[2:3]
	s_mov_b32 m0, s0
	v_lshlrev_b32_e32 v162, 2, v23
	global_load_lds_dwordx4 v[2:3], off
	v_add_u32_e32 v2, v162, v19
	v_lshlrev_b32_e32 v23, 10, v23
	v_ashrrev_i32_e32 v3, 31, v2
	v_add_u32_e32 v24, 0x2000, v23
	v_lshlrev_b64 v[2:3], 13, v[2:3]
	v_readfirstlane_b32 s0, v24
	v_or_b32_e32 v24, 3, v18
	v_lshl_add_u64 v[2:3], v[138:139], 0, v[2:3]
	s_mov_b32 m0, s0
	v_lshlrev_b32_e32 v163, 2, v24
	global_load_lds_dwordx4 v[2:3], off
	v_add_u32_e32 v2, v163, v19
	v_lshlrev_b32_e32 v19, 10, v24
	v_ashrrev_i32_e32 v3, 31, v2
	v_add_u32_e32 v24, 0x2000, v19
	v_lshlrev_b64 v[2:3], 13, v[2:3]
	v_readfirstlane_b32 s0, v24
	v_lshl_add_u64 v[2:3], v[138:139], 0, v[2:3]
	s_mov_b32 m0, s0
	s_lshl_b32 s0, s24, 6
	global_load_lds_dwordx4 v[2:3], off
	v_or_b32_e32 v2, s0, v15
	v_add_u32_e32 v2, v2, v158
	v_ashrrev_i32_e32 v3, 31, v2
	v_lshlrev_b64 v[2:3], 13, v[2:3]
	v_lshl_add_u64 v[2:3], s[6:7], 0, v[2:3]
	v_add_u32_e32 v24, 0x6000, v16
	v_lshl_add_u64 v[2:3], v[2:3], 0, v[0:1]
	v_readfirstlane_b32 s1, v24
	v_lshl_add_u64 v[2:3], v[2:3], 0, s[12:13]
	s_mov_b32 m0, s1
	v_add_u32_e32 v17, 0x6000, v17
	global_load_lds_dwordx4 v[2:3], off
	v_add_u32_e32 v2, s0, v160
	v_ashrrev_i32_e32 v3, 31, v2
	v_lshlrev_b64 v[2:3], 13, v[2:3]
	v_lshl_add_u64 v[2:3], s[6:7], 0, v[2:3]
	v_lshl_add_u64 v[2:3], v[2:3], 0, v[4:5]
	v_readfirstlane_b32 s1, v17
	v_lshl_add_u64 v[2:3], v[2:3], 0, s[12:13]
	s_mov_b32 m0, s1
	v_or_b32_e32 v17, s0, v159
	global_load_lds_dwordx4 v[2:3], off
	v_add_u32_e32 v2, v17, v158
	v_ashrrev_i32_e32 v3, 31, v2
	v_add_u32_e32 v21, 0x8000, v21
	v_lshlrev_b64 v[2:3], 13, v[2:3]
	v_readfirstlane_b32 s0, v21
	v_lshl_add_u64 v[2:3], v[138:139], 0, v[2:3]
; DI int ltid() { int x = threadIdx.x; asm volatile("" : "+v"(x)); return x; }
; #define RAW_BARRIER() do { asm volatile("s_waitcnt lgkmcnt(0)" ::: "memory"); __builtin_amdgcn_s_barrier(); } while (0)
; template <int DV>
; DI void pv_tile(f32x16 (&ot)[DV / 32], const bf16x8 (&pk)[2][2], char* sb, int lane) {
;   constexpr int VP = 2 * DV, NDC = DV / 32;
;   const int h = lane >> 5, i16 = lane & 15, qq = i16 >> 2, pp = i16 & 3, blk = (lane >> 4) & 1;
;   const int qx = (DV == 128) ? qq : (qq >> 1);
;   const unsigned vb = (unsigned)(size_t)(sb + 8192) + (4 * h + qq) * VP + 32 * blk + 8 * pp;
;   unsigned a[NDC];
; #pragma unroll
;   for (int dc = 0; dc < NDC; ++dc) a[dc] = vb + ((dc ^ qx) << 6);
; template <int DV, bool SEL, bool TERM> ...
;   constexpr int G = Ring<DV>::G;
;   const int tid = ltid(), lane = tid & 63, wid = tid >> 6, r = lane & 31, h = lane >> 5;
;   unsigned* flags = (unsigned*)(smem + SM_FLAG);
;   int foff[4];
;   make_foff(foff, r, h);
;   unsigned done = 0u;
;   const float sk = slope2 * (float)kp_mul;
;   RAW_BARRIER();
;   int t = prev_active(thi - 1, tlo, um);
;   int t1 = (t >= tlo) ? prev_active(t - 1, tlo, um) : t;
;   if (t >= tlo) kv_issue<DV, true>(smem, 0, kbase, kpitch, vbase, vpitch, t, lane, wid);
;   if (t1 >= tlo) kv_issue<DV, true>(smem, 1, kbase, kpitch, vbase, vpitch, t1, lane, wid);
;   int c = 0;
	s_mov_b32 m0, s0
	v_add_u32_e32 v21, 0x8000, v22
	global_load_lds_dwordx4 v[2:3], off
	v_add_u32_e32 v2, v161, v17
	v_ashrrev_i32_e32 v3, 31, v2
	v_lshlrev_b64 v[2:3], 13, v[2:3]
	v_readfirstlane_b32 s0, v21
	v_lshl_add_u64 v[2:3], v[138:139], 0, v[2:3]
	s_mov_b32 m0, s0
	v_add_u32_e32 v21, 0x8000, v23
	global_load_lds_dwordx4 v[2:3], off
	v_add_u32_e32 v2, v162, v17
	v_ashrrev_i32_e32 v3, 31, v2
	v_lshlrev_b64 v[2:3], 13, v[2:3]
	v_readfirstlane_b32 s0, v21
	v_lshl_add_u64 v[2:3], v[138:139], 0, v[2:3]
	s_mov_b32 m0, s0
	v_lshl_add_u64 v[140:141], s[6:7], 0, v[0:1]
	global_load_lds_dwordx4 v[2:3], off
	v_add_u32_e32 v2, v163, v17
	v_ashrrev_i32_e32 v3, 31, v2
	v_add_u32_e32 v17, 0x8000, v19
	v_lshlrev_b64 v[2:3], 13, v[2:3]
	v_readfirstlane_b32 s0, v17
	v_lshl_add_u64 v[2:3], v[138:139], 0, v[2:3]
	s_mov_b32 m0, s0
	v_bfe_u32 v0, v6, 2, 2
	global_load_lds_dwordx4 v[2:3], off
	v_lshrrev_b32_e32 v2, 3, v6
	v_lshlrev_b32_e32 v20, 3, v6
	v_and_or_b32 v2, v2, 4, v0
	v_lshlrev_b32_e32 v3, 1, v6
	v_and_b32_e32 v7, 63, v6
	v_lshlrev_b32_e32 v8, 12, v8
	v_or_b32_e32 v165, v158, v15
	v_lshl_add_u64 v[142:143], s[6:7], 0, v[4:5]
	v_lshlrev_b32_e32 v2, 8, v2
	v_and_b32_e32 v3, 32, v3
	v_and_b32_e32 v4, 24, v20
	v_lshl_or_b32 v179, v14, 4, v10
	v_mov_b32_e32 v14, v1
	v_mov_b32_e32 v15, v1
	v_add_u32_e32 v164, 0x12000, v18
	v_cmp_eq_u32_e64 s[4:5], 0, v7
	v_or3_b32 v166, v4, v3, v2
	v_lshlrev_b32_e32 v167, 6, v0
	v_lshlrev_b32_e32 v172, 2, v9
	v_add_u32_e32 v173, 0xec00, v8
	v_add_u32_e32 v174, 0xe800, v8
	v_add_u32_e32 v175, 0xe400, v8
	v_add_u32_e32 v176, 0xe000, v8
	v_add_u32_e32 v177, 0xc400, v16
	v_add_u32_e32 v178, 0xc000, v16
	v_lshl_or_b32 v180, v11, 4, v10
	v_lshl_or_b32 v181, v13, 4, v10
	v_lshl_or_b32 v182, v12, 4, v10
	v_mov_b32_e32 v0, v1
	v_mov_b32_e32 v2, v1
	v_mov_b32_e32 v3, v1
	v_mov_b32_e32 v4, v1
	v_mov_b32_e32 v6, v1
	v_mov_b32_e32 v7, v1
	v_mov_b32_e32 v8, v1
	v_mov_b32_e32 v9, v1
	v_mov_b32_e32 v10, v1
	v_mov_b32_e32 v11, v1
	v_mov_b32_e32 v12, v1
	v_mov_b32_e32 v13, v1
	v_mov_b64_e32 v[30:31], v[14:15]
	v_mov_b64_e32 v[46:47], v[14:15]
	v_mov_b64_e32 v[62:63], v[14:15]
	v_mov_b64_e32 v[78:79], v[14:15]
	v_xor_b32_e32 v168, 64, v167
	v_xor_b32_e32 v169, 0x80, v167
	v_xor_b32_e32 v170, 0xc0, v167
	v_mov_b64_e32 v[28:29], v[12:13]
	v_mov_b64_e32 v[26:27], v[10:11]
	v_mov_b64_e32 v[24:25], v[8:9]
	v_mov_b64_e32 v[22:23], v[6:7]
	v_mov_b64_e32 v[20:21], v[4:5]
	v_mov_b64_e32 v[18:19], v[2:3]
	v_mov_b64_e32 v[16:17], v[0:1]
	v_mov_b64_e32 v[44:45], v[12:13]
	v_mov_b64_e32 v[42:43], v[10:11]
	v_mov_b64_e32 v[40:41], v[8:9]
	v_mov_b64_e32 v[38:39], v[6:7]
	v_mov_b64_e32 v[36:37], v[4:5]
	v_mov_b64_e32 v[34:35], v[2:3]
	v_mov_b64_e32 v[32:33], v[0:1]
	v_mov_b64_e32 v[60:61], v[12:13]
	v_mov_b64_e32 v[58:59], v[10:11]
	v_mov_b64_e32 v[56:57], v[8:9]
	v_mov_b64_e32 v[54:55], v[6:7]
	v_mov_b64_e32 v[52:53], v[4:5]
	v_mov_b64_e32 v[50:51], v[2:3]
	v_mov_b64_e32 v[48:49], v[0:1]
	v_mov_b64_e32 v[76:77], v[12:13]
	v_mov_b64_e32 v[74:75], v[10:11]
	v_mov_b64_e32 v[72:73], v[8:9]
	v_mov_b64_e32 v[70:71], v[6:7]
	v_mov_b64_e32 v[68:69], v[4:5]
	v_mov_b64_e32 v[66:67], v[2:3]
	v_mov_b64_e32 v[64:65], v[0:1]
	v_mov_b32_e32 v6, 0
	v_mov_b32_e32 v224, v165
	v_ashrrev_i32_e32 v225, 31, v224
	v_lshlrev_b64 v[224:225], 13, v[224:225]
	v_lshl_add_u64 v[224:225], v[140:141], 0, v[224:225]
	v_lshl_add_u64 v[224:225], v[224:225], 0, s[12:13]
	v_mov_b32_e32 v226, v160
	v_ashrrev_i32_e32 v227, 31, v226
	v_lshlrev_b64 v[226:227], 13, v[226:227]
	v_lshl_add_u64 v[226:227], v[142:143], 0, v[226:227]
	v_lshl_add_u64 v[226:227], v[226:227], 0, s[12:13]
	v_add_u32_e32 v228, v159, v158
	v_ashrrev_i32_e32 v229, 31, v228
	v_lshlrev_b64 v[228:229], 13, v[228:229]
	v_lshl_add_u64 v[228:229], v[138:139], 0, v[228:229]
	v_add_u32_e32 v230, v159, v161
	v_ashrrev_i32_e32 v231, 31, v230
	v_lshlrev_b64 v[230:231], 13, v[230:231]
	v_lshl_add_u64 v[230:231], v[138:139], 0, v[230:231]
	v_add_u32_e32 v232, v159, v162
	v_ashrrev_i32_e32 v233, 31, v232
	v_lshlrev_b64 v[232:233], 13, v[232:233]
	v_lshl_add_u64 v[232:233], v[138:139], 0, v[232:233]
	v_add_u32_e32 v234, v159, v163
	v_ashrrev_i32_e32 v235, 31, v234
	v_lshlrev_b64 v[234:235], 13, v[234:235]
	v_lshl_add_u64 v[234:235], v[138:139], 0, v[234:235]
	.p2align	6

; DI void diff_attn_phase(const Params& p, char* smem) {
;     ...
;     if (tid == 0) {
;       unsigned sp = 0;
;       while (__hip_atomic_load(p.pflag + pair, __ATOMIC_RELAXED, __HIP_MEMORY_SCOPE_AGENT) == 0u) { __builtin_amdgcn_s_sleep(2); if (++sp > (1u << 26)) break; }
;       __builtin_amdgcn_fence(__ATOMIC_ACQUIRE, "agent");
;       asm volatile("s_waitcnt vmcnt(0)" ::: "memory");
;     }
.LBB0_1504:
	s_and_b64 vcc, exec, s[6:7]
	s_cbranch_vccnz .LBB0_1511
	.p2align	6

; template <bool HI_BF, bool HO_BF>
; DI void post_phase(const u16* __restrict__ y, const void* hin_, void* hout_,
;                    const float* __restrict__ gpost, const float* __restrict__ gpre, u16* __restrict__ uout) {
;     ...
;   for (int row = gw; row < T_TOK; row += nw) {
;     float4 hv[4];
; #pragma unroll
;     for (int j = 0; j < 4; ++j) {
;       if (HI_BF) {
;         const u32x2 hb = *(const u32x2*)((const u16*)hin_ + (long)row * 1024 + 4 * lane + 256 * j);
;         hv[j] = make_float4(bflo(hb.x), bfhi(hb.x), bflo(hb.y), bfhi(hb.y));
;       } else hv[j] = *(const float4*)(hin + (long)row * 1024 + 4 * lane + 256 * j);
;     }
;     if (y) {
;       float4 yv[4]; float ss = 0.f;
; #pragma unroll
;       for (int j = 0; j < 4; ++j) {
;         const u32x2 yb = *(const u32x2*)(y + (long)row * 1024 + 4 * lane + 256 * j);
;         yv[j] = make_float4(bflo(yb.x), bfhi(yb.x), bflo(yb.y), bfhi(yb.y));
;         ss += yv[j].x * yv[j].x + yv[j].y * yv[j].y + yv[j].z * yv[j].z + yv[j].w * yv[j].w;
;       }
; #pragma unroll
;       for (int o = 32; o > 0; o >>= 1) ss += __shfl_xor(ss, o);
;       const float ri = rsqrtf(ss * (1.f / 1024.f) + RMS_EPS);
; #pragma unroll
;       for (int j = 0; j < 4; ++j) {
;         const float4 g = *(const float4*)(gpost + 4 * lane + 256 * j);
;         hv[j].x += yv[j].x * ri * g.x; hv[j].y += yv[j].y * ri * g.y; hv[j].z += yv[j].z * ri * g.z; hv[j].w += yv[j].w * ri * g.w;
;       }
;     }
;     if (hout_) {
; #pragma unroll
;       for (int j = 0; j < 4; ++j) {
;         if (HO_BF) { u32x2 v; v.x = pack2(hv[j].x, hv[j].y); v.y = pack2(hv[j].z, hv[j].w); *(u32x2*)((u16*)hout_ + (long)row * 1024 + 4 * lane + 256 * j) = v; }
;         else *(float4*)(hout + (long)row * 1024 + 4 * lane + 256 * j) = hv[j];
;       }
;     }
;     if (uout) {
;       float ss = 0.f;
; #pragma unroll
;       for (int j = 0; j < 4; ++j) ss += hv[j].x * hv[j].x + hv[j].y * hv[j].y + hv[j].z * hv[j].z + hv[j].w * hv[j].w;
; #pragma unroll
;       for (int o = 32; o > 0; o >>= 1) ss += __shfl_xor(ss, o);
;       const float ri = rsqrtf(ss * (1.f / 1024.f) + RMS_EPS);
; #pragma unroll
;       for (int j = 0; j < 4; ++j) {
;         const float4 g = *(const float4*)(gpre + 4 * lane + 256 * j);
;         u32x2 v; v.x = pack2(hv[j].x * ri * g.x, hv[j].y * ri * g.y); v.y = pack2(hv[j].z * ri * g.z, hv[j].w * ri * g.w);
.LBB0_1634:
	v_add_u32_e32 v30, s24, v30
	v_cmp_lt_i32_e32 vcc, s1, v30
	v_lshl_add_u64 v[6:7], v[6:7], 0, s[28:29]
	v_lshl_add_u64 v[8:9], v[8:9], 0, s[28:29]
	s_or_b64 s[26:27], vcc, s[26:27]
	v_lshl_add_u64 v[10:11], v[10:11], 0, s[28:29]
	s_andn2_b64 exec, exec, s[26:27]
	s_cbranch_execz .LBB0_1641
	.p2align	6

; DI unsigned xb_ld(unsigned* p) { return __hip_atomic_load(p, __ATOMIC_RELAXED, __HIP_MEMORY_SCOPE_AGENT); }
; DI unsigned xb_add(unsigned* p, unsigned v) { return __hip_atomic_fetch_add(p, v, __ATOMIC_RELAXED, __HIP_MEMORY_SCOPE_AGENT); }
; #define XB_SPIN(cond, bar) do { unsigned _sp = 0; while (cond) { __builtin_amdgcn_s_sleep(1); \
;     if ((++_sp & 255u) == 0u) { if (xb_ld(&(bar)[XB_TMO])) break; if (_sp > XB_SPIN_CAP) { atomicAdd(&(bar)[XB_TMO], 1u); break; } } } } while (0)
; DI void xcd_barrier(const XcdBarrier& b) {
;     ...
;       else XB_SPIN(xb_ld(&bar[XB_TOPGEN]) == tg, bar);
;       __builtin_amdgcn_fence(__ATOMIC_ACQUIRE, "agent");
;       xb_add(&bar[XB_XGEN(b.x)], 1u);
;       asm volatile("s_waitcnt vmcnt(0)" ::: "memory");
;     } else {
;       XB_SPIN(xb_ld(&bar[XB_XGEN(b.x)]) == gen, bar);
.LBB0_1665:
	s_and_b64 s[14:15], exec, s[14:15]
	s_or_b64 s[10:11], s[14:15], s[10:11]
	s_andn2_b64 s[12:13], s[12:13], exec
	s_and_b64 s[14:15], s[18:19], exec
	s_or_b64 s[12:13], s[12:13], s[14:15]
	s_andn2_b64 exec, exec, s[10:11]
	s_cbranch_execz .LBB0_1672
	.p2align	6

; DI unsigned xb_ld(unsigned* p) { return __hip_atomic_load(p, __ATOMIC_RELAXED, __HIP_MEMORY_SCOPE_AGENT); }
; DI unsigned xb_add(unsigned* p, unsigned v) { return __hip_atomic_fetch_add(p, v, __ATOMIC_RELAXED, __HIP_MEMORY_SCOPE_AGENT); }
; #define XB_SPIN(cond, bar) do { unsigned _sp = 0; while (cond) { __builtin_amdgcn_s_sleep(1); \
;     if ((++_sp & 255u) == 0u) { if (xb_ld(&(bar)[XB_TMO])) break; if (_sp > XB_SPIN_CAP) { atomicAdd(&(bar)[XB_TMO], 1u); break; } } } } while (0)
; DI void xcd_barrier(const XcdBarrier& b) {
;     ...
;       else XB_SPIN(xb_ld(&bar[XB_TOPGEN]) == tg, bar);
;       __builtin_amdgcn_fence(__ATOMIC_ACQUIRE, "agent");
;       xb_add(&bar[XB_XGEN(b.x)], 1u);
;       asm volatile("s_waitcnt vmcnt(0)" ::: "memory");
;     } else {
;       XB_SPIN(xb_ld(&bar[XB_XGEN(b.x)]) == gen, bar);
.LBB0_1682:
	s_xor_b64 s[18:19], s[18:19], -1
	s_and_b64 s[20:21], exec, s[22:23]
	s_or_b64 s[12:13], s[20:21], s[12:13]
	s_andn2_b64 s[14:15], s[14:15], exec
	s_and_b64 s[18:19], s[18:19], exec
	s_or_b64 s[14:15], s[14:15], s[18:19]
	s_andn2_b64 exec, exec, s[12:13]
	s_cbranch_execz .LBB0_1689
	.p2align	6

; DI int ltid() { int x = threadIdx.x; asm volatile("" : "+v"(x)); return x; }
; DI int lbid() { int x = blockIdx.x; asm volatile("" : "+s"(x)); return x; }
; template <class ARow, class Epi>
; DI void gemm_tile(const ARow& arow, long a_kstride, const u16* __restrict__ Bt, long ldb, int K, int m0, int n0,
;                   const Epi& epi, char* smem) {
;   const int tid = ltid(), lane = tid & 63, wid = tid >> 6;
;   const int r = lane & 31, h = lane >> 5;
;   const int wn = wid & 1, wm = wid >> 1;
;   const u16* ap[4]; const u16* bp[4];
;   {
;     const int lr = lane >> 3;
; #pragma unroll
;     for (int j = 0; j < 4; ++j) {
;       const int row = (wid * 4 + j) * 8 + lr;
;       const int cc = (lane & 7) ^ ((row >> 1) & 7);
;       ap[j] = arow(m0 + row) + cc * 8;
;       bp[j] = Bt + (long)(n0 + row) * ldb + cc * 8;
;     }
;   }
;     ...
;   const int fr = lane & 15, fq = lane >> 4;
;   int foff[2];
; #pragma unroll
;   for (int ks = 0; ks < 2; ++ks) foff[ks] = fr * 128 + ((((4 * ks + fq) ^ ((fr >> 1) & 7))) << 4);
;   f32x4 acc[4][4];
; #pragma unroll
;   for (int a = 0; a < 4; ++a)
; #pragma unroll
;     for (int b = 0; b < 4; ++b) acc[a][b] = (f32x4){0.f, 0.f, 0.f, 0.f};
;   const int KT = K >> 6;
;   GEMM_STAGE(0, 0);
; template <class Epi>
; DI void gemm_phase_plain(const u16* A, long lda, const u16* Bt, long ldb, int M, int N, int K, const Epi& epi, char* smem) {
;     ...
;   for (int t = lbid(); t < nwg; t += gridDim.x) {
;     const int xcd = t & 7, off = t >> 3;
;     const int wg = (xcd < rr ? xcd * (q + 1) : rr * (q + 1) + (xcd - rr) * q) + off;
;     const int nig = 8 * MT, gid = wg / nig, fm = gid * 8, gsz = (NT - fm) < 8 ? (NT - fm) : 8;
;     const int nt = fm + (wg % nig) % gsz, mt = (wg % nig) / gsz;
.LBB0_1701:
	s_and_b32 s1, s25, 7
	s_ashr_i32 s0, s25, 3
	s_mulk_i32 s1, 0x1c0
	s_add_i32 s4, s1, s0
	s_ashr_i32 s0, s4, 31
	s_lshr_b32 s0, s0, 22
	s_add_i32 s0, s4, s0
	s_ashr_i32 s1, s0, 10
	s_lshl_b32 s5, s1, 3
	s_sub_i32 s1, 28, s5
	s_min_u32 s6, s1, 8
	s_and_b32 s7, s0, 0xfffffc00
	s_sub_i32 s8, s4, s7
	v_cvt_f32_ubyte0_e32 v1, s6
	v_cvt_f32_i32_e32 v0, s8
	v_rcp_iflag_f32_e32 v2, v1
	s_ashr_i32 s0, s8, 30
	s_or_b32 s9, s0, 1
	v_mov_b32_e32 v82, v222
	v_mul_f32_e32 v2, v0, v2
	v_trunc_f32_e32 v2, v2
	v_fma_f32 v0, -v2, v1, v0
	v_cvt_i32_f32_e32 v2, v2
	v_cmp_ge_f32_e64 s[0:1], |v0|, v1
	s_and_b64 s[0:1], s[0:1], exec
	s_cselect_b32 s0, s9, 0
	v_readfirstlane_b32 s1, v2
	s_add_i32 s0, s1, s0
	s_mul_i32 s6, s0, s6
	s_sext_i32_i16 s1, s0
	s_sub_i32 s0, s8, s6
	s_sext_i32_i16 s0, s0
	v_ashrrev_i32_e32 v16, 6, v82
	v_bfe_u32 v17, v82, 3, 3
	v_lshlrev_b32_e32 v18, 5, v16
	s_add_i32 s5, s5, s0
	s_lshl_b32 s0, s1, 7
	v_or_b32_e32 v12, v18, v17
	v_bfe_u32 v83, v82, 4, 2
	v_add_u32_e32 v0, s0, v12
	s_lshl_b32 s35, s5, 7
	v_xor_b32_e32 v2, v83, v82
	v_ashrrev_i32_e32 v1, 31, v0
	v_or_b32_e32 v8, 8, v12
	v_lshlrev_b64 v[0:1], 11, v[0:1]
	v_lshlrev_b32_e32 v2, 4, v2
	v_lshrrev_b32_e32 v19, 1, v8
	v_add_u32_e32 v4, s0, v8
	v_add_u32_e32 v8, s35, v8
	v_lshlrev_b32_e32 v90, 12, v16
	v_lshl_add_u64 v[0:1], s[12:13], 0, v[0:1]
	v_and_b32_e32 v64, 0x70, v2
	v_add_u32_e32 v2, s35, v12
	v_xor_b32_e32 v6, v19, v82
	v_ashrrev_i32_e32 v5, 31, v4
	v_ashrrev_i32_e32 v9, 31, v8
	v_readfirstlane_b32 s1, v90
	v_lshl_add_u64 v[0:1], v[0:1], 0, v[64:65]
	v_ashrrev_i32_e32 v3, 31, v2
	v_lshlrev_b64 v[4:5], 11, v[4:5]
	v_lshlrev_b32_e32 v6, 4, v6
	v_lshlrev_b64 v[8:9], 11, v[8:9]
	s_mov_b32 m0, s1
	v_lshlrev_b64 v[2:3], 11, v[2:3]
	v_lshl_add_u64 v[4:5], s[12:13], 0, v[4:5]
	v_and_b32_e32 v6, 0x70, v6
	v_mov_b32_e32 v7, v65
	v_lshl_add_u64 v[8:9], s[2:3], 0, v[8:9]
	v_or_b32_e32 v10, 16, v12
	global_load_lds_dwordx4 v[0:1], off
	v_add_u32_e32 v0, 0x4000, v90
	v_lshl_add_u64 v[2:3], s[2:3], 0, v[2:3]
	v_lshl_add_u64 v[4:5], v[4:5], 0, v[6:7]
	v_lshl_add_u64 v[6:7], v[8:9], 0, v[6:7]
	v_add_u32_e32 v8, s0, v10
	v_add_u32_e32 v10, s35, v10
	v_or_b32_e32 v14, 24, v12
	v_readfirstlane_b32 s1, v0
	v_or_b32_e32 v0, 0x400, v90
	v_lshl_add_u64 v[2:3], v[2:3], 0, v[64:65]
	v_ashrrev_i32_e32 v9, 31, v8
	v_ashrrev_i32_e32 v11, 31, v10
	v_lshrrev_b32_e32 v20, 1, v14
	s_mov_b32 m0, s1
	v_readfirstlane_b32 s1, v0
	v_add_u32_e32 v0, 0x4400, v90
	v_lshlrev_b64 v[8:9], 11, v[8:9]
	v_lshlrev_b64 v[10:11], 11, v[10:11]
	v_xor_b32_e32 v15, v20, v82
	v_add_u32_e32 v12, s0, v14
	global_load_lds_dwordx4 v[2:3], off
	s_mov_b32 m0, s1
	v_readfirstlane_b32 s1, v0
	v_or_b32_e32 v0, 0x800, v90
	v_lshl_add_u64 v[8:9], s[12:13], 0, v[8:9]
	v_lshl_add_u64 v[10:11], s[2:3], 0, v[10:11]
	v_ashrrev_i32_e32 v13, 31, v12
	v_lshlrev_b32_e32 v15, 4, v15
	v_add_u32_e32 v14, s35, v14
	global_load_lds_dwordx4 v[4:5], off
	s_mov_b32 m0, s1
	v_readfirstlane_b32 s1, v0
	v_add_u32_e32 v0, 0x4800, v90
	v_lshl_add_u64 v[8:9], v[8:9], 0, v[64:65]
	v_lshl_add_u64 v[10:11], v[10:11], 0, v[64:65]
	v_lshlrev_b64 v[12:13], 11, v[12:13]
	v_and_b32_e32 v64, 0x70, v15
	v_ashrrev_i32_e32 v15, 31, v14
	global_load_lds_dwordx4 v[6:7], off
	s_mov_b32 m0, s1
	v_readfirstlane_b32 s1, v0
	v_or_b32_e32 v0, 0xc00, v90
	v_lshl_add_u64 v[12:13], s[12:13], 0, v[12:13]
	v_lshlrev_b64 v[14:15], 11, v[14:15]
	global_load_lds_dwordx4 v[8:9], off
	s_mov_b32 m0, s1
	v_readfirstlane_b32 s1, v0
	v_add_u32_e32 v0, 0x4c00, v90
	v_lshl_add_u64 v[12:13], v[12:13], 0, v[64:65]
	v_lshl_add_u64 v[14:15], s[2:3], 0, v[14:15]
	global_load_lds_dwordx4 v[10:11], off
	s_mov_b32 m0, s1
	v_readfirstlane_b32 s1, v0
	v_lshl_add_u64 v[14:15], v[14:15], 0, v[64:65]
	global_load_lds_dwordx4 v[12:13], off
	s_mov_b32 m0, s1
	v_or_b32_e32 v0, s0, v17
	global_load_lds_dwordx4 v[14:15], off
	s_sub_i32 s1, s4, s6
	v_add_u32_e32 v0, v0, v18
	s_sub_i32 s1, s1, s7
	v_ashrrev_i32_e32 v1, 31, v0
	v_bitop3_b32 v2, v83, 7, v82 bitop3:0x48
	s_sext_i32_i16 s1, s1
	v_lshlrev_b64 v[0:1], 11, v[0:1]
	v_lshlrev_b32_e32 v2, 4, v2
	s_lshl_b32 s1, s1, 7
	v_or_b32_e32 v0, v0, v2
	s_add_i32 s1, s1, s7
	v_lshl_add_u64 v[66:67], s[20:21], 0, v[0:1]
	v_or_b32_e32 v0, s1, v17
	v_add_u32_e32 v0, v0, v18
	v_ashrrev_i32_e32 v1, 31, v0
	v_lshlrev_b64 v[0:1], 11, v[0:1]
	v_or_b32_e32 v0, v0, v2
	v_or_b32_e32 v3, 8, v17
	v_lshl_add_u64 v[68:69], s[22:23], 0, v[0:1]
	v_or_b32_e32 v0, s0, v3
	v_add_u32_e32 v0, v0, v18
	v_ashrrev_i32_e32 v1, 31, v0
	v_bitop3_b32 v4, v19, 7, v82 bitop3:0x48
	v_lshlrev_b64 v[0:1], 11, v[0:1]
	v_lshlrev_b32_e32 v4, 4, v4
	v_or_b32_e32 v0, v0, v4
	v_lshl_add_u64 v[70:71], s[20:21], 0, v[0:1]
	v_or_b32_e32 v0, s1, v3
	v_add_u32_e32 v0, v0, v18
	v_ashrrev_i32_e32 v1, 31, v0
	v_lshlrev_b64 v[0:1], 11, v[0:1]
	v_or_b32_e32 v0, v0, v4
	v_or_b32_e32 v3, 16, v17
	v_lshl_add_u64 v[72:73], s[22:23], 0, v[0:1]
	v_or_b32_e32 v0, s0, v3
	v_add_u32_e32 v0, v0, v18
	v_ashrrev_i32_e32 v1, 31, v0
	v_lshlrev_b64 v[0:1], 11, v[0:1]
	v_or_b32_e32 v0, v0, v2
	v_lshl_add_u64 v[74:75], s[20:21], 0, v[0:1]
	v_or_b32_e32 v0, s1, v3
	v_add_u32_e32 v0, v0, v18
	v_ashrrev_i32_e32 v1, 31, v0
	v_lshlrev_b64 v[0:1], 11, v[0:1]
	v_or_b32_e32 v0, v0, v2
	v_or_b32_e32 v2, 24, v17
	v_lshl_add_u64 v[76:77], s[22:23], 0, v[0:1]
	v_or_b32_e32 v0, s0, v2
	v_add_u32_e32 v0, v0, v18
	v_ashrrev_i32_e32 v1, 31, v0
	v_bitop3_b32 v3, v20, 7, v82 bitop3:0x48
	v_lshlrev_b64 v[0:1], 11, v[0:1]
	v_lshlrev_b32_e32 v3, 4, v3
	v_or_b32_e32 v0, v0, v3
	v_lshl_add_u64 v[78:79], s[20:21], 0, v[0:1]
	v_or_b32_e32 v0, s1, v2
	v_add_u32_e32 v0, v0, v18
	v_and_b32_e32 v64, 15, v82
	v_lshrrev_b32_e32 v22, 1, v82
	v_ashrrev_i32_e32 v1, 31, v0
	v_lshlrev_b32_e32 v21, 7, v64
	v_bfe_u32 v23, v82, 1, 3
	v_bitop3_b32 v22, v83, v22, 7 bitop3:0x78
	s_waitcnt vmcnt(0)
; template <class ARow, class Epi>
; DI void gemm_tile(const ARow& arow, long a_kstride, const u16* __restrict__ Bt, long ldb, int K, int m0, int n0,
;                   const Epi& epi, char* smem) {
;     ...
;   const int fr = lane & 15, fq = lane >> 4;
;   int foff[2];
; #pragma unroll
;   for (int ks = 0; ks < 2; ++ks) foff[ks] = fr * 128 + ((((4 * ks + fq) ^ ((fr >> 1) & 7))) << 4);
;   f32x4 acc[4][4];
; #pragma unroll
;   for (int a = 0; a < 4; ++a)
; #pragma unroll
;     for (int b = 0; b < 4; ++b) acc[a][b] = (f32x4){0.f, 0.f, 0.f, 0.f};
;   const int KT = K >> 6;
;   GEMM_STAGE(0, 0);
;   asm volatile("s_waitcnt vmcnt(0)" ::: "memory");
;   __syncthreads();
	v_lshlrev_b64 v[0:1], 11, v[0:1]
	v_and_b32_e32 v84, 1, v16
	v_lshl_or_b32 v87, v22, 4, v21
	v_bitop3_b32 v22, v83, v23, 4 bitop3:0x36
	v_ashrrev_i32_e32 v85, 7, v82
	v_or_b32_e32 v0, v0, v3
	v_lshl_or_b32 v86, v22, 4, v21
	v_lshlrev_b32_e32 v88, 13, v85
	v_lshlrev_b32_e32 v89, 13, v84
	v_lshl_add_u64 v[80:81], s[22:23], 0, v[0:1]
	s_mov_b64 s[4:5], 0
	s_mov_b32 s1, 0
	v_mov_b32_e32 v44, 0
	v_mov_b32_e32 v45, v65
	v_mov_b32_e32 v46, v65
	v_mov_b32_e32 v47, v65
	v_mov_b32_e32 v52, 0
	v_mov_b32_e32 v53, v65
	v_mov_b32_e32 v54, v65
	v_mov_b32_e32 v55, v65
	v_mov_b32_e32 v0, 0
	v_mov_b32_e32 v1, v65
	v_mov_b32_e32 v2, v65
	v_mov_b32_e32 v3, v65
	v_mov_b32_e32 v4, 0
	v_mov_b32_e32 v5, v65
	v_mov_b32_e32 v6, v65
	v_mov_b32_e32 v7, v65
	v_mov_b32_e32 v8, 0
	v_mov_b32_e32 v9, v65
	v_mov_b32_e32 v10, v65
	v_mov_b32_e32 v11, v65
	v_mov_b32_e32 v12, 0
	v_mov_b32_e32 v13, v65
	v_mov_b32_e32 v14, v65
	v_mov_b32_e32 v15, v65
	v_mov_b32_e32 v16, 0
	v_mov_b32_e32 v17, v65
	v_mov_b32_e32 v18, v65
	v_mov_b32_e32 v19, v65
	v_mov_b32_e32 v20, 0
	v_mov_b32_e32 v21, v65
	v_mov_b32_e32 v22, v65
	v_mov_b32_e32 v23, v65
	v_mov_b32_e32 v24, 0
	v_mov_b32_e32 v25, v65
	v_mov_b32_e32 v26, v65
	v_mov_b32_e32 v27, v65
	v_mov_b32_e32 v28, 0
	v_mov_b32_e32 v29, v65
	v_mov_b32_e32 v30, v65
	v_mov_b32_e32 v31, v65
	v_mov_b32_e32 v32, 0
	v_mov_b32_e32 v33, v65
	v_mov_b32_e32 v34, v65
	v_mov_b32_e32 v35, v65
	v_mov_b32_e32 v36, 0
	v_mov_b32_e32 v37, v65
	v_mov_b32_e32 v38, v65
	v_mov_b32_e32 v39, v65
	v_mov_b32_e32 v40, 0
	v_mov_b32_e32 v41, v65
	v_mov_b32_e32 v42, v65
	v_mov_b32_e32 v43, v65
	v_mov_b32_e32 v48, 0
	v_mov_b32_e32 v49, v65
	v_mov_b32_e32 v50, v65
	v_mov_b32_e32 v51, v65
	v_mov_b32_e32 v56, 0
	v_mov_b32_e32 v57, v65
	v_mov_b32_e32 v58, v65
	v_mov_b32_e32 v59, v65
	v_mov_b32_e32 v60, 0
	v_mov_b32_e32 v61, v65
	v_mov_b32_e32 v62, v65
	v_mov_b32_e32 v63, v65
	s_waitcnt vmcnt(0) lgkmcnt(0)
	s_barrier
	.p2align	6

; DI int ltid() { int x = threadIdx.x; asm volatile("" : "+v"(x)); return x; }
; #define RAW_BARRIER() do { asm volatile("s_waitcnt lgkmcnt(0)" ::: "memory"); __builtin_amdgcn_s_barrier(); } while (0)
; template <int DV, bool SEL, bool TERM> ...
;     ...
;   const int tid = ltid(), lane = tid & 63, wid = tid >> 6, r = lane & 31, h = lane >> 5;
;   unsigned* flags = (unsigned*)(smem + SM_FLAG);
;   int foff[4];
;   make_foff(foff, r, h);
;   unsigned done = 0u;
;   const float sk = slope2 * (float)kp_mul;
;   RAW_BARRIER();
;   int t = prev_active(thi - 1, tlo, um);
;   int t1 = (t >= tlo) ? prev_active(t - 1, tlo, um) : t;
;   if (t >= tlo) kv_issue<DV, true>(smem, 0, kbase, kpitch, vbase, vpitch, t, lane, wid);
;   if (t1 >= tlo) kv_issue<DV, true>(smem, 1, kbase, kpitch, vbase, vpitch, t1, lane, wid);
;   int c = 0;
; DI void dil1_attn_phase(const Params& p, char* smem) {
;     ...
;     f32x16 ot[4];
;     float m = 0.f, l = 0.f;
; #pragma unroll
;     for (int dc = 0; dc < 4; ++dc)
; #pragma unroll
;       for (int i = 0; i < 16; ++i) ot[dc][i] = 0.f;
;     const float slope2 = exp2f(-8.f * (float)(hg + 1) / 12.f) * LOG2E;
;     bf16x8 qf[4];
;     load_q(qf, p.qkvz + tok * LD + hg * 64, h);
;     const u16* kb_ = p.qkvz + (long)b * SEQ * LD + 768 + hg * 64;
;     const u16* vb_ = p.qkvz + (long)b * SEQ * LD + 1536 + hg * 256 + half * 128;
;     const int g0 = qb128 * 128;
;     const int tlo = (g0 - 128) > 0 ? ((g0 - 128) >> 6) : 0, thi = ((g0 + 127) >> 6) + 1;
;     flash_pass<128, false, false>(smem, kb_, LD, vb_, LD, tlo, thi, nullptr, qf, pos, 1, 129, slope2, q0, q0 + 31, nullptr, 0.f, ot, m, l);
.LBB0_1997:
	s_andn2_b64 vcc, exec, s[0:1]
	s_cbranch_vccnz .LBB0_2015
	s_not_b32 s0, s92
	s_lshl_b32 s0, s0, 3
	v_cvt_f32_i32_e32 v0, s0
	v_lshlrev_b32_e32 v153, 4, v4
	v_lshrrev_b32_e32 v155, 4, v2
	v_lshlrev_b32_e32 v13, 6, v155
	v_div_scale_f32 v5, s[0:1], s57, s57, v0
	v_rcp_f32_e32 v6, v5
	v_div_scale_f32 v7, vcc, v0, s57, v0
	s_mov_b32 s0, 0xc2fc0000
	v_fma_f32 v8, -v5, v6, 1.0
	v_fmac_f32_e32 v6, v8, v6
	v_mul_f32_e32 v8, v7, v6
	v_fma_f32 v9, -v5, v8, v7
	v_fmac_f32_e32 v8, v9, v6
	v_fma_f32 v5, -v5, v8, v7
	v_div_fmas_f32 v5, v5, v6, v8
	v_div_fixup_f32 v0, v5, s57, v0
	v_cmp_gt_f32_e32 vcc, s0, v0
	s_and_b64 s[0:1], vcc, exec
	s_cselect_b32 s0, 0xffffffc0, 0
	v_cndmask_b32_e32 v5, 0, v148, vcc
	v_add_f32_e32 v0, v0, v5
	v_exp_f32_e32 v0, v0
	v_lshrrev_b32_e32 v5, 5, v2
	v_bfe_u32 v7, v3, 1, 3
	v_lshlrev_b32_e32 v11, 11, v4
	v_ldexp_f32 v0, v0, s0
	v_mul_f32_e32 v132, 0x3fb8aa3b, v0
	v_lshlrev_b32_e32 v0, 7, v3
	v_and_b32_e32 v6, 0xf80, v0
	v_lshrrev_b32_e32 v0, 1, v3
	v_bitop3_b32 v8, v5, v0, 7 bitop3:0x78
	v_lshrrev_b32_e32 v0, 3, v2
	v_or_b32_e32 v154, v153, v0
	v_xor_b32_e32 v0, v155, v2
	v_lshlrev_b32_e32 v0, 4, v0
	v_and_b32_e32 v0, 0x70, v0
	v_or_b32_e32 v156, 8, v154
	v_lshl_add_u64 v[134:135], s[4:5], 0, v[0:1]
	v_lshrrev_b32_e32 v0, 1, v156
	v_xor_b32_e32 v0, v0, v3
	v_lshlrev_b32_e32 v0, 4, v0
	v_and_b32_e32 v0, 0x70, v0
	v_lshl_add_u64 v[136:137], s[4:5], 0, v[0:1]
	v_lshlrev_b32_e32 v0, 4, v2
	v_bitop3_b32 v0, v13, v0, s56 bitop3:0x78
	v_lshl_add_u64 v[138:139], s[6:7], 0, v[0:1]
	v_lshlrev_b32_e32 v0, 12, v4
	v_bfe_u32 v4, v3, 2, 2
	v_lshrrev_b32_e32 v3, 3, v3
	v_lshlrev_b32_e32 v12, 3, v2
	v_and_or_b32 v3, v3, 4, v4
	v_lshlrev_b32_e32 v2, 1, v2
	v_bitop3_b32 v9, v5, v7, 2 bitop3:0x36
	v_bitop3_b32 v10, v5, v7, 4 bitop3:0x36
	v_bitop3_b32 v7, v5, v7, 6 bitop3:0x36
	v_lshlrev_b32_e32 v3, 8, v3
	v_and_b32_e32 v2, 32, v2
	v_and_b32_e32 v12, 24, v12
	v_mov_b32_e32 v14, v1
	v_mov_b32_e32 v15, v1
	v_or3_b32 v160, v12, v2, v3
	v_lshlrev_b32_e32 v161, 6, v4
	v_lshlrev_b32_e32 v166, 2, v5
	v_add_u32_e32 v167, 0xec00, v0
	v_add_u32_e32 v168, 0xe800, v0
	v_add_u32_e32 v169, 0xe400, v0
	v_add_u32_e32 v170, 0xe000, v0
	v_add_u32_e32 v171, 0xc400, v11
	v_add_u32_e32 v172, 0xc000, v11
	v_lshl_or_b32 v173, v8, 4, v6
	v_lshl_or_b32 v174, v7, 4, v6
	v_lshl_or_b32 v175, v9, 4, v6
	v_lshl_or_b32 v176, v10, 4, v6
	v_mov_b32_e32 v0, v1
	v_mov_b32_e32 v2, v1
	v_mov_b32_e32 v3, v1
	v_mov_b32_e32 v4, v1
	v_mov_b32_e32 v5, v1
	v_mov_b32_e32 v6, v1
	v_mov_b32_e32 v7, v1
	v_mov_b32_e32 v8, v1
	v_mov_b32_e32 v9, v1
	v_mov_b32_e32 v10, v1
	v_mov_b32_e32 v11, v1
	v_mov_b32_e32 v12, v1
	v_mov_b32_e32 v13, v1
	v_mov_b32_e32 v165, 0
	v_mov_b64_e32 v[30:31], v[14:15]
	v_mov_b64_e32 v[46:47], v[14:15]
	v_mov_b64_e32 v[62:63], v[14:15]
	v_mov_b64_e32 v[78:79], v[14:15]
	s_mov_b32 s95, 0
	v_or_b32_e32 v152, 31, v151
	s_mov_b32 s96, 2
	v_or_b32_e32 v157, 4, v153
	v_or_b32_e32 v158, 8, v153
	v_or_b32_e32 v159, 12, v153
	v_xor_b32_e32 v162, 64, v161
	v_xor_b32_e32 v163, 0x80, v161
	v_xor_b32_e32 v164, 0xc0, v161
	v_mov_b32_e32 v140, v132
	v_mov_b32_e32 v141, v132
	v_mov_b32_e32 v142, v132
	v_mov_b32_e32 v143, v132
	s_mov_b32 s97, 0
	v_mov_b64_e32 v[28:29], v[12:13]
	v_mov_b64_e32 v[26:27], v[10:11]
	v_mov_b64_e32 v[24:25], v[8:9]
	v_mov_b64_e32 v[22:23], v[6:7]
	v_mov_b64_e32 v[20:21], v[4:5]
	v_mov_b64_e32 v[18:19], v[2:3]
	v_mov_b64_e32 v[16:17], v[0:1]
	v_mov_b64_e32 v[44:45], v[12:13]
	v_mov_b64_e32 v[42:43], v[10:11]
	v_mov_b64_e32 v[40:41], v[8:9]
	v_mov_b64_e32 v[38:39], v[6:7]
	v_mov_b64_e32 v[36:37], v[4:5]
	v_mov_b64_e32 v[34:35], v[2:3]
	v_mov_b64_e32 v[32:33], v[0:1]
	v_mov_b64_e32 v[60:61], v[12:13]
	v_mov_b64_e32 v[58:59], v[10:11]
	v_mov_b64_e32 v[56:57], v[8:9]
	v_mov_b64_e32 v[54:55], v[6:7]
	v_mov_b64_e32 v[52:53], v[4:5]
	v_mov_b64_e32 v[50:51], v[2:3]
	v_mov_b64_e32 v[48:49], v[0:1]
	v_mov_b64_e32 v[76:77], v[12:13]
	v_mov_b64_e32 v[74:75], v[10:11]
	v_mov_b64_e32 v[72:73], v[8:9]
	v_mov_b64_e32 v[70:71], v[6:7]
	v_mov_b64_e32 v[68:69], v[4:5]
	v_mov_b64_e32 v[66:67], v[2:3]
	v_mov_b64_e32 v[64:65], v[0:1]
	v_mov_b32_e32 v131, 0
	v_mov_b32_e32 v80, 0
	v_mov_b32_e32 v81, v165
	v_mov_b32_e32 v82, v165
	v_mov_b32_e32 v83, v165
	v_mov_b32_e32 v84, v165
	v_mov_b32_e32 v85, v165
	v_mov_b32_e32 v86, v165
	v_mov_b32_e32 v87, v165
	v_mov_b32_e32 v88, v165
	v_mov_b32_e32 v89, v165
	v_mov_b32_e32 v90, v165
	v_mov_b32_e32 v91, v165
	v_mov_b32_e32 v92, v165
	v_mov_b32_e32 v93, v165
	v_mov_b32_e32 v94, v165
	v_mov_b32_e32 v95, v165
	v_mov_b32_e32 v96, v165
	v_mov_b32_e32 v97, v165
	v_mov_b32_e32 v98, v165
	v_mov_b32_e32 v99, v165
	v_mov_b32_e32 v100, v165
	v_mov_b32_e32 v101, v165
	v_mov_b32_e32 v102, v165
	v_mov_b32_e32 v103, v165
	v_mov_b32_e32 v104, v165
	v_mov_b32_e32 v105, v165
	v_mov_b32_e32 v106, v165
	v_mov_b32_e32 v107, v165
	v_mov_b32_e32 v108, v165
	v_mov_b32_e32 v109, v165
	v_mov_b32_e32 v110, v165
	v_mov_b32_e32 v111, v165
	s_waitcnt vmcnt(0)
	.p2align	6

; DI void dil_attn_phase(const Params& p, char* smem) {
;     ...
;     f32x16 ot[4];
;     float m = 0.f, l = 0.f;
; #pragma unroll
;     for (int dc = 0; dc < 4; ++dc)
; #pragma unroll
;       for (int i = 0; i < 16; ++i) ot[dc][i] = 0.f;
; #pragma unroll
;     for (int g = 1; g < 3; ++g) {
;       const int d = (g == 1) ? 4 : 16;
;       const int res = pos % d;
;       const int uq = pos / d;
;       const int wpos0 = r16 + 16 * (U0 + wid * 32), wpos1 = wpos0 + 16 * 31;
;       const int wq_min = wpos0 / d, wq_max = wpos1 / d;
;       const int gpos0 = r16 + 16 * U0, gpos1 = gpos0 + 16 * 127;
;       const int gq_min = gpos0 / d, gq_max = gpos1 / d;
;       const int tlo = (gq_min - 128) > 0 ? ((gq_min - 128) >> 6) : 0;
;       const int thi = (gq_max >> 6) + 1;
;       const float slope = exp2f(-8.f * (float)(4 * g + hg + 1) / 12.f);
;       const float slope2 = slope * (float)d * LOG2E;
;       bf16x8 qf[4];
;       load_q(qf, p.qkvz + tok * LD + g * 256 + hg * 64, h);
;       const u16* kb_ = p.qkvz + ((long)b * SEQ + res) * LD + 768 + g * 256 + hg * 64;
;       const u16* vb_ = p.qkvz + ((long)b * SEQ + res) * LD + 1536 + hg * 256 + half * 128;
;       flash_pass<128, false, false>(smem, kb_, LD * d, vb_, LD * d, tlo, thi, nullptr, qf, uq, 1, 129, slope2, wq_min, wq_max, nullptr, 0.f, ot, m, l);
.LBB0_2086:
	v_lshl_or_b32 v158, v9, 4, s6
	v_or_b32_e32 v157, 0x1f0, v158
	s_andn2_b64 vcc, exec, s[0:1]
	s_lshl_b32 s90, s14, 3
	s_cbranch_vccnz .LBB0_2104
	s_sub_i32 s0, 0xffffffd8, s90
	v_cvt_f32_i32_e32 v9, s0
	v_ashrrev_i32_e32 v0, 31, v158
	v_ashrrev_i32_e32 v159, 2, v10
	v_lshrrev_b32_e32 v0, 30, v0
	v_div_scale_f32 v10, s[0:1], s2, s2, v9
	v_add_u32_e32 v0, v158, v0
	v_rcp_f32_e32 v11, v10
	v_ashrrev_i32_e32 v160, 2, v0
	v_ashrrev_i32_e32 v0, 31, v157
	v_lshrrev_b32_e32 v0, 30, v0
	v_add_u32_e32 v0, v157, v0
	v_ashrrev_i32_e32 v161, 2, v0
	v_fma_f32 v0, -v10, v11, 1.0
	v_fmac_f32_e32 v11, v0, v11
	v_div_scale_f32 v0, vcc, v9, s2, v9
	v_mul_f32_e32 v12, v0, v11
	v_fma_f32 v13, -v10, v12, v0
	v_fmac_f32_e32 v12, v13, v11
	v_fma_f32 v0, -v10, v12, v0
	v_div_fmas_f32 v0, v0, v11, v12
	v_div_fixup_f32 v0, v0, s2, v9
	s_mov_b32 s0, 0xc2fc0000
	v_cmp_gt_f32_e32 vcc, s0, v0
	s_and_b64 s[0:1], vcc, exec
	s_cselect_b32 s0, 0xffffffc0, 0
	v_cndmask_b32_e32 v9, 0, v152, vcc
	v_add_f32_e32 v0, v0, v9
	v_exp_f32_e32 v0, v0
	v_lshrrev_b32_e32 v9, 5, v6
	v_lshlrev_b32_e32 v162, 4, v8
	v_lshrrev_b32_e32 v164, 4, v6
	v_ldexp_f32 v0, v0, s0
	v_mul_f32_e32 v0, 4.0, v0
	v_mul_f32_e32 v136, 0x3fb8aa3b, v0
	v_lshlrev_b32_e32 v0, 7, v7
	v_and_b32_e32 v10, 0xf80, v0
	v_lshrrev_b32_e32 v0, 1, v7
	v_bitop3_b32 v12, v9, v0, 7 bitop3:0x78
	v_lshrrev_b32_e32 v0, 3, v6
	v_or_b32_e32 v163, v162, v0
	v_xor_b32_e32 v0, v164, v6
	v_lshlrev_b32_e32 v0, 4, v0
	v_and_b32_e32 v0, 0x70, v0
	v_or_b32_e32 v165, 8, v163
	v_lshl_add_u64 v[138:139], v[2:3], 0, v[0:1]
	v_lshrrev_b32_e32 v0, 1, v165
	v_xor_b32_e32 v0, v0, v7
	v_lshlrev_b32_e32 v0, 4, v0
	v_and_b32_e32 v0, 0x70, v0
	v_lshl_add_u64 v[140:141], v[2:3], 0, v[0:1]
	v_lshlrev_b32_e32 v0, 4, v6
	v_lshlrev_b32_e32 v3, 6, v164
	s_movk_i32 s0, 0xf0
	v_bitop3_b32 v0, v3, v0, s0 bitop3:0x78
	v_bfe_u32 v11, v7, 1, 3
	v_lshl_add_u64 v[142:143], v[4:5], 0, v[0:1]
	v_bfe_u32 v3, v7, 2, 2
	v_lshrrev_b32_e32 v4, 3, v7
	v_bitop3_b32 v14, v9, v11, 4 bitop3:0x36
	v_lshlrev_b32_e32 v15, 11, v8
	v_lshlrev_b32_e32 v2, 3, v6
	v_and_or_b32 v4, v4, 4, v3
	v_lshlrev_b32_e32 v5, 1, v6
	v_bitop3_b32 v13, v9, v11, 2 bitop3:0x36
	v_bitop3_b32 v11, v9, v11, 6 bitop3:0x36
	v_lshlrev_b32_e32 v0, 12, v8
	v_lshlrev_b32_e32 v4, 8, v4
	v_and_b32_e32 v5, 32, v5
	v_and_b32_e32 v2, 24, v2
	v_add_u32_e32 v179, 0xc400, v15
	v_add_u32_e32 v180, 0xc000, v15
	v_lshl_or_b32 v184, v14, 4, v10
	v_mov_b32_e32 v14, v1
	v_mov_b32_e32 v15, v1
	v_or3_b32 v169, v2, v5, v4
	v_lshlrev_b32_e32 v170, 6, v3
	v_lshlrev_b32_e32 v174, 2, v9
	v_add_u32_e32 v175, 0xec00, v0
	v_add_u32_e32 v176, 0xe800, v0
	v_add_u32_e32 v177, 0xe400, v0
	v_add_u32_e32 v178, 0xe000, v0
	v_lshl_or_b32 v181, v12, 4, v10
	v_lshl_or_b32 v182, v11, 4, v10
	v_lshl_or_b32 v183, v13, 4, v10
	v_mov_b32_e32 v0, v1
	v_mov_b32_e32 v2, v1
	v_mov_b32_e32 v3, v1
	v_mov_b32_e32 v4, v1
	v_mov_b32_e32 v5, v1
	v_mov_b32_e32 v6, v1
	v_mov_b32_e32 v7, v1
	v_mov_b32_e32 v8, v1
	v_mov_b32_e32 v9, v1
	v_mov_b32_e32 v10, v1
	v_mov_b32_e32 v11, v1
	v_mov_b32_e32 v12, v1
	v_mov_b32_e32 v13, v1
	v_mov_b32_e32 v155, 0
	v_mov_b64_e32 v[30:31], v[14:15]
	v_mov_b64_e32 v[46:47], v[14:15]
	v_mov_b64_e32 v[62:63], v[14:15]
	v_mov_b64_e32 v[78:79], v[14:15]
	s_mov_b32 s18, 2
	s_mov_b32 s19, 0
	v_or_b32_e32 v166, 4, v162
	v_or_b32_e32 v167, 8, v162
	v_or_b32_e32 v168, 12, v162
	v_xor_b32_e32 v171, 64, v170
	v_xor_b32_e32 v172, 0x80, v170
	v_xor_b32_e32 v173, 0xc0, v170
	v_mov_b32_e32 v144, v136
	v_mov_b32_e32 v145, v136
	v_mov_b32_e32 v146, v136
	v_mov_b32_e32 v147, v136
	s_mov_b32 s96, 0
	v_mov_b64_e32 v[28:29], v[12:13]
	v_mov_b64_e32 v[26:27], v[10:11]
	v_mov_b64_e32 v[24:25], v[8:9]
	v_mov_b64_e32 v[22:23], v[6:7]
	v_mov_b64_e32 v[20:21], v[4:5]
	v_mov_b64_e32 v[18:19], v[2:3]
	v_mov_b64_e32 v[16:17], v[0:1]
	v_mov_b64_e32 v[44:45], v[12:13]
	v_mov_b64_e32 v[42:43], v[10:11]
	v_mov_b64_e32 v[40:41], v[8:9]
	v_mov_b64_e32 v[38:39], v[6:7]
	v_mov_b64_e32 v[36:37], v[4:5]
	v_mov_b64_e32 v[34:35], v[2:3]
	v_mov_b64_e32 v[32:33], v[0:1]
	v_mov_b64_e32 v[60:61], v[12:13]
	v_mov_b64_e32 v[58:59], v[10:11]
	v_mov_b64_e32 v[56:57], v[8:9]
	v_mov_b64_e32 v[54:55], v[6:7]
	v_mov_b64_e32 v[52:53], v[4:5]
	v_mov_b64_e32 v[50:51], v[2:3]
	v_mov_b64_e32 v[48:49], v[0:1]
	v_mov_b64_e32 v[76:77], v[12:13]
	v_mov_b64_e32 v[74:75], v[10:11]
	v_mov_b64_e32 v[72:73], v[8:9]
	v_mov_b64_e32 v[70:71], v[6:7]
	v_mov_b64_e32 v[68:69], v[4:5]
	v_mov_b64_e32 v[66:67], v[2:3]
	v_mov_b64_e32 v[64:65], v[0:1]
	v_mov_b32_e32 v156, 0
	v_mov_b32_e32 v80, 0
	v_mov_b32_e32 v81, v155
	v_mov_b32_e32 v82, v155
	v_mov_b32_e32 v83, v155
	v_mov_b32_e32 v84, v155
	v_mov_b32_e32 v85, v155
	v_mov_b32_e32 v86, v155
	v_mov_b32_e32 v87, v155
	v_mov_b32_e32 v88, v155
	v_mov_b32_e32 v89, v155
	v_mov_b32_e32 v90, v155
	v_mov_b32_e32 v91, v155
	v_mov_b32_e32 v92, v155
	v_mov_b32_e32 v93, v155
	v_mov_b32_e32 v94, v155
	v_mov_b32_e32 v95, v155
	v_mov_b32_e32 v96, v155
	v_mov_b32_e32 v97, v155
	v_mov_b32_e32 v98, v155
	v_mov_b32_e32 v99, v155
	v_mov_b32_e32 v100, v155
	v_mov_b32_e32 v101, v155
	v_mov_b32_e32 v102, v155
	v_mov_b32_e32 v103, v155
	v_mov_b32_e32 v104, v155
	v_mov_b32_e32 v105, v155
	v_mov_b32_e32 v106, v155
	v_mov_b32_e32 v107, v155
	v_mov_b32_e32 v108, v155
	v_mov_b32_e32 v109, v155
	v_mov_b32_e32 v110, v155
	v_mov_b32_e32 v111, v155
	s_waitcnt vmcnt(0)
	.p2align	6

; DI void dil_attn_phase(const Params& p, char* smem) {
;     ...
;     for (int g = 1; g < 3; ++g) {
;       const int d = (g == 1) ? 4 : 16;
;       const int res = pos % d;
;       const int uq = pos / d;
;       const int wpos0 = r16 + 16 * (U0 + wid * 32), wpos1 = wpos0 + 16 * 31;
;       const int wq_min = wpos0 / d, wq_max = wpos1 / d;
;       const int gpos0 = r16 + 16 * U0, gpos1 = gpos0 + 16 * 127;
;       const int gq_min = gpos0 / d, gq_max = gpos1 / d;
;       const int tlo = (gq_min - 128) > 0 ? ((gq_min - 128) >> 6) : 0;
;       const int thi = (gq_max >> 6) + 1;
;       const float slope = exp2f(-8.f * (float)(4 * g + hg + 1) / 12.f);
;       const float slope2 = slope * (float)d * LOG2E;
;       bf16x8 qf[4];
;       load_q(qf, p.qkvz + tok * LD + g * 256 + hg * 64, h);
;       const u16* kb_ = p.qkvz + ((long)b * SEQ + res) * LD + 768 + g * 256 + hg * 64;
;       const u16* vb_ = p.qkvz + ((long)b * SEQ + res) * LD + 1536 + hg * 256 + half * 128;
;       flash_pass<128, false, false>(smem, kb_, LD * d, vb_, LD * d, tlo, thi, nullptr, qf, uq, 1, 129, slope2, wq_min, wq_max, nullptr, 0.f, ot, m, l);
.LBB0_2110:
	s_andn2_b64 vcc, exec, s[0:1]
	s_cbranch_vccnz .LBB0_2075
	s_sub_i32 s0, 0xffffffb8, s90
	v_ashrrev_i32_e32 v134, 4, v14
	v_cvt_f32_i32_e32 v14, s0
	v_ashrrev_i32_e32 v0, 31, v158
	v_lshrrev_b32_e32 v0, 28, v0
	v_add_u32_e32 v0, v158, v0
	v_div_scale_f32 v80, s[0:1], s2, s2, v14
	v_rcp_f32_e32 v87, v80
	v_ashrrev_i32_e32 v135, 4, v0
	v_ashrrev_i32_e32 v0, 31, v157
	v_lshrrev_b32_e32 v0, 28, v0
	v_add_u32_e32 v0, v157, v0
	v_ashrrev_i32_e32 v136, 4, v0
	v_fma_f32 v0, -v80, v87, 1.0
	v_fmac_f32_e32 v87, v0, v87
	v_div_scale_f32 v0, vcc, v14, s2, v14
	v_mul_f32_e32 v88, v0, v87
	v_fma_f32 v89, -v80, v88, v0
	v_fmac_f32_e32 v88, v89, v87
	v_fma_f32 v0, -v80, v88, v0
	v_div_fmas_f32 v0, v0, v87, v88
	v_div_fixup_f32 v0, v0, s2, v14
	s_mov_b32 s0, 0xc2fc0000
	v_cmp_gt_f32_e32 vcc, s0, v0
	s_and_b64 s[0:1], vcc, exec
	s_cselect_b32 s0, 0xffffffc0, 0
	v_cndmask_b32_e32 v14, 0, v152, vcc
	v_add_f32_e32 v0, v0, v14
	v_exp_f32_e32 v0, v0
	v_lshrrev_b32_e32 v87, 5, v15
	v_lshlrev_b32_e32 v137, 4, v86
	v_lshrrev_b32_e32 v139, 4, v15
	v_ldexp_f32 v0, v0, s0
	v_mul_f32_e32 v0, 0x41800000, v0
	v_mul_f32_e32 v14, 0x3fb8aa3b, v0
	v_lshlrev_b32_e32 v0, 7, v81
	v_and_b32_e32 v88, 0xf80, v0
	v_lshrrev_b32_e32 v0, 1, v81
	v_bitop3_b32 v90, v87, v0, 7 bitop3:0x78
	v_lshrrev_b32_e32 v0, 3, v15
	v_or_b32_e32 v138, v137, v0
	v_xor_b32_e32 v0, v139, v15
	v_lshlrev_b32_e32 v0, 4, v0
	v_and_b32_e32 v0, 0x70, v0
	v_or_b32_e32 v140, 8, v138
	s_waitcnt vmcnt(0)
	v_lshl_add_u64 v[120:121], v[82:83], 0, v[0:1]
	v_lshrrev_b32_e32 v0, 1, v140
	v_xor_b32_e32 v0, v0, v81
	v_lshlrev_b32_e32 v0, 4, v0
	v_and_b32_e32 v0, 0x70, v0
	v_lshl_add_u64 v[122:123], v[82:83], 0, v[0:1]
	v_lshlrev_b32_e32 v0, 4, v15
	v_lshlrev_b32_e32 v83, 6, v139
	s_movk_i32 s0, 0xf0
	v_bfe_u32 v89, v81, 1, 3
	v_bitop3_b32 v0, v83, v0, s0 bitop3:0x78
	v_bfe_u32 v83, v81, 2, 2
	v_lshrrev_b32_e32 v81, 3, v81
	v_lshlrev_b32_e32 v82, 3, v15
	v_and_or_b32 v81, v81, 4, v83
	v_lshlrev_b32_e32 v15, 1, v15
	v_mov_b32_e32 v80, 0
	v_bitop3_b32 v91, v87, v89, 2 bitop3:0x36
	v_bitop3_b32 v92, v87, v89, 4 bitop3:0x36
	v_bitop3_b32 v89, v87, v89, 6 bitop3:0x36
	v_lshlrev_b32_e32 v93, 11, v86
	v_lshl_add_u64 v[124:125], v[84:85], 0, v[0:1]
	v_lshlrev_b32_e32 v0, 12, v86
	v_lshlrev_b32_e32 v81, 8, v81
	v_and_b32_e32 v15, 32, v15
	v_and_b32_e32 v82, 24, v82
	v_lshlrev_b32_e32 v145, 6, v83
	s_mov_b32 s17, 0
	s_mov_b32 s18, 2
	v_or_b32_e32 v141, 4, v137
	v_or_b32_e32 v142, 8, v137
	v_or_b32_e32 v143, 12, v137
	v_or3_b32 v144, v82, v15, v81
	v_xor_b32_e32 v146, 64, v145
	v_xor_b32_e32 v147, 0x80, v145
	v_xor_b32_e32 v157, 0xc0, v145
	v_lshlrev_b32_e32 v158, 2, v87
	v_mov_b32_e32 v126, v14
	v_mov_b32_e32 v127, v14
	v_mov_b32_e32 v132, v14
	v_mov_b32_e32 v133, v14
	v_add_u32_e32 v159, 0xec00, v0
	v_add_u32_e32 v160, 0xe800, v0
	v_add_u32_e32 v161, 0xe400, v0
	v_add_u32_e32 v162, 0xe000, v0
	v_add_u32_e32 v163, 0xc400, v93
	v_add_u32_e32 v164, 0xc000, v93
	v_lshl_or_b32 v165, v90, 4, v88
	v_lshl_or_b32 v166, v89, 4, v88
	v_lshl_or_b32 v167, v91, 4, v88
	v_lshl_or_b32 v168, v92, 4, v88
	s_mov_b32 s19, 0
	v_mov_b32_e32 v81, v80
	v_mov_b32_e32 v82, v80
	v_mov_b32_e32 v83, v80
	v_mov_b32_e32 v84, v80
	v_mov_b32_e32 v85, v80
	v_mov_b32_e32 v86, v80
	v_mov_b32_e32 v87, v80
	v_mov_b32_e32 v88, v80
	v_mov_b32_e32 v89, v80
	v_mov_b32_e32 v90, v80
	v_mov_b32_e32 v91, v80
	v_mov_b32_e32 v92, v80
	v_mov_b32_e32 v93, v80
	v_mov_b32_e32 v94, v80
	v_mov_b32_e32 v95, v80
	v_mov_b32_e32 v96, v80
	v_mov_b32_e32 v97, v80
	v_mov_b32_e32 v98, v80
	v_mov_b32_e32 v99, v80
	v_mov_b32_e32 v100, v80
	v_mov_b32_e32 v101, v80
	v_mov_b32_e32 v102, v80
	v_mov_b32_e32 v103, v80
	v_mov_b32_e32 v104, v80
	v_mov_b32_e32 v105, v80
	v_mov_b32_e32 v106, v80
	v_mov_b32_e32 v107, v80
	v_mov_b32_e32 v108, v80
	v_mov_b32_e32 v109, v80
	v_mov_b32_e32 v110, v80
	v_mov_b32_e32 v111, v80
	.p2align	6

; DI int ltid() { int x = threadIdx.x; asm volatile("" : "+v"(x)); return x; }
; DI int lbid() { int x = blockIdx.x; asm volatile("" : "+s"(x)); return x; }
; template <class ARow, class Epi>
; DI void gemm_tile(const ARow& arow, long a_kstride, const u16* __restrict__ Bt, long ldb, int K, int m0, int n0,
;                   const Epi& epi, char* smem) {
;   const int tid = ltid(), lane = tid & 63, wid = tid >> 6;
;   const int r = lane & 31, h = lane >> 5;
;   const int wn = wid & 1, wm = wid >> 1;
;   const u16* ap[4]; const u16* bp[4];
;   {
;     const int lr = lane >> 3;
; #pragma unroll
;     for (int j = 0; j < 4; ++j) {
;       const int row = (wid * 4 + j) * 8 + lr;
;       const int cc = (lane & 7) ^ ((row >> 1) & 7);
;       ap[j] = arow(m0 + row) + cc * 8;
;       bp[j] = Bt + (long)(n0 + row) * ldb + cc * 8;
;     }
;   }
;     ...
;   const int fr = lane & 15, fq = lane >> 4;
;   int foff[2];
; #pragma unroll
;   for (int ks = 0; ks < 2; ++ks) foff[ks] = fr * 128 + ((((4 * ks + fq) ^ ((fr >> 1) & 7))) << 4);
;   f32x4 acc[4][4];
; #pragma unroll
;   for (int a = 0; a < 4; ++a)
; #pragma unroll
;     for (int b = 0; b < 4; ++b) acc[a][b] = (f32x4){0.f, 0.f, 0.f, 0.f};
;   const int KT = K >> 6;
;   GEMM_STAGE(0, 0);
; template <class Epi>
; DI void gemm_phase_plain(const u16* A, long lda, const u16* Bt, long ldb, int M, int N, int K, const Epi& epi, char* smem) {
;     ...
;   for (int t = lbid(); t < nwg; t += gridDim.x) {
;     const int xcd = t & 7, off = t >> 3;
;     const int wg = (xcd < rr ? xcd * (q + 1) : rr * (q + 1) + (xcd - rr) * q) + off;
;     const int nig = 8 * MT, gid = wg / nig, fm = gid * 8, gsz = (NT - fm) < 8 ? (NT - fm) : 8;
;     const int nt = fm + (wg % nig) % gsz, mt = (wg % nig) / gsz;
.LBB0_2186:
	s_lshl_b32 s16, s0, 7
	s_ashr_i32 s1, s0, 3
	s_and_b32 s16, s16, 0x380
	s_add_i32 s1, s16, s1
	s_ashr_i32 s16, s1, 31
	s_lshr_b32 s16, s16, 22
	s_add_i32 s16, s1, s16
	s_and_b32 s16, s16, 0xfffffc00
	s_sub_i32 s1, s1, s16
	s_sext_i32_i16 s17, s1
	s_bfe_u32 s17, s17, 0x3001c
	s_add_i32 s17, s1, s17
	s_sext_i32_i16 s18, s17
	s_and_b32 s17, s17, 0xfff8
	v_mov_b32_e32 v82, v222
	s_sub_i32 s1, s1, s17
	s_sext_i32_i16 s17, s1
	v_ashrrev_i32_e32 v16, 6, v82
	s_lshl_b32 s1, s18, 4
	v_bfe_u32 v17, v82, 3, 3
	v_lshlrev_b32_e32 v18, 5, v16
	s_and_b32 s1, s1, 0xffffff80
	v_or_b32_e32 v12, v18, v17
	s_lshl_b32 s18, s17, 7
	v_bfe_u32 v83, v82, 4, 2
	v_add_u32_e32 v0, s1, v12
	s_add_i32 s18, s18, s16
	v_xor_b32_e32 v2, v83, v82
	v_ashrrev_i32_e32 v1, 31, v0
	v_or_b32_e32 v8, 8, v12
	v_lshlrev_b64 v[0:1], 11, v[0:1]
	v_lshlrev_b32_e32 v2, 4, v2
	v_lshrrev_b32_e32 v19, 1, v8
	v_add_u32_e32 v4, s1, v8
	v_add_u32_e32 v8, s18, v8
	v_lshlrev_b32_e32 v88, 12, v16
	v_lshl_add_u64 v[0:1], s[2:3], 0, v[0:1]
	v_and_b32_e32 v64, 0x70, v2
	v_add_u32_e32 v2, s18, v12
	v_xor_b32_e32 v6, v19, v82
	v_ashrrev_i32_e32 v5, 31, v4
	v_ashrrev_i32_e32 v9, 31, v8
	v_readfirstlane_b32 s16, v88
	v_lshl_add_u64 v[0:1], v[0:1], 0, v[64:65]
	v_ashrrev_i32_e32 v3, 31, v2
	v_lshlrev_b64 v[4:5], 11, v[4:5]
	v_lshlrev_b32_e32 v6, 4, v6
	v_lshlrev_b64 v[8:9], 11, v[8:9]
	s_mov_b32 m0, s16
	v_lshlrev_b64 v[2:3], 11, v[2:3]
	v_lshl_add_u64 v[4:5], s[2:3], 0, v[4:5]
	v_and_b32_e32 v6, 0x70, v6
	v_mov_b32_e32 v7, v65
	v_lshl_add_u64 v[8:9], s[8:9], 0, v[8:9]
	v_or_b32_e32 v10, 16, v12
	global_load_lds_dwordx4 v[0:1], off
	v_add_u32_e32 v0, 0x4000, v88
	v_lshl_add_u64 v[2:3], s[8:9], 0, v[2:3]
	v_lshl_add_u64 v[4:5], v[4:5], 0, v[6:7]
	v_lshl_add_u64 v[6:7], v[8:9], 0, v[6:7]
	v_add_u32_e32 v8, s1, v10
	v_add_u32_e32 v10, s18, v10
	v_or_b32_e32 v14, 24, v12
	v_readfirstlane_b32 s16, v0
	v_or_b32_e32 v0, 0x400, v88
	v_lshl_add_u64 v[2:3], v[2:3], 0, v[64:65]
	v_ashrrev_i32_e32 v9, 31, v8
	v_ashrrev_i32_e32 v11, 31, v10
	v_lshrrev_b32_e32 v20, 1, v14
	s_mov_b32 m0, s16
	v_readfirstlane_b32 s16, v0
	v_add_u32_e32 v0, 0x4400, v88
	v_lshlrev_b64 v[8:9], 11, v[8:9]
	v_lshlrev_b64 v[10:11], 11, v[10:11]
	v_xor_b32_e32 v15, v20, v82
	v_add_u32_e32 v12, s1, v14
	global_load_lds_dwordx4 v[2:3], off
	s_mov_b32 m0, s16
	v_readfirstlane_b32 s16, v0
	v_or_b32_e32 v0, 0x800, v88
	v_lshl_add_u64 v[8:9], s[2:3], 0, v[8:9]
	v_lshl_add_u64 v[10:11], s[8:9], 0, v[10:11]
	v_ashrrev_i32_e32 v13, 31, v12
	v_lshlrev_b32_e32 v15, 4, v15
	v_add_u32_e32 v14, s18, v14
	global_load_lds_dwordx4 v[4:5], off
	s_mov_b32 m0, s16
	v_readfirstlane_b32 s16, v0
	v_add_u32_e32 v0, 0x4800, v88
	v_lshl_add_u64 v[8:9], v[8:9], 0, v[64:65]
	v_lshl_add_u64 v[10:11], v[10:11], 0, v[64:65]
	v_lshlrev_b64 v[12:13], 11, v[12:13]
	v_and_b32_e32 v64, 0x70, v15
	v_ashrrev_i32_e32 v15, 31, v14
	global_load_lds_dwordx4 v[6:7], off
	s_mov_b32 m0, s16
	v_readfirstlane_b32 s16, v0
	v_or_b32_e32 v0, 0xc00, v88
	v_lshl_add_u64 v[12:13], s[2:3], 0, v[12:13]
	v_lshlrev_b64 v[14:15], 11, v[14:15]
	global_load_lds_dwordx4 v[8:9], off
	s_mov_b32 m0, s16
	v_readfirstlane_b32 s16, v0
	v_add_u32_e32 v0, 0x4c00, v88
	v_lshl_add_u64 v[12:13], v[12:13], 0, v[64:65]
	v_lshl_add_u64 v[14:15], s[8:9], 0, v[14:15]
	global_load_lds_dwordx4 v[10:11], off
	s_mov_b32 m0, s16
	v_readfirstlane_b32 s16, v0
	v_lshl_add_u64 v[14:15], v[14:15], 0, v[64:65]
	global_load_lds_dwordx4 v[12:13], off
	s_mov_b32 m0, s16
	v_or_b32_e32 v0, s1, v17
	global_load_lds_dwordx4 v[14:15], off
	v_add_u32_e32 v0, v0, v18
	v_ashrrev_i32_e32 v1, 31, v0
	v_bitop3_b32 v2, v83, 7, v82 bitop3:0x48
	v_lshlrev_b64 v[0:1], 11, v[0:1]
	v_lshlrev_b32_e32 v2, 4, v2
	v_or_b32_e32 v0, v0, v2
	v_lshl_add_u64 v[66:67], s[12:13], 0, v[0:1]
	v_or_b32_e32 v0, s18, v17
	v_add_u32_e32 v0, v0, v18
	v_ashrrev_i32_e32 v1, 31, v0
	v_lshlrev_b64 v[0:1], 11, v[0:1]
	v_or_b32_e32 v0, v0, v2
	v_or_b32_e32 v3, 8, v17
	v_lshl_add_u64 v[68:69], s[14:15], 0, v[0:1]
	v_or_b32_e32 v0, s1, v3
	v_add_u32_e32 v0, v0, v18
	v_ashrrev_i32_e32 v1, 31, v0
	v_bitop3_b32 v4, v19, 7, v82 bitop3:0x48
	v_lshlrev_b64 v[0:1], 11, v[0:1]
	v_lshlrev_b32_e32 v4, 4, v4
	v_or_b32_e32 v0, v0, v4
	v_lshl_add_u64 v[70:71], s[12:13], 0, v[0:1]
	v_or_b32_e32 v0, s18, v3
	v_add_u32_e32 v0, v0, v18
	v_ashrrev_i32_e32 v1, 31, v0
	v_lshlrev_b64 v[0:1], 11, v[0:1]
	v_or_b32_e32 v0, v0, v4
	v_or_b32_e32 v3, 16, v17
	v_lshl_add_u64 v[72:73], s[14:15], 0, v[0:1]
	v_or_b32_e32 v0, s1, v3
	v_add_u32_e32 v0, v0, v18
	v_ashrrev_i32_e32 v1, 31, v0
	v_lshlrev_b64 v[0:1], 11, v[0:1]
	v_or_b32_e32 v0, v0, v2
	v_lshl_add_u64 v[74:75], s[12:13], 0, v[0:1]
	v_or_b32_e32 v0, s18, v3
	v_add_u32_e32 v0, v0, v18
	v_ashrrev_i32_e32 v1, 31, v0
	v_lshlrev_b64 v[0:1], 11, v[0:1]
	v_or_b32_e32 v0, v0, v2
	v_or_b32_e32 v2, 24, v17
	v_lshl_add_u64 v[76:77], s[14:15], 0, v[0:1]
	v_or_b32_e32 v0, s1, v2
	v_add_u32_e32 v0, v0, v18
	v_ashrrev_i32_e32 v1, 31, v0
	v_bitop3_b32 v3, v20, 7, v82 bitop3:0x48
	v_lshlrev_b64 v[0:1], 11, v[0:1]
	v_lshlrev_b32_e32 v3, 4, v3
	v_or_b32_e32 v0, v0, v3
	v_lshl_add_u64 v[78:79], s[12:13], 0, v[0:1]
	v_or_b32_e32 v0, s18, v2
	v_add_u32_e32 v0, v0, v18
	v_and_b32_e32 v64, 15, v82
	v_lshrrev_b32_e32 v22, 1, v82
	v_ashrrev_i32_e32 v1, 31, v0
	v_lshlrev_b32_e32 v21, 7, v64
	v_bfe_u32 v23, v82, 1, 3
	v_bitop3_b32 v22, v83, v22, 7 bitop3:0x78
	s_waitcnt vmcnt(0)
; template <class ARow, class Epi>
; DI void gemm_tile(const ARow& arow, long a_kstride, const u16* __restrict__ Bt, long ldb, int K, int m0, int n0,
;                   const Epi& epi, char* smem) {
;     ...
;   const int fr = lane & 15, fq = lane >> 4;
;   int foff[2];
; #pragma unroll
;   for (int ks = 0; ks < 2; ++ks) foff[ks] = fr * 128 + ((((4 * ks + fq) ^ ((fr >> 1) & 7))) << 4);
;   f32x4 acc[4][4];
; #pragma unroll
;   for (int a = 0; a < 4; ++a)
; #pragma unroll
;     for (int b = 0; b < 4; ++b) acc[a][b] = (f32x4){0.f, 0.f, 0.f, 0.f};
;   const int KT = K >> 6;
;   GEMM_STAGE(0, 0);
;   asm volatile("s_waitcnt vmcnt(0)" ::: "memory");
;   __syncthreads();
	v_lshlrev_b64 v[0:1], 11, v[0:1]
	v_and_b32_e32 v84, 1, v16
	v_lshl_or_b32 v87, v22, 4, v21
	v_bitop3_b32 v22, v83, v23, 4 bitop3:0x36
	v_ashrrev_i32_e32 v85, 7, v82
	v_or_b32_e32 v0, v0, v3
	v_lshl_or_b32 v86, v22, 4, v21
	v_lshlrev_b32_e32 v89, 13, v85
	v_lshlrev_b32_e32 v90, 13, v84
	v_lshl_add_u64 v[80:81], s[14:15], 0, v[0:1]
	s_mov_b64 s[16:17], 0
	s_mov_b32 s19, 0
	v_mov_b32_e32 v20, 0
	v_mov_b32_e32 v21, v65
	v_mov_b32_e32 v22, v65
	v_mov_b32_e32 v23, v65
	v_mov_b32_e32 v28, 0
	v_mov_b32_e32 v29, v65
	v_mov_b32_e32 v30, v65
	v_mov_b32_e32 v31, v65
	v_mov_b32_e32 v0, 0
	v_mov_b32_e32 v1, v65
	v_mov_b32_e32 v2, v65
	v_mov_b32_e32 v3, v65
	v_mov_b32_e32 v24, 0
	v_mov_b32_e32 v25, v65
	v_mov_b32_e32 v26, v65
	v_mov_b32_e32 v27, v65
	v_mov_b32_e32 v4, 0
	v_mov_b32_e32 v5, v65
	v_mov_b32_e32 v6, v65
	v_mov_b32_e32 v7, v65
	v_mov_b32_e32 v8, 0
	v_mov_b32_e32 v9, v65
	v_mov_b32_e32 v10, v65
	v_mov_b32_e32 v11, v65
	v_mov_b32_e32 v12, 0
	v_mov_b32_e32 v13, v65
	v_mov_b32_e32 v14, v65
	v_mov_b32_e32 v15, v65
	v_mov_b32_e32 v32, 0
	v_mov_b32_e32 v33, v65
	v_mov_b32_e32 v34, v65
	v_mov_b32_e32 v35, v65
	v_mov_b32_e32 v16, 0
	v_mov_b32_e32 v17, v65
	v_mov_b32_e32 v18, v65
	v_mov_b32_e32 v19, v65
	v_mov_b32_e32 v36, 0
	v_mov_b32_e32 v37, v65
	v_mov_b32_e32 v38, v65
	v_mov_b32_e32 v39, v65
	v_mov_b32_e32 v40, 0
	v_mov_b32_e32 v41, v65
	v_mov_b32_e32 v42, v65
	v_mov_b32_e32 v43, v65
	v_mov_b32_e32 v44, 0
	v_mov_b32_e32 v45, v65
	v_mov_b32_e32 v46, v65
	v_mov_b32_e32 v47, v65
	v_mov_b32_e32 v48, 0
	v_mov_b32_e32 v49, v65
	v_mov_b32_e32 v50, v65
	v_mov_b32_e32 v51, v65
	v_mov_b32_e32 v52, 0
	v_mov_b32_e32 v53, v65
	v_mov_b32_e32 v54, v65
	v_mov_b32_e32 v55, v65
	v_mov_b32_e32 v56, 0
	v_mov_b32_e32 v57, v65
	v_mov_b32_e32 v58, v65
	v_mov_b32_e32 v59, v65
	v_mov_b32_e32 v60, 0
	v_mov_b32_e32 v61, v65
	v_mov_b32_e32 v62, v65
	v_mov_b32_e32 v63, v65
	s_waitcnt vmcnt(0) lgkmcnt(0)
	s_barrier
	.p2align	6

; template <bool HI_BF, bool HO_BF>
; DI void post_phase(const u16* __restrict__ y, const void* hin_, void* hout_,
;                    const float* __restrict__ gpost, const float* __restrict__ gpre, u16* __restrict__ uout) {
;     ...
;   for (int row = gw; row < T_TOK; row += nw) {
.LBB0_2246:
	v_add_u32_e32 v30, s24, v30
	v_cmp_lt_i32_e32 vcc, s1, v30
	v_lshl_add_u64 v[6:7], v[6:7], 0, s[28:29]
	v_lshl_add_u64 v[8:9], v[8:9], 0, s[28:29]
	v_lshl_add_u64 v[10:11], v[10:11], 0, s[28:29]
	s_or_b64 s[26:27], vcc, s[26:27]
	v_lshl_add_u64 v[12:13], v[12:13], 0, s[28:29]
	s_andn2_b64 exec, exec, s[26:27]
	s_cbranch_execz .LBB0_2253
	.p2align	6

; DI int ltid() { int x = threadIdx.x; asm volatile("" : "+v"(x)); return x; }
; DI int lbid() { int x = blockIdx.x; asm volatile("" : "+s"(x)); return x; }
; template <class ARow, class Epi>
; DI void gemm_tile(const ARow& arow, long a_kstride, const u16* __restrict__ Bt, long ldb, int K, int m0, int n0,
;                   const Epi& epi, char* smem) {
;   const int tid = ltid(), lane = tid & 63, wid = tid >> 6;
;   const int r = lane & 31, h = lane >> 5;
;   const int wn = wid & 1, wm = wid >> 1;
;   const u16* ap[4]; const u16* bp[4];
;   {
;     const int lr = lane >> 3;
; #pragma unroll
;     for (int j = 0; j < 4; ++j) {
;       const int row = (wid * 4 + j) * 8 + lr;
;       const int cc = (lane & 7) ^ ((row >> 1) & 7);
;       ap[j] = arow(m0 + row) + cc * 8;
;       bp[j] = Bt + (long)(n0 + row) * ldb + cc * 8;
;     }
;   }
;     ...
;   const int fr = lane & 15, fq = lane >> 4;
;   int foff[2];
; #pragma unroll
;   for (int ks = 0; ks < 2; ++ks) foff[ks] = fr * 128 + ((((4 * ks + fq) ^ ((fr >> 1) & 7))) << 4);
;   f32x4 acc[4][4];
; #pragma unroll
;   for (int a = 0; a < 4; ++a)
; #pragma unroll
;     for (int b = 0; b < 4; ++b) acc[a][b] = (f32x4){0.f, 0.f, 0.f, 0.f};
;   const int KT = K >> 6;
;   GEMM_STAGE(0, 0);
; template <class Epi>
; DI void gemm_phase_plain(const u16* A, long lda, const u16* Bt, long ldb, int M, int N, int K, const Epi& epi, char* smem) {
;     ...
;   for (int t = lbid(); t < nwg; t += gridDim.x) {
;     const int xcd = t & 7, off = t >> 3;
;     const int wg = (xcd < rr ? xcd * (q + 1) : rr * (q + 1) + (xcd - rr) * q) + off;
;     const int nig = 8 * MT, gid = wg / nig, fm = gid * 8, gsz = (NT - fm) < 8 ? (NT - fm) : 8;
;     const int nt = fm + (wg % nig) % gsz, mt = (wg % nig) / gsz;
.LBB0_2313:
	s_lshl_b32 s1, s25, 9
	s_ashr_i32 s0, s25, 3
	s_and_b32 s1, s1, 0xe00
	s_add_i32 s0, s1, s0
	s_ashr_i32 s1, s0, 31
	s_lshr_b32 s1, s1, 22
	s_add_i32 s1, s0, s1
	s_and_b32 s1, s1, 0xfffffc00
	s_sub_i32 s0, s0, s1
	s_sext_i32_i16 s4, s0
	s_bfe_u32 s4, s4, 0x3001c
	s_add_i32 s4, s0, s4
	s_sext_i32_i16 s5, s4
	s_and_b32 s4, s4, 0xfff8
	v_mov_b32_e32 v82, v222
	s_sub_i32 s0, s0, s4
	s_sext_i32_i16 s4, s0
	v_ashrrev_i32_e32 v16, 6, v82
	s_lshl_b32 s0, s5, 4
	v_bfe_u32 v17, v82, 3, 3
	v_lshlrev_b32_e32 v18, 5, v16
	s_and_b32 s0, s0, 0xffffff80
	v_or_b32_e32 v12, v18, v17
	s_lshl_b32 s34, s4, 7
	v_bfe_u32 v83, v82, 4, 2
	v_add_u32_e32 v0, s0, v12
	s_add_i32 s34, s34, s1
	v_xor_b32_e32 v2, v83, v82
	v_ashrrev_i32_e32 v1, 31, v0
	v_or_b32_e32 v8, 8, v12
	v_lshlrev_b64 v[0:1], 11, v[0:1]
	v_lshlrev_b32_e32 v2, 4, v2
	v_lshrrev_b32_e32 v19, 1, v8
	v_add_u32_e32 v4, s0, v8
	v_add_u32_e32 v8, s34, v8
	v_lshlrev_b32_e32 v90, 12, v16
	v_lshl_add_u64 v[0:1], s[12:13], 0, v[0:1]
	v_and_b32_e32 v64, 0x70, v2
	v_add_u32_e32 v2, s34, v12
	v_xor_b32_e32 v6, v19, v82
	v_ashrrev_i32_e32 v5, 31, v4
	v_ashrrev_i32_e32 v9, 31, v8
	v_readfirstlane_b32 s1, v90
	v_lshl_add_u64 v[0:1], v[0:1], 0, v[64:65]
	v_ashrrev_i32_e32 v3, 31, v2
	v_lshlrev_b64 v[4:5], 11, v[4:5]
	v_lshlrev_b32_e32 v6, 4, v6
	v_lshlrev_b64 v[8:9], 11, v[8:9]
	s_mov_b32 m0, s1
	v_lshlrev_b64 v[2:3], 11, v[2:3]
	v_lshl_add_u64 v[4:5], s[12:13], 0, v[4:5]
	v_and_b32_e32 v6, 0x70, v6
	v_mov_b32_e32 v7, v65
	v_lshl_add_u64 v[8:9], s[16:17], 0, v[8:9]
	v_or_b32_e32 v10, 16, v12
	global_load_lds_dwordx4 v[0:1], off
	v_add_u32_e32 v0, 0x4000, v90
	v_lshl_add_u64 v[2:3], s[16:17], 0, v[2:3]
	v_lshl_add_u64 v[4:5], v[4:5], 0, v[6:7]
	v_lshl_add_u64 v[6:7], v[8:9], 0, v[6:7]
	v_add_u32_e32 v8, s0, v10
	v_add_u32_e32 v10, s34, v10
	v_or_b32_e32 v14, 24, v12
	v_readfirstlane_b32 s1, v0
	v_or_b32_e32 v0, 0x400, v90
	v_lshl_add_u64 v[2:3], v[2:3], 0, v[64:65]
	v_ashrrev_i32_e32 v9, 31, v8
	v_ashrrev_i32_e32 v11, 31, v10
	v_lshrrev_b32_e32 v20, 1, v14
	s_mov_b32 m0, s1
	v_readfirstlane_b32 s1, v0
	v_add_u32_e32 v0, 0x4400, v90
	v_lshlrev_b64 v[8:9], 11, v[8:9]
	v_lshlrev_b64 v[10:11], 11, v[10:11]
	v_xor_b32_e32 v15, v20, v82
	v_add_u32_e32 v12, s0, v14
	global_load_lds_dwordx4 v[2:3], off
	s_mov_b32 m0, s1
	v_readfirstlane_b32 s1, v0
	v_or_b32_e32 v0, 0x800, v90
	v_lshl_add_u64 v[8:9], s[12:13], 0, v[8:9]
	v_lshl_add_u64 v[10:11], s[16:17], 0, v[10:11]
	v_ashrrev_i32_e32 v13, 31, v12
	v_lshlrev_b32_e32 v15, 4, v15
	v_add_u32_e32 v14, s34, v14
	global_load_lds_dwordx4 v[4:5], off
	s_mov_b32 m0, s1
	v_readfirstlane_b32 s1, v0
	v_add_u32_e32 v0, 0x4800, v90
	v_lshl_add_u64 v[8:9], v[8:9], 0, v[64:65]
	v_lshl_add_u64 v[10:11], v[10:11], 0, v[64:65]
	v_lshlrev_b64 v[12:13], 11, v[12:13]
	v_and_b32_e32 v64, 0x70, v15
	v_ashrrev_i32_e32 v15, 31, v14
	global_load_lds_dwordx4 v[6:7], off
	s_mov_b32 m0, s1
	v_readfirstlane_b32 s1, v0
	v_or_b32_e32 v0, 0xc00, v90
	v_lshl_add_u64 v[12:13], s[12:13], 0, v[12:13]
	v_lshlrev_b64 v[14:15], 11, v[14:15]
	global_load_lds_dwordx4 v[8:9], off
	s_mov_b32 m0, s1
	v_readfirstlane_b32 s1, v0
	v_add_u32_e32 v0, 0x4c00, v90
	v_lshl_add_u64 v[12:13], v[12:13], 0, v[64:65]
	v_lshl_add_u64 v[14:15], s[16:17], 0, v[14:15]
	global_load_lds_dwordx4 v[10:11], off
	s_mov_b32 m0, s1
	v_readfirstlane_b32 s1, v0
	v_lshl_add_u64 v[14:15], v[14:15], 0, v[64:65]
	global_load_lds_dwordx4 v[12:13], off
	s_mov_b32 m0, s1
	v_or_b32_e32 v0, s0, v17
	global_load_lds_dwordx4 v[14:15], off
	v_add_u32_e32 v0, v0, v18
	v_ashrrev_i32_e32 v1, 31, v0
	v_bitop3_b32 v2, v83, 7, v82 bitop3:0x48
	v_lshlrev_b64 v[0:1], 11, v[0:1]
	v_lshlrev_b32_e32 v2, 4, v2
	v_or_b32_e32 v0, v0, v2
	v_lshl_add_u64 v[66:67], s[20:21], 0, v[0:1]
	v_or_b32_e32 v0, s34, v17
	v_add_u32_e32 v0, v0, v18
	v_ashrrev_i32_e32 v1, 31, v0
	v_lshlrev_b64 v[0:1], 11, v[0:1]
	v_or_b32_e32 v0, v0, v2
	v_or_b32_e32 v3, 8, v17
	v_lshl_add_u64 v[68:69], s[22:23], 0, v[0:1]
	v_or_b32_e32 v0, s0, v3
	v_add_u32_e32 v0, v0, v18
	v_ashrrev_i32_e32 v1, 31, v0
	v_bitop3_b32 v4, v19, 7, v82 bitop3:0x48
	v_lshlrev_b64 v[0:1], 11, v[0:1]
	v_lshlrev_b32_e32 v4, 4, v4
	v_or_b32_e32 v0, v0, v4
	v_lshl_add_u64 v[70:71], s[20:21], 0, v[0:1]
	v_or_b32_e32 v0, s34, v3
	v_add_u32_e32 v0, v0, v18
	v_ashrrev_i32_e32 v1, 31, v0
	v_lshlrev_b64 v[0:1], 11, v[0:1]
	v_or_b32_e32 v0, v0, v4
	v_or_b32_e32 v3, 16, v17
	v_lshl_add_u64 v[72:73], s[22:23], 0, v[0:1]
	v_or_b32_e32 v0, s0, v3
	v_add_u32_e32 v0, v0, v18
	v_ashrrev_i32_e32 v1, 31, v0
	v_lshlrev_b64 v[0:1], 11, v[0:1]
	v_or_b32_e32 v0, v0, v2
	v_lshl_add_u64 v[74:75], s[20:21], 0, v[0:1]
	v_or_b32_e32 v0, s34, v3
	v_add_u32_e32 v0, v0, v18
	v_ashrrev_i32_e32 v1, 31, v0
	v_lshlrev_b64 v[0:1], 11, v[0:1]
	v_or_b32_e32 v0, v0, v2
	v_or_b32_e32 v2, 24, v17
	v_lshl_add_u64 v[76:77], s[22:23], 0, v[0:1]
	v_or_b32_e32 v0, s0, v2
	v_add_u32_e32 v0, v0, v18
	v_ashrrev_i32_e32 v1, 31, v0
	v_bitop3_b32 v3, v20, 7, v82 bitop3:0x48
	v_lshlrev_b64 v[0:1], 11, v[0:1]
	v_lshlrev_b32_e32 v3, 4, v3
	v_or_b32_e32 v0, v0, v3
	v_lshl_add_u64 v[78:79], s[20:21], 0, v[0:1]
	v_or_b32_e32 v0, s34, v2
	v_add_u32_e32 v0, v0, v18
	v_and_b32_e32 v64, 15, v82
	v_lshrrev_b32_e32 v22, 1, v82
	v_ashrrev_i32_e32 v1, 31, v0
	v_lshlrev_b32_e32 v21, 7, v64
	v_bfe_u32 v23, v82, 1, 3
	v_bitop3_b32 v22, v83, v22, 7 bitop3:0x78
	s_waitcnt vmcnt(0)
; template <class ARow, class Epi>
; DI void gemm_tile(const ARow& arow, long a_kstride, const u16* __restrict__ Bt, long ldb, int K, int m0, int n0,
;                   const Epi& epi, char* smem) {
;     ...
;   const int fr = lane & 15, fq = lane >> 4;
;   int foff[2];
; #pragma unroll
;   for (int ks = 0; ks < 2; ++ks) foff[ks] = fr * 128 + ((((4 * ks + fq) ^ ((fr >> 1) & 7))) << 4);
;   f32x4 acc[4][4];
; #pragma unroll
;   for (int a = 0; a < 4; ++a)
; #pragma unroll
;     for (int b = 0; b < 4; ++b) acc[a][b] = (f32x4){0.f, 0.f, 0.f, 0.f};
;   const int KT = K >> 6;
;   GEMM_STAGE(0, 0);
;   asm volatile("s_waitcnt vmcnt(0)" ::: "memory");
;   __syncthreads();
	v_lshlrev_b64 v[0:1], 11, v[0:1]
	v_and_b32_e32 v84, 1, v16
	v_lshl_or_b32 v87, v22, 4, v21
	v_bitop3_b32 v22, v83, v23, 4 bitop3:0x36
	v_ashrrev_i32_e32 v85, 7, v82
	v_or_b32_e32 v0, v0, v3
	v_lshl_or_b32 v86, v22, 4, v21
	v_lshlrev_b32_e32 v88, 13, v85
	v_lshlrev_b32_e32 v89, 13, v84
	v_lshl_add_u64 v[80:81], s[22:23], 0, v[0:1]
	s_mov_b64 s[4:5], 0
	s_mov_b32 s1, 0
	v_mov_b32_e32 v44, 0
	v_mov_b32_e32 v45, v65
	v_mov_b32_e32 v46, v65
	v_mov_b32_e32 v47, v65
	v_mov_b32_e32 v52, 0
	v_mov_b32_e32 v53, v65
	v_mov_b32_e32 v54, v65
	v_mov_b32_e32 v55, v65
	v_mov_b32_e32 v0, 0
	v_mov_b32_e32 v1, v65
	v_mov_b32_e32 v2, v65
	v_mov_b32_e32 v3, v65
	v_mov_b32_e32 v4, 0
	v_mov_b32_e32 v5, v65
	v_mov_b32_e32 v6, v65
	v_mov_b32_e32 v7, v65
	v_mov_b32_e32 v8, 0
	v_mov_b32_e32 v9, v65
	v_mov_b32_e32 v10, v65
	v_mov_b32_e32 v11, v65
	v_mov_b32_e32 v12, 0
	v_mov_b32_e32 v13, v65
	v_mov_b32_e32 v14, v65
	v_mov_b32_e32 v15, v65
	v_mov_b32_e32 v16, 0
	v_mov_b32_e32 v17, v65
	v_mov_b32_e32 v18, v65
	v_mov_b32_e32 v19, v65
	v_mov_b32_e32 v20, 0
	v_mov_b32_e32 v21, v65
	v_mov_b32_e32 v22, v65
	v_mov_b32_e32 v23, v65
	v_mov_b32_e32 v24, 0
	v_mov_b32_e32 v25, v65
	v_mov_b32_e32 v26, v65
	v_mov_b32_e32 v27, v65
	v_mov_b32_e32 v28, 0
	v_mov_b32_e32 v29, v65
	v_mov_b32_e32 v30, v65
	v_mov_b32_e32 v31, v65
	v_mov_b32_e32 v32, 0
	v_mov_b32_e32 v33, v65
	v_mov_b32_e32 v34, v65
	v_mov_b32_e32 v35, v65
	v_mov_b32_e32 v36, 0
	v_mov_b32_e32 v37, v65
	v_mov_b32_e32 v38, v65
	v_mov_b32_e32 v39, v65
	v_mov_b32_e32 v40, 0
	v_mov_b32_e32 v41, v65
	v_mov_b32_e32 v42, v65
	v_mov_b32_e32 v43, v65
	v_mov_b32_e32 v48, 0
	v_mov_b32_e32 v49, v65
	v_mov_b32_e32 v50, v65
	v_mov_b32_e32 v51, v65
	v_mov_b32_e32 v56, 0
	v_mov_b32_e32 v57, v65
	v_mov_b32_e32 v58, v65
	v_mov_b32_e32 v59, v65
	v_mov_b32_e32 v60, 0
	v_mov_b32_e32 v61, v65
	v_mov_b32_e32 v62, v65
	v_mov_b32_e32 v63, v65
	s_waitcnt vmcnt(0) lgkmcnt(0)
	s_barrier
	.p2align	6

; DI float fexp(float x) { return __builtin_amdgcn_exp2f(x * LOG2E); }
; DI void stick_attn_phase(const Params& p, char* smem) {
;     ...
;     while (t >= 0) {
;       if (t >= 1) WAIT_VM(4); else WAIT_VM(0);
;       if (lane == 0) flags[(c & 1) * 4 + wid] = done;
;       RAW_BARRIER();
;       { const unsigned* f = flags + (c & 1) * 4; if (f[0] & f[1] & f[2] & f[3]) break; }
;       if (t >= 2) kv_issue<64, true>(smem, (c + 2) % 3, kb_, LD, vb_, LD, t - 2, lane, wid);
;       char* sb = smem + (c % 3) * Ring<64>::STAGE;
;       const int k0 = t * 64;
;       if (k0 < q0 + 31) {
;         const bool need_mask = (k0 + 63 >= q0);
;         f32x16 st[2];
; #pragma unroll
;         for (int kb = 0; kb < 2; ++kb)
; #pragma unroll
;           for (int i = 0; i < 16; ++i) st[kb][i] = 0.f;
;         qk_acc(st, qf, sb, foff);
;         bf16x8 pk[2][2];
; #pragma unroll
;     ...
;           float lo[16], cs[4], pc[4];
; #pragma unroll
;           for (int i = 0; i < 16; ++i) {
;             const float z = st[kb][i];
;             const float sp = fmaxf(z, 0.f) + flog(1.f + fexp(-fabsf(z)));
;             bool valid = true;
;             if (need_mask) valid = (k0 + kb * 32 + (i & 3) + 8 * (i >> 2) + 4 * h) < tq;
;             lo[i] = valid ? -sp : 0.f;
;             st[kb][i] = valid ? z : -INFINITY;
;           }
; #pragma unroll
;           for (int g4 = 0; g4 < 4; ++g4) { cs[g4] = (lo[4 * g4] + lo[4 * g4 + 1]) + (lo[4 * g4 + 2] + lo[4 * g4 + 3]); pc[g4] = xhalf(cs[g4]); }
;           float run = carry;
; #pragma unroll
;     ...
;             const float b3 = run + (h == 0 ? pc[g4] : 0.f);
;             const float b2 = b3 + lo[4 * g4 + 3];
;             const float b1 = b2 + lo[4 * g4 + 2];
;             const float b0 = b1 + lo[4 * g4 + 1];
;             st[kb][4 * g4 + 3] = fexp(st[kb][4 * g4 + 3] + lo[4 * g4 + 3] + b3);
;             st[kb][4 * g4 + 2] = fexp(st[kb][4 * g4 + 2] + lo[4 * g4 + 2] + b2);
;             st[kb][4 * g4 + 1] = fexp(st[kb][4 * g4 + 1] + lo[4 * g4 + 1] + b1);
;             st[kb][4 * g4 + 0] = fexp(st[kb][4 * g4 + 0] + lo[4 * g4 + 0] + b0);
;             run += cs[g4] + pc[g4];
;           }
;           carry = run;
;           pk[kb][0] = pack8(st[kb], 0);
;           pk[kb][1] = pack8(st[kb], 1);
;         }
;         pv_tile<64>(ot, pk, sb, lane);
;         done = __all(carry < -105.f) ? 1u : 0u;
;       }
;       --t; ++c;
;     }
.LBB0_2606:
	s_or_b64 exec, exec, s[26:27]
	s_add_i32 s33, s33, -1
	s_add_i32 s37, s37, 1
	s_sub_i32 s35, s35, 64
	s_add_i32 s18, s18, 1
	s_addk_i32 s36, 0x4000
	s_add_i32 s34, s34, 4
	s_cmp_eq_u32 s33, -1
	s_cselect_b64 s[0:1], -1, 0
	s_and_b64 vcc, exec, s[0:1]
	s_cbranch_vccnz .LBB0_2598
	.p2align	6

; template <bool HI_BF, bool HO_BF>
; DI void post_phase(const u16* __restrict__ y, const void* hin_, void* hout_,
;                    const float* __restrict__ gpost, const float* __restrict__ gpre, u16* __restrict__ uout) {
;     ...
;   for (int row = gw; row < T_TOK; row += nw) {
.LBB0_2736:
	v_add_u32_e32 v22, s8, v22
	v_cmp_lt_i32_e32 vcc, s16, v22
	v_lshl_add_u64 v[18:19], v[18:19], 0, s[12:13]
	s_or_b64 s[10:11], vcc, s[10:11]
	v_lshl_add_u64 v[20:21], v[20:21], 0, s[14:15]
	s_andn2_b64 exec, exec, s[10:11]
	s_cbranch_execz .LBB0_2741
	.p2align	6
